# a+b plus: K-loop load phases reordered DMA-first (M0 hazard slots filled by ds_reads, nops dropped, read burst after the DMA issue)
# baseline (speedup 1.0000x reference)
; #define PG8_STAGE(bufoff, gbase, voff) do { const char* _gb = (const char*)(gbase); asm volatile("" : "+s"(_gb)); _Pragma("unroll") for (int _i = 0; _i < 2; ++_i) { asm volatile("" : "+v"((voff)[_i])); \
;         __builtin_amdgcn_global_load_lds((const unsigned*)(_gb + (voff)[_i]), (PG8_LAS unsigned*)(lds + (bufoff) + ldsw + _i * 8192), 16, 0, 0); } } while (0)
; #define PG8_LDA(dst, b, h) do { _Pragma("unroll") for (int m = 0; m < 4; ++m) _Pragma("unroll") for (int k = 0; k < 2; ++k) dst[m][k] = *(const PG8_LAS bf16x8*)(lds + PG8_SA(b, h) + aoff + m * 2048 + k * 1024); } while (0)
; #define PG8_LDB(dst, b, h) do { _Pragma("unroll") for (int n = 0; n < 2; ++n) _Pragma("unroll") for (int k = 0; k < 2; ++k) dst[n][k] = *(const PG8_LAS bf16x8*)(lds + PG8_SB(b, h) + boff + n * 2048 + k * 1024); } while (0)
; #define PG8_WAIT_V(n) asm volatile("s_waitcnt vmcnt(" #n ")" ::: "memory")
; #define PG8_WAIT_L(n) asm volatile("s_waitcnt lgkmcnt(" #n ")" ::: "memory")
; #define PG8_BAR __builtin_amdgcn_s_barrier()
; #define PG8_SCHED __builtin_amdgcn_sched_barrier(0)
; #define PG8_LDA(dst, b, h) do { _Pragma("unroll") for (int m = 0; m < 4; ++m) _Pragma("unroll") for (int k = 0; k < 2; ++k) dst[m][k] = *(const PG8_LAS bf16x8*)(lds + PG8_SA(b, h) + aoff + m * 2048 + k * 1024); } while (0)
; #define PG8_BAR __builtin_amdgcn_s_barrier()
; template <class Epi, class Sched, bool ALIGN_EPI = false, bool SP2 = false>
; __device__ __forceinline__ void gemm_phase(PG8_LAS unsigned char* lds, const Gemm g, const Sched& S, const Epi& E) {
;     ...
;             const bool last = (t == nt - 2);
;             const char* a1 = cA + (size_t)(t + 1) * kstep;
;             const char* a2 = last ? nA : cA + (size_t)(t + 2) * kstep; const char* b2 = last ? nB : cB + (size_t)(t + 2) * kstep;
;             const char* a3 = a2 + kstep; const char* b3 = b2 + kstep;
;             if (last && has_next) S.a_ready(nxt);
;             if constexpr (SP2) {
;             PG8_LDB(B0, 0, 0); PG8_LDB(B1, 0, 1); PG8_SCHED; PG8_LDA(At, 0, 0); PG8_STAGE(PG8_SA(1, 1), a1 + hstep, voffA);
;             PG8_WAIT_V(8); PG8_WAIT_L(0); PG8_BAR; PG8_MMA2(0); PG8_BAR; PG8_SCHED;
;             PG8_LDA(At, 0, 1); PG8_STAGE(PG8_SB(0, 0), b2, voffB); PG8_STAGE(PG8_SB(0, 1), b2 + hstep, voffB); PG8_STAGE(PG8_SA(0, 0), a2, voffA);
;             PG8_WAIT_V(8); PG8_WAIT_L(0); PG8_BAR; PG8_MMA2(1); PG8_BAR; PG8_SCHED;
.LBB0_313:
	s_add_u32 s14, s8, 0x100
	s_addc_u32 s15, s9, 0
	s_cmp_eq_u32 s43, 60
	s_cselect_b32 s24, s13, s14
	s_cselect_b32 s25, s11, s15
	s_cselect_b32 s16, s36, s37
	s_cselect_b32 s17, s33, s42
	s_add_u32 s2, s24, 0x80
	s_addc_u32 s3, s25, 0
	s_add_u32 s8, s8, 0x100080
	s_addc_u32 s9, s9, 0
	s_add_i32 m0, s63, 0xc000
	ds_read_b128 v[202:205], v152 offset:6144
	global_load_lds_dwordx4 v1, s[8:9]
	s_add_i32 m0, s63, 0xe000
	ds_read_b128 v[206:209], v152 offset:7168
	global_load_lds_dwordx4 v145, s[8:9]
	ds_read_b128 v[136:139], v150
	ds_read_b128 v[140:143], v150 offset:1024
	ds_read_b128 v[154:157], v150 offset:2048
	ds_read_b128 v[158:161], v150 offset:3072
	ds_read_b128 v[162:165], v151
	ds_read_b128 v[166:169], v151 offset:1024
	ds_read_b128 v[170:173], v151 offset:2048
	ds_read_b128 v[174:177], v151 offset:3072
	ds_read_b128 v[178:181], v152
	ds_read_b128 v[182:185], v152 offset:1024
	ds_read_b128 v[186:189], v152 offset:2048
	ds_read_b128 v[190:193], v152 offset:3072
	ds_read_b128 v[194:197], v152 offset:4096
	ds_read_b128 v[198:201], v152 offset:5120
	s_waitcnt vmcnt(8)
	s_waitcnt lgkmcnt(0)
	s_setprio 1
	s_waitcnt lgkmcnt(0)
	s_barrier
	v_mfma_f32_16x16x32_bf16 v[126:129], v[136:139], v[178:181], v[126:129]
	v_mfma_f32_16x16x32_bf16 v[122:125], v[154:157], v[178:181], v[122:125]
	v_mfma_f32_16x16x32_bf16 v[110:113], v[136:139], v[186:189], v[110:113]
	v_mfma_f32_16x16x32_bf16 v[106:109], v[154:157], v[186:189], v[106:109]
	v_mfma_f32_16x16x32_bf16 v[94:97], v[136:139], v[194:197], v[94:97]
	v_mfma_f32_16x16x32_bf16 v[90:93], v[154:157], v[194:197], v[90:93]
	v_mfma_f32_16x16x32_bf16 v[78:81], v[136:139], v[202:205], v[78:81]
	v_mfma_f32_16x16x32_bf16 v[74:77], v[154:157], v[202:205], v[74:77]
	v_mfma_f32_16x16x32_bf16 v[118:121], v[162:165], v[178:181], v[118:121]
	v_mfma_f32_16x16x32_bf16 v[114:117], v[170:173], v[178:181], v[114:117]
	v_mfma_f32_16x16x32_bf16 v[102:105], v[162:165], v[186:189], v[102:105]
	v_mfma_f32_16x16x32_bf16 v[98:101], v[170:173], v[186:189], v[98:101]
	v_mfma_f32_16x16x32_bf16 v[86:89], v[162:165], v[194:197], v[86:89]
	v_mfma_f32_16x16x32_bf16 v[82:85], v[170:173], v[194:197], v[82:85]
	v_mfma_f32_16x16x32_bf16 v[70:73], v[162:165], v[202:205], v[70:73]
	v_mfma_f32_16x16x32_bf16 v[66:69], v[170:173], v[202:205], v[66:69]
	v_mfma_f32_16x16x32_bf16 v[126:129], v[140:143], v[182:185], v[126:129]
	v_mfma_f32_16x16x32_bf16 v[122:125], v[158:161], v[182:185], v[122:125]
	v_mfma_f32_16x16x32_bf16 v[110:113], v[140:143], v[190:193], v[110:113]
	v_mfma_f32_16x16x32_bf16 v[106:109], v[158:161], v[190:193], v[106:109]
	v_mfma_f32_16x16x32_bf16 v[94:97], v[140:143], v[198:201], v[94:97]
	v_mfma_f32_16x16x32_bf16 v[90:93], v[158:161], v[198:201], v[90:93]
	v_mfma_f32_16x16x32_bf16 v[78:81], v[140:143], v[206:209], v[78:81]
	v_mfma_f32_16x16x32_bf16 v[74:77], v[158:161], v[206:209], v[74:77]
	v_mfma_f32_16x16x32_bf16 v[118:121], v[166:169], v[182:185], v[118:121]
	v_mfma_f32_16x16x32_bf16 v[114:117], v[174:177], v[182:185], v[114:117]
	v_mfma_f32_16x16x32_bf16 v[102:105], v[166:169], v[190:193], v[102:105]
	v_mfma_f32_16x16x32_bf16 v[98:101], v[174:177], v[190:193], v[98:101]
	v_mfma_f32_16x16x32_bf16 v[86:89], v[166:169], v[198:201], v[86:89]
	v_mfma_f32_16x16x32_bf16 v[82:85], v[174:177], v[198:201], v[82:85]
	v_mfma_f32_16x16x32_bf16 v[70:73], v[166:169], v[206:209], v[70:73]
	v_mfma_f32_16x16x32_bf16 v[66:69], v[174:177], v[206:209], v[66:69]
	s_setprio 0
	s_barrier
	s_add_i32 s44, s95, s61
	s_mov_b64 s[8:9], s[16:17]
	s_mov_b32 m0, s44
	ds_read_b128 v[186:189], v152 offset:18432
	global_load_lds_dwordx4 v144, s[8:9]
	s_add_i32 m0, s44, 0x2000
	ds_read_b128 v[190:193], v152 offset:19456
	global_load_lds_dwordx4 v146, s[8:9]
	s_add_u32 s8, s16, 0x100000
	s_addc_u32 s9, s17, 0
	s_add_i32 s44, s96, s61
	s_mov_b32 m0, s44
	ds_read_b128 v[194:197], v152 offset:20480
	global_load_lds_dwordx4 v144, s[8:9]
	s_add_i32 m0, s44, 0x2000
	ds_read_b128 v[198:201], v152 offset:21504
	global_load_lds_dwordx4 v146, s[8:9]
	s_mov_b64 s[8:9], s[24:25]
	s_mov_b32 m0, s63
	ds_read_b128 v[202:205], v152 offset:22528
	global_load_lds_dwordx4 v1, s[8:9]
	s_mov_b32 m0, s65
	ds_read_b128 v[206:209], v152 offset:23552
	global_load_lds_dwordx4 v145, s[8:9]
	ds_read_b128 v[178:181], v152 offset:16384
	ds_read_b128 v[182:185], v152 offset:17408
	s_waitcnt vmcnt(8)
	s_waitcnt lgkmcnt(0)
	s_setprio 1
	s_waitcnt lgkmcnt(0)
	s_barrier
	v_mfma_f32_16x16x32_bf16 v[62:65], v[136:139], v[178:181], v[62:65]
	v_mfma_f32_16x16x32_bf16 v[58:61], v[154:157], v[178:181], v[58:61]
	v_mfma_f32_16x16x32_bf16 v[46:49], v[136:139], v[186:189], v[46:49]
	v_mfma_f32_16x16x32_bf16 v[42:45], v[154:157], v[186:189], v[42:45]
	v_mfma_f32_16x16x32_bf16 v[30:33], v[136:139], v[194:197], v[30:33]
	v_mfma_f32_16x16x32_bf16 v[26:29], v[154:157], v[194:197], v[26:29]
	v_mfma_f32_16x16x32_bf16 v[14:17], v[136:139], v[202:205], v[14:17]
	v_mfma_f32_16x16x32_bf16 v[10:13], v[154:157], v[202:205], v[10:13]
	v_mfma_f32_16x16x32_bf16 v[54:57], v[162:165], v[178:181], v[54:57]
	v_mfma_f32_16x16x32_bf16 v[50:53], v[170:173], v[178:181], v[50:53]
	v_mfma_f32_16x16x32_bf16 v[38:41], v[162:165], v[186:189], v[38:41]
	v_mfma_f32_16x16x32_bf16 v[34:37], v[170:173], v[186:189], v[34:37]
	v_mfma_f32_16x16x32_bf16 v[22:25], v[162:165], v[194:197], v[22:25]
	v_mfma_f32_16x16x32_bf16 v[18:21], v[170:173], v[194:197], v[18:21]
	v_mfma_f32_16x16x32_bf16 v[6:9], v[162:165], v[202:205], v[6:9]
	v_mfma_f32_16x16x32_bf16 v[2:5], v[170:173], v[202:205], v[2:5]
	v_mfma_f32_16x16x32_bf16 v[62:65], v[140:143], v[182:185], v[62:65]
	v_mfma_f32_16x16x32_bf16 v[58:61], v[158:161], v[182:185], v[58:61]
	v_mfma_f32_16x16x32_bf16 v[46:49], v[140:143], v[190:193], v[46:49]
	v_mfma_f32_16x16x32_bf16 v[42:45], v[158:161], v[190:193], v[42:45]
	v_mfma_f32_16x16x32_bf16 v[30:33], v[140:143], v[198:201], v[30:33]
	v_mfma_f32_16x16x32_bf16 v[26:29], v[158:161], v[198:201], v[26:29]
	v_mfma_f32_16x16x32_bf16 v[14:17], v[140:143], v[206:209], v[14:17]
	v_mfma_f32_16x16x32_bf16 v[10:13], v[158:161], v[206:209], v[10:13]
	v_mfma_f32_16x16x32_bf16 v[54:57], v[166:169], v[182:185], v[54:57]
	v_mfma_f32_16x16x32_bf16 v[50:53], v[174:177], v[182:185], v[50:53]
	v_mfma_f32_16x16x32_bf16 v[38:41], v[166:169], v[190:193], v[38:41]
	v_mfma_f32_16x16x32_bf16 v[34:37], v[174:177], v[190:193], v[34:37]
	v_mfma_f32_16x16x32_bf16 v[22:25], v[166:169], v[198:201], v[22:25]
	v_mfma_f32_16x16x32_bf16 v[18:21], v[174:177], v[198:201], v[18:21]
	v_mfma_f32_16x16x32_bf16 v[6:9], v[166:169], v[206:209], v[6:9]
	v_mfma_f32_16x16x32_bf16 v[2:5], v[174:177], v[206:209], v[2:5]
	s_setprio 0
	s_barrier
; #define PG8_STAGE(bufoff, gbase, voff) do { const char* _gb = (const char*)(gbase); asm volatile("" : "+s"(_gb)); _Pragma("unroll") for (int _i = 0; _i < 2; ++_i) { asm volatile("" : "+v"((voff)[_i])); \
;         __builtin_amdgcn_global_load_lds((const unsigned*)(_gb + (voff)[_i]), (PG8_LAS unsigned*)(lds + (bufoff) + ldsw + _i * 8192), 16, 0, 0); } } while (0)
; #define PG8_LDA(dst, b, h) do { _Pragma("unroll") for (int m = 0; m < 4; ++m) _Pragma("unroll") for (int k = 0; k < 2; ++k) dst[m][k] = *(const PG8_LAS bf16x8*)(lds + PG8_SA(b, h) + aoff + m * 2048 + k * 1024); } while (0)
; #define PG8_LDB(dst, b, h) do { _Pragma("unroll") for (int n = 0; n < 2; ++n) _Pragma("unroll") for (int k = 0; k < 2; ++k) dst[n][k] = *(const PG8_LAS bf16x8*)(lds + PG8_SB(b, h) + boff + n * 2048 + k * 1024); } while (0)
; #define PG8_WAIT_V(n) asm volatile("s_waitcnt vmcnt(" #n ")" ::: "memory")
; #define PG8_WAIT_L(n) asm volatile("s_waitcnt lgkmcnt(" #n ")" ::: "memory")
; #define PG8_BAR __builtin_amdgcn_s_barrier()
; #define PG8_SCHED __builtin_amdgcn_sched_barrier(0)
; #define PG8_STAGE(bufoff, gbase, voff) do { const char* _gb = (const char*)(gbase); asm volatile("" : "+s"(_gb)); _Pragma("unroll") for (int _i = 0; _i < 2; ++_i) { asm volatile("" : "+v"((voff)[_i])); \
;         __builtin_amdgcn_global_load_lds((const unsigned*)(_gb + (voff)[_i]), (PG8_LAS unsigned*)(lds + (bufoff) + ldsw + _i * 8192), 16, 0, 0); } } while (0)
; #define PG8_LDA(dst, b, h) do { _Pragma("unroll") for (int m = 0; m < 4; ++m) _Pragma("unroll") for (int k = 0; k < 2; ++k) dst[m][k] = *(const PG8_LAS bf16x8*)(lds + PG8_SA(b, h) + aoff + m * 2048 + k * 1024); } while (0)
; #define PG8_WAIT_V(n) asm volatile("s_waitcnt vmcnt(" #n ")" ::: "memory")
; template <class Epi, class Sched, bool ALIGN_EPI = false, bool SP2 = false>
; __device__ __forceinline__ void gemm_phase(PG8_LAS unsigned char* lds, const Gemm g, const Sched& S, const Epi& E) {
;     ...
;             PG8_LDB(B0, 1, 0); PG8_LDB(B1, 1, 1); PG8_SCHED; PG8_LDA(At, 1, 0); PG8_STAGE(PG8_SA(0, 1), a2 + hstep, voffA);
;             PG8_WAIT_V(8); PG8_WAIT_L(0); PG8_BAR; PG8_MMA2(0); PG8_BAR; PG8_SCHED;
;             PG8_LDA(At, 1, 1); PG8_STAGE(PG8_SB(1, 0), b3, voffB); PG8_STAGE(PG8_SB(1, 1), b3 + hstep, voffB); PG8_STAGE(PG8_SA(1, 0), a3, voffA);
;             PG8_WAIT_V(8); PG8_WAIT_L(0); PG8_BAR; PG8_MMA2(1); PG8_BAR; PG8_SCHED;
	s_add_i32 s44, 0, 0x18000
	s_add_i32 s45, 0, 0x1c000
	s_add_u32 s8, s24, 0x100000
	s_addc_u32 s9, s25, 0
	s_mov_b32 m0, s88
	ds_read_b128 v[202:205], v152 offset:38912
	global_load_lds_dwordx4 v1, s[8:9]
	s_mov_b32 m0, s89
	ds_read_b128 v[206:209], v152 offset:39936
	global_load_lds_dwordx4 v145, s[8:9]
	v_add_u32_e32 v135, s44, v148
	ds_read_b128 v[136:139], v135
	ds_read_b128 v[140:143], v135 offset:1024
	ds_read_b128 v[154:157], v135 offset:2048
	ds_read_b128 v[158:161], v135 offset:3072
	v_add_u32_e32 v135, s45, v148
	ds_read_b128 v[162:165], v135
	ds_read_b128 v[166:169], v135 offset:1024
	ds_read_b128 v[170:173], v135 offset:2048
	ds_read_b128 v[174:177], v135 offset:3072
	ds_read_b128 v[178:181], v152 offset:32768
	ds_read_b128 v[182:185], v152 offset:33792
	ds_read_b128 v[186:189], v152 offset:34816
	ds_read_b128 v[190:193], v152 offset:35840
	ds_read_b128 v[194:197], v152 offset:36864
	ds_read_b128 v[198:201], v152 offset:37888
	s_waitcnt vmcnt(8)
	s_waitcnt lgkmcnt(0)
	s_setprio 1
	s_waitcnt lgkmcnt(0)
	s_barrier
	v_mfma_f32_16x16x32_bf16 v[126:129], v[136:139], v[178:181], v[126:129]
	v_mfma_f32_16x16x32_bf16 v[122:125], v[154:157], v[178:181], v[122:125]
	v_mfma_f32_16x16x32_bf16 v[110:113], v[136:139], v[186:189], v[110:113]
	v_mfma_f32_16x16x32_bf16 v[106:109], v[154:157], v[186:189], v[106:109]
	v_mfma_f32_16x16x32_bf16 v[94:97], v[136:139], v[194:197], v[94:97]
	v_mfma_f32_16x16x32_bf16 v[90:93], v[154:157], v[194:197], v[90:93]
	v_mfma_f32_16x16x32_bf16 v[78:81], v[136:139], v[202:205], v[78:81]
	v_mfma_f32_16x16x32_bf16 v[74:77], v[154:157], v[202:205], v[74:77]
	v_mfma_f32_16x16x32_bf16 v[118:121], v[162:165], v[178:181], v[118:121]
	v_mfma_f32_16x16x32_bf16 v[114:117], v[170:173], v[178:181], v[114:117]
	v_mfma_f32_16x16x32_bf16 v[102:105], v[162:165], v[186:189], v[102:105]
	v_mfma_f32_16x16x32_bf16 v[98:101], v[170:173], v[186:189], v[98:101]
	v_mfma_f32_16x16x32_bf16 v[86:89], v[162:165], v[194:197], v[86:89]
	v_mfma_f32_16x16x32_bf16 v[82:85], v[170:173], v[194:197], v[82:85]
	v_mfma_f32_16x16x32_bf16 v[70:73], v[162:165], v[202:205], v[70:73]
	v_mfma_f32_16x16x32_bf16 v[66:69], v[170:173], v[202:205], v[66:69]
	v_mfma_f32_16x16x32_bf16 v[126:129], v[140:143], v[182:185], v[126:129]
	v_mfma_f32_16x16x32_bf16 v[122:125], v[158:161], v[182:185], v[122:125]
	v_mfma_f32_16x16x32_bf16 v[110:113], v[140:143], v[190:193], v[110:113]
	v_mfma_f32_16x16x32_bf16 v[106:109], v[158:161], v[190:193], v[106:109]
	v_mfma_f32_16x16x32_bf16 v[94:97], v[140:143], v[198:201], v[94:97]
	v_mfma_f32_16x16x32_bf16 v[90:93], v[158:161], v[198:201], v[90:93]
	v_mfma_f32_16x16x32_bf16 v[78:81], v[140:143], v[206:209], v[78:81]
	v_mfma_f32_16x16x32_bf16 v[74:77], v[158:161], v[206:209], v[74:77]
	v_mfma_f32_16x16x32_bf16 v[118:121], v[166:169], v[182:185], v[118:121]
	v_mfma_f32_16x16x32_bf16 v[114:117], v[174:177], v[182:185], v[114:117]
	v_mfma_f32_16x16x32_bf16 v[102:105], v[166:169], v[190:193], v[102:105]
	v_mfma_f32_16x16x32_bf16 v[98:101], v[174:177], v[190:193], v[98:101]
	v_mfma_f32_16x16x32_bf16 v[86:89], v[166:169], v[198:201], v[86:89]
	v_mfma_f32_16x16x32_bf16 v[82:85], v[174:177], v[198:201], v[82:85]
	v_mfma_f32_16x16x32_bf16 v[70:73], v[166:169], v[206:209], v[70:73]
	v_mfma_f32_16x16x32_bf16 v[66:69], v[174:177], v[206:209], v[66:69]
	s_setprio 0
	s_barrier
	s_add_u32 s8, s16, 0x80
	s_addc_u32 s9, s17, 0
	s_add_i32 s24, s44, s61
	s_mov_b32 m0, s24
	ds_read_b128 v[186:189], v152 offset:51200
	global_load_lds_dwordx4 v144, s[8:9]
	s_add_i32 m0, s24, 0x2000
	ds_read_b128 v[190:193], v152 offset:52224
	global_load_lds_dwordx4 v146, s[8:9]
	s_add_u32 s8, s16, 0x100080
	s_addc_u32 s9, s17, 0
	s_add_i32 s16, s45, s61
	s_mov_b32 m0, s16
	ds_read_b128 v[194:197], v152 offset:53248
	global_load_lds_dwordx4 v144, s[8:9]
	s_add_i32 m0, s16, 0x2000
	ds_read_b128 v[198:201], v152 offset:54272
	global_load_lds_dwordx4 v146, s[8:9]
	s_mov_b32 m0, s91
	ds_read_b128 v[202:205], v152 offset:55296
	global_load_lds_dwordx4 v1, s[2:3]
	s_mov_b32 m0, s92
	ds_read_b128 v[206:209], v152 offset:56320
	global_load_lds_dwordx4 v145, s[2:3]
	ds_read_b128 v[178:181], v152 offset:49152
	ds_read_b128 v[182:185], v152 offset:50176
	s_waitcnt vmcnt(8)
	s_waitcnt lgkmcnt(0)
	s_setprio 1
	s_waitcnt lgkmcnt(0)
	s_barrier
	v_mfma_f32_16x16x32_bf16 v[62:65], v[136:139], v[178:181], v[62:65]
	v_mfma_f32_16x16x32_bf16 v[58:61], v[154:157], v[178:181], v[58:61]
	v_mfma_f32_16x16x32_bf16 v[46:49], v[136:139], v[186:189], v[46:49]
	v_mfma_f32_16x16x32_bf16 v[42:45], v[154:157], v[186:189], v[42:45]
	v_mfma_f32_16x16x32_bf16 v[30:33], v[136:139], v[194:197], v[30:33]
	v_mfma_f32_16x16x32_bf16 v[26:29], v[154:157], v[194:197], v[26:29]
	v_mfma_f32_16x16x32_bf16 v[14:17], v[136:139], v[202:205], v[14:17]
	v_mfma_f32_16x16x32_bf16 v[10:13], v[154:157], v[202:205], v[10:13]
	v_mfma_f32_16x16x32_bf16 v[54:57], v[162:165], v[178:181], v[54:57]
	v_mfma_f32_16x16x32_bf16 v[50:53], v[170:173], v[178:181], v[50:53]
	v_mfma_f32_16x16x32_bf16 v[38:41], v[162:165], v[186:189], v[38:41]
	v_mfma_f32_16x16x32_bf16 v[34:37], v[170:173], v[186:189], v[34:37]
	v_mfma_f32_16x16x32_bf16 v[22:25], v[162:165], v[194:197], v[22:25]
	v_mfma_f32_16x16x32_bf16 v[18:21], v[170:173], v[194:197], v[18:21]
	v_mfma_f32_16x16x32_bf16 v[6:9], v[162:165], v[202:205], v[6:9]
	v_mfma_f32_16x16x32_bf16 v[2:5], v[170:173], v[202:205], v[2:5]
	v_mfma_f32_16x16x32_bf16 v[62:65], v[140:143], v[182:185], v[62:65]
	v_mfma_f32_16x16x32_bf16 v[58:61], v[158:161], v[182:185], v[58:61]
	v_mfma_f32_16x16x32_bf16 v[46:49], v[140:143], v[190:193], v[46:49]
	v_mfma_f32_16x16x32_bf16 v[42:45], v[158:161], v[190:193], v[42:45]
	v_mfma_f32_16x16x32_bf16 v[30:33], v[140:143], v[198:201], v[30:33]
	v_mfma_f32_16x16x32_bf16 v[26:29], v[158:161], v[198:201], v[26:29]
	v_mfma_f32_16x16x32_bf16 v[14:17], v[140:143], v[206:209], v[14:17]
	v_mfma_f32_16x16x32_bf16 v[10:13], v[158:161], v[206:209], v[10:13]
	v_mfma_f32_16x16x32_bf16 v[54:57], v[166:169], v[182:185], v[54:57]
	v_mfma_f32_16x16x32_bf16 v[50:53], v[174:177], v[182:185], v[50:53]
	v_mfma_f32_16x16x32_bf16 v[38:41], v[166:169], v[190:193], v[38:41]
	v_mfma_f32_16x16x32_bf16 v[34:37], v[174:177], v[190:193], v[34:37]
	v_mfma_f32_16x16x32_bf16 v[22:25], v[166:169], v[198:201], v[22:25]
	v_mfma_f32_16x16x32_bf16 v[18:21], v[174:177], v[198:201], v[18:21]
	v_mfma_f32_16x16x32_bf16 v[6:9], v[166:169], v[206:209], v[6:9]
	v_mfma_f32_16x16x32_bf16 v[2:5], v[174:177], v[206:209], v[2:5]
	s_setprio 0
	s_barrier
	s_add_i32 s43, s43, 2
	s_add_u32 s37, s37, 0x100
	s_addc_u32 s42, s42, 0
	s_cmp_gt_u32 s43, 61
	s_mov_b64 s[8:9], s[14:15]
	s_cbranch_scc0 .LBB0_313
	s_and_b64 vcc, exec, s[58:59]
	s_cbranch_vccz .LBB0_333
	s_barrier
	s_cmp_lt_i32 s12, 24
	s_cbranch_scc0 .LBB0_334

.LBB0_746:
	s_add_u32 s16, s0, 0x100
	s_addc_u32 s17, s1, 0
	s_cmp_eq_u32 s33, 28
	s_cselect_b32 s26, s30, s16
	s_cselect_b32 s27, s31, s17
	s_cselect_b32 s24, s78, s5
	s_cselect_b32 s25, s79, s21
	s_add_u32 s2, s26, 0x80
	s_addc_u32 s3, s27, 0
	s_add_u32 s0, s0, 0x100080
	s_addc_u32 s1, s1, 0
	s_add_i32 s76, s46, 0xc000
	s_mov_b32 m0, s76
	s_add_i32 s77, s46, 0xe000
	ds_read_b128 v[204:207], v174 offset:6144
	global_load_lds_dwordx4 v1, s[0:1]
	s_mov_b32 m0, s77
	ds_read_b128 v[208:211], v174 offset:7168
	global_load_lds_dwordx4 v165, s[0:1]
	ds_read_b128 v[118:121], v172
	ds_read_b128 v[134:137], v172 offset:1024
	ds_read_b128 v[138:141], v172 offset:2048
	ds_read_b128 v[142:145], v172 offset:3072
	ds_read_b128 v[146:149], v173
	ds_read_b128 v[150:153], v173 offset:1024
	ds_read_b128 v[154:157], v173 offset:2048
	ds_read_b128 v[176:179], v173 offset:3072
	ds_read_b128 v[180:183], v174
	ds_read_b128 v[184:187], v174 offset:1024
	ds_read_b128 v[188:191], v174 offset:2048
	ds_read_b128 v[192:195], v174 offset:3072
	ds_read_b128 v[196:199], v174 offset:4096
	ds_read_b128 v[200:203], v174 offset:5120
	s_waitcnt vmcnt(8)
	s_waitcnt lgkmcnt(0)
	s_setprio 1
	s_waitcnt lgkmcnt(0)
	s_barrier
	v_mfma_f32_16x16x32_bf16 v[34:37], v[118:121], v[180:183], v[34:37]
	v_mfma_f32_16x16x32_bf16 v[30:33], v[138:141], v[180:183], v[30:33]
	v_mfma_f32_16x16x32_bf16 v[46:49], v[118:121], v[188:191], v[46:49]
	v_mfma_f32_16x16x32_bf16 v[62:65], v[138:141], v[188:191], v[62:65]
	v_mfma_f32_16x16x32_bf16 v[78:81], v[118:121], v[196:199], v[78:81]
	v_mfma_f32_16x16x32_bf16 v[90:93], v[138:141], v[196:199], v[90:93]
	v_mfma_f32_16x16x32_bf16 v[130:133], v[118:121], v[204:207], v[130:133]
	v_mfma_f32_16x16x32_bf16 v[114:117], v[138:141], v[204:207], v[114:117]
	v_mfma_f32_16x16x32_bf16 v[26:29], v[146:149], v[180:183], v[26:29]
	v_mfma_f32_16x16x32_bf16 v[50:53], v[154:157], v[180:183], v[50:53]
	v_mfma_f32_16x16x32_bf16 v[58:61], v[146:149], v[188:191], v[58:61]
	v_mfma_f32_16x16x32_bf16 v[82:85], v[154:157], v[188:191], v[82:85]
	v_mfma_f32_16x16x32_bf16 v[110:113], v[146:149], v[196:199], v[110:113]
	v_mfma_f32_16x16x32_bf16 v[106:109], v[154:157], v[196:199], v[106:109]
	v_mfma_f32_16x16x32_bf16 v[122:125], v[146:149], v[204:207], v[122:125]
	v_mfma_f32_16x16x32_bf16 v[126:129], v[154:157], v[204:207], v[126:129]
	v_mfma_f32_16x16x32_bf16 v[34:37], v[134:137], v[184:187], v[34:37]
	v_mfma_f32_16x16x32_bf16 v[30:33], v[142:145], v[184:187], v[30:33]
	v_mfma_f32_16x16x32_bf16 v[46:49], v[134:137], v[192:195], v[46:49]
	v_mfma_f32_16x16x32_bf16 v[62:65], v[142:145], v[192:195], v[62:65]
	v_mfma_f32_16x16x32_bf16 v[78:81], v[134:137], v[200:203], v[78:81]
	v_mfma_f32_16x16x32_bf16 v[90:93], v[142:145], v[200:203], v[90:93]
	v_mfma_f32_16x16x32_bf16 v[130:133], v[134:137], v[208:211], v[130:133]
	v_mfma_f32_16x16x32_bf16 v[114:117], v[142:145], v[208:211], v[114:117]
	v_mfma_f32_16x16x32_bf16 v[26:29], v[150:153], v[184:187], v[26:29]
	v_mfma_f32_16x16x32_bf16 v[50:53], v[176:179], v[184:187], v[50:53]
	v_mfma_f32_16x16x32_bf16 v[58:61], v[150:153], v[192:195], v[58:61]
	v_mfma_f32_16x16x32_bf16 v[82:85], v[176:179], v[192:195], v[82:85]
	v_mfma_f32_16x16x32_bf16 v[110:113], v[150:153], v[200:203], v[110:113]
	v_mfma_f32_16x16x32_bf16 v[106:109], v[176:179], v[200:203], v[106:109]
	v_mfma_f32_16x16x32_bf16 v[122:125], v[150:153], v[208:211], v[122:125]
	v_mfma_f32_16x16x32_bf16 v[126:129], v[176:179], v[208:211], v[126:129]
	s_setprio 0
	s_barrier
	s_add_i32 s80, s72, s45
	s_mov_b64 s[0:1], s[24:25]
	s_mov_b32 m0, s80
	s_add_i32 s81, s80, 0x2000
	ds_read_b128 v[188:191], v174 offset:18432
	global_load_lds_dwordx4 v164, s[0:1]
	s_mov_b32 m0, s81
	ds_read_b128 v[192:195], v174 offset:19456
	global_load_lds_dwordx4 v166, s[0:1]
	s_add_u32 s0, s24, 0x100000
	s_addc_u32 s1, s25, 0
	s_add_i32 s82, s73, s45
	s_mov_b32 m0, s82
	s_add_i32 s83, s82, 0x2000
	ds_read_b128 v[196:199], v174 offset:20480
	global_load_lds_dwordx4 v164, s[0:1]
	s_mov_b32 m0, s83
	ds_read_b128 v[200:203], v174 offset:21504
	global_load_lds_dwordx4 v166, s[0:1]
	s_mov_b64 s[0:1], s[26:27]
	s_mov_b32 m0, s46
	ds_read_b128 v[204:207], v174 offset:22528
	global_load_lds_dwordx4 v1, s[0:1]
	s_mov_b32 m0, s47
	ds_read_b128 v[208:211], v174 offset:23552
	global_load_lds_dwordx4 v165, s[0:1]
	ds_read_b128 v[180:183], v174 offset:16384
	ds_read_b128 v[184:187], v174 offset:17408
	s_waitcnt vmcnt(8)
	s_waitcnt lgkmcnt(0)
	s_setprio 1
	s_waitcnt lgkmcnt(0)
	s_barrier
	v_mfma_f32_16x16x32_bf16 v[102:105], v[118:121], v[180:183], v[102:105]
	v_mfma_f32_16x16x32_bf16 v[98:101], v[138:141], v[180:183], v[98:101]
	v_mfma_f32_16x16x32_bf16 v[74:77], v[118:121], v[188:191], v[74:77]
	v_mfma_f32_16x16x32_bf16 v[70:73], v[138:141], v[188:191], v[70:73]
	v_mfma_f32_16x16x32_bf16 v[42:45], v[118:121], v[196:199], v[42:45]
	v_mfma_f32_16x16x32_bf16 v[38:41], v[138:141], v[196:199], v[38:41]
	v_mfma_f32_16x16x32_bf16 v[18:21], v[118:121], v[204:207], v[18:21]
	v_mfma_f32_16x16x32_bf16 v[10:13], v[138:141], v[204:207], v[10:13]
	v_mfma_f32_16x16x32_bf16 v[94:97], v[146:149], v[180:183], v[94:97]
	v_mfma_f32_16x16x32_bf16 v[86:89], v[154:157], v[180:183], v[86:89]
	v_mfma_f32_16x16x32_bf16 v[66:69], v[146:149], v[188:191], v[66:69]
	v_mfma_f32_16x16x32_bf16 v[54:57], v[154:157], v[188:191], v[54:57]
	v_mfma_f32_16x16x32_bf16 v[22:25], v[146:149], v[196:199], v[22:25]
	v_mfma_f32_16x16x32_bf16 v[14:17], v[154:157], v[196:199], v[14:17]
	v_mfma_f32_16x16x32_bf16 v[6:9], v[146:149], v[204:207], v[6:9]
	v_mfma_f32_16x16x32_bf16 v[2:5], v[154:157], v[204:207], v[2:5]
	v_mfma_f32_16x16x32_bf16 v[102:105], v[134:137], v[184:187], v[102:105]
	v_mfma_f32_16x16x32_bf16 v[98:101], v[142:145], v[184:187], v[98:101]
	v_mfma_f32_16x16x32_bf16 v[74:77], v[134:137], v[192:195], v[74:77]
	v_mfma_f32_16x16x32_bf16 v[70:73], v[142:145], v[192:195], v[70:73]
	v_mfma_f32_16x16x32_bf16 v[42:45], v[134:137], v[200:203], v[42:45]
	v_mfma_f32_16x16x32_bf16 v[38:41], v[142:145], v[200:203], v[38:41]
	v_mfma_f32_16x16x32_bf16 v[18:21], v[134:137], v[208:211], v[18:21]
	v_mfma_f32_16x16x32_bf16 v[10:13], v[142:145], v[208:211], v[10:13]
	v_mfma_f32_16x16x32_bf16 v[94:97], v[150:153], v[184:187], v[94:97]
	v_mfma_f32_16x16x32_bf16 v[86:89], v[176:179], v[184:187], v[86:89]
	v_mfma_f32_16x16x32_bf16 v[66:69], v[150:153], v[192:195], v[66:69]
	v_mfma_f32_16x16x32_bf16 v[54:57], v[176:179], v[192:195], v[54:57]
	v_mfma_f32_16x16x32_bf16 v[22:25], v[150:153], v[200:203], v[22:25]
	v_mfma_f32_16x16x32_bf16 v[14:17], v[176:179], v[200:203], v[14:17]
	v_mfma_f32_16x16x32_bf16 v[6:9], v[150:153], v[208:211], v[6:9]
	v_mfma_f32_16x16x32_bf16 v[2:5], v[176:179], v[208:211], v[2:5]
	s_setprio 0
	s_barrier
	s_add_i32 s84, 0, 0x18000
	s_add_i32 s86, 0, 0x1c000
	s_add_u32 s0, s26, 0x100000
	s_addc_u32 s1, s27, 0
	s_mov_b32 m0, s48
	ds_read_b128 v[206:209], v174 offset:38912
	global_load_lds_dwordx4 v1, s[0:1]
	s_mov_b32 m0, s49
	ds_read_b128 v[210:213], v174 offset:39936
	global_load_lds_dwordx4 v165, s[0:1]
	v_add_u32_e32 v175, s84, v170
	v_add_u32_e32 v176, s86, v170
	ds_read_b128 v[118:121], v175
	ds_read_b128 v[134:137], v175 offset:1024
	ds_read_b128 v[138:141], v175 offset:2048
	ds_read_b128 v[142:145], v175 offset:3072
	ds_read_b128 v[146:149], v176
	ds_read_b128 v[150:153], v176 offset:1024
	ds_read_b128 v[154:157], v176 offset:2048
	ds_read_b128 v[178:181], v176 offset:3072
	ds_read_b128 v[182:185], v174 offset:32768
	ds_read_b128 v[186:189], v174 offset:33792
	ds_read_b128 v[190:193], v174 offset:34816
	ds_read_b128 v[194:197], v174 offset:35840
	ds_read_b128 v[198:201], v174 offset:36864
	ds_read_b128 v[202:205], v174 offset:37888
	s_waitcnt vmcnt(8)
	s_waitcnt lgkmcnt(0)
	s_setprio 1
	s_waitcnt lgkmcnt(0)
	s_barrier
	v_mfma_f32_16x16x32_bf16 v[34:37], v[118:121], v[182:185], v[34:37]
	v_mfma_f32_16x16x32_bf16 v[30:33], v[138:141], v[182:185], v[30:33]
	v_mfma_f32_16x16x32_bf16 v[46:49], v[118:121], v[190:193], v[46:49]
	v_mfma_f32_16x16x32_bf16 v[62:65], v[138:141], v[190:193], v[62:65]
	v_mfma_f32_16x16x32_bf16 v[78:81], v[118:121], v[198:201], v[78:81]
	v_mfma_f32_16x16x32_bf16 v[90:93], v[138:141], v[198:201], v[90:93]
	v_mfma_f32_16x16x32_bf16 v[130:133], v[118:121], v[206:209], v[130:133]
	v_mfma_f32_16x16x32_bf16 v[114:117], v[138:141], v[206:209], v[114:117]
	v_mfma_f32_16x16x32_bf16 v[26:29], v[146:149], v[182:185], v[26:29]
	v_mfma_f32_16x16x32_bf16 v[50:53], v[154:157], v[182:185], v[50:53]
	v_mfma_f32_16x16x32_bf16 v[58:61], v[146:149], v[190:193], v[58:61]
	v_mfma_f32_16x16x32_bf16 v[82:85], v[154:157], v[190:193], v[82:85]
	v_mfma_f32_16x16x32_bf16 v[110:113], v[146:149], v[198:201], v[110:113]
	v_mfma_f32_16x16x32_bf16 v[106:109], v[154:157], v[198:201], v[106:109]
	v_mfma_f32_16x16x32_bf16 v[122:125], v[146:149], v[206:209], v[122:125]
	v_mfma_f32_16x16x32_bf16 v[126:129], v[154:157], v[206:209], v[126:129]
	v_mfma_f32_16x16x32_bf16 v[34:37], v[134:137], v[186:189], v[34:37]
	v_mfma_f32_16x16x32_bf16 v[30:33], v[142:145], v[186:189], v[30:33]
	v_mfma_f32_16x16x32_bf16 v[46:49], v[134:137], v[194:197], v[46:49]
	v_mfma_f32_16x16x32_bf16 v[62:65], v[142:145], v[194:197], v[62:65]
	v_mfma_f32_16x16x32_bf16 v[78:81], v[134:137], v[202:205], v[78:81]
	v_mfma_f32_16x16x32_bf16 v[90:93], v[142:145], v[202:205], v[90:93]
	v_mfma_f32_16x16x32_bf16 v[130:133], v[134:137], v[210:213], v[130:133]
	v_mfma_f32_16x16x32_bf16 v[114:117], v[142:145], v[210:213], v[114:117]
	v_mfma_f32_16x16x32_bf16 v[26:29], v[150:153], v[186:189], v[26:29]
	v_mfma_f32_16x16x32_bf16 v[50:53], v[178:181], v[186:189], v[50:53]
	v_mfma_f32_16x16x32_bf16 v[58:61], v[150:153], v[194:197], v[58:61]
	v_mfma_f32_16x16x32_bf16 v[82:85], v[178:181], v[194:197], v[82:85]
	v_mfma_f32_16x16x32_bf16 v[110:113], v[150:153], v[202:205], v[110:113]
	v_mfma_f32_16x16x32_bf16 v[106:109], v[178:181], v[202:205], v[106:109]
	v_mfma_f32_16x16x32_bf16 v[122:125], v[150:153], v[210:213], v[122:125]
	v_mfma_f32_16x16x32_bf16 v[126:129], v[178:181], v[210:213], v[126:129]
	s_setprio 0
	s_barrier
	s_add_u32 s0, s24, 0x80
	s_addc_u32 s1, s25, 0
	s_add_i32 s84, s84, s45
	s_mov_b32 m0, s84
	s_add_i32 s85, s84, 0x2000
	ds_read_b128 v[190:193], v174 offset:51200
	global_load_lds_dwordx4 v164, s[0:1]
	s_mov_b32 m0, s85
	ds_read_b128 v[194:197], v174 offset:52224
	global_load_lds_dwordx4 v166, s[0:1]
	s_add_u32 s0, s24, 0x100080
	s_addc_u32 s1, s25, 0
	s_add_i32 s86, s86, s45
	s_mov_b32 m0, s86
	s_add_i32 s87, s86, 0x2000
	ds_read_b128 v[198:201], v174 offset:53248
	global_load_lds_dwordx4 v164, s[0:1]
	s_mov_b32 m0, s87
	ds_read_b128 v[202:205], v174 offset:54272
	global_load_lds_dwordx4 v166, s[0:1]
	s_mov_b32 m0, s57
	ds_read_b128 v[206:209], v174 offset:55296
	global_load_lds_dwordx4 v1, s[2:3]
	s_mov_b32 m0, s62
	ds_read_b128 v[210:213], v174 offset:56320
	global_load_lds_dwordx4 v165, s[2:3]
	ds_read_b128 v[182:185], v174 offset:49152
	ds_read_b128 v[186:189], v174 offset:50176
	s_waitcnt vmcnt(8)
	s_waitcnt lgkmcnt(0)
	s_setprio 1
	s_waitcnt lgkmcnt(0)
	s_barrier
	v_mfma_f32_16x16x32_bf16 v[102:105], v[118:121], v[182:185], v[102:105]
	v_mfma_f32_16x16x32_bf16 v[98:101], v[138:141], v[182:185], v[98:101]
	v_mfma_f32_16x16x32_bf16 v[74:77], v[118:121], v[190:193], v[74:77]
	v_mfma_f32_16x16x32_bf16 v[70:73], v[138:141], v[190:193], v[70:73]
	v_mfma_f32_16x16x32_bf16 v[42:45], v[118:121], v[198:201], v[42:45]
	v_mfma_f32_16x16x32_bf16 v[38:41], v[138:141], v[198:201], v[38:41]
	v_mfma_f32_16x16x32_bf16 v[18:21], v[118:121], v[206:209], v[18:21]
	v_mfma_f32_16x16x32_bf16 v[10:13], v[138:141], v[206:209], v[10:13]
	v_mfma_f32_16x16x32_bf16 v[94:97], v[146:149], v[182:185], v[94:97]
	v_mfma_f32_16x16x32_bf16 v[86:89], v[154:157], v[182:185], v[86:89]
	v_mfma_f32_16x16x32_bf16 v[66:69], v[146:149], v[190:193], v[66:69]
	v_mfma_f32_16x16x32_bf16 v[54:57], v[154:157], v[190:193], v[54:57]
	v_mfma_f32_16x16x32_bf16 v[22:25], v[146:149], v[198:201], v[22:25]
	v_mfma_f32_16x16x32_bf16 v[14:17], v[154:157], v[198:201], v[14:17]
	v_mfma_f32_16x16x32_bf16 v[6:9], v[146:149], v[206:209], v[6:9]
	v_mfma_f32_16x16x32_bf16 v[2:5], v[154:157], v[206:209], v[2:5]
	v_mfma_f32_16x16x32_bf16 v[102:105], v[134:137], v[186:189], v[102:105]
	v_mfma_f32_16x16x32_bf16 v[98:101], v[142:145], v[186:189], v[98:101]
	v_mfma_f32_16x16x32_bf16 v[74:77], v[134:137], v[194:197], v[74:77]
	v_mfma_f32_16x16x32_bf16 v[70:73], v[142:145], v[194:197], v[70:73]
	v_mfma_f32_16x16x32_bf16 v[42:45], v[134:137], v[202:205], v[42:45]
	v_mfma_f32_16x16x32_bf16 v[38:41], v[142:145], v[202:205], v[38:41]
	v_mfma_f32_16x16x32_bf16 v[18:21], v[134:137], v[210:213], v[18:21]
	v_mfma_f32_16x16x32_bf16 v[10:13], v[142:145], v[210:213], v[10:13]
	v_mfma_f32_16x16x32_bf16 v[94:97], v[150:153], v[186:189], v[94:97]
	v_mfma_f32_16x16x32_bf16 v[86:89], v[178:181], v[186:189], v[86:89]
	v_mfma_f32_16x16x32_bf16 v[66:69], v[150:153], v[194:197], v[66:69]
	v_mfma_f32_16x16x32_bf16 v[54:57], v[178:181], v[194:197], v[54:57]
	v_mfma_f32_16x16x32_bf16 v[22:25], v[150:153], v[202:205], v[22:25]
	v_mfma_f32_16x16x32_bf16 v[14:17], v[178:181], v[202:205], v[14:17]
	v_mfma_f32_16x16x32_bf16 v[6:9], v[150:153], v[210:213], v[6:9]
	v_mfma_f32_16x16x32_bf16 v[2:5], v[178:181], v[210:213], v[2:5]
	s_setprio 0
	s_barrier
; __device__ __forceinline__ float bf_lo(unsigned w) { return __uint_as_float(w << 16); }
; __device__ __forceinline__ float bf_hi(unsigned w) { return __uint_as_float(w & 0xffff0000u); }
;     __device__ __forceinline__ void mid(f32x4 (&acc)[2][2][4][2], const Unit& u, int wr, int wc, int fr, int fq) const {
;         asm volatile("" : "+v"(fr), "+v"(fq));
;         const int row0 = u.pm * BM + wr * 64 + fr, col0 = u.pn * BM + wc * 32 + 8 * fq;
; #pragma unroll
;         for (int ai = 0; ai < 2; ++ai)
; #pragma unroll
;             for (int m = 0; m < 4; ++m) { const size_t off = (size_t)(row0 + ai * HALF + m * 16) * 4096 + col0;
; #pragma unroll
;                 for (int bj = 0; bj < 2; ++bj) { const u32x4 ga = *(const u32x4*)(SGA + off + bj * HALF), gb = *(const u32x4*)(SGB + off + bj * HALF);
;                     const unsigned wa[4] = {ga.x, ga.y, ga.z, ga.w}, wb[4] = {gb.x, gb.y, gb.z, gb.w};
; #pragma unroll
;                     for (int p = 0; p < 4; ++p) { const float rl = bf_lo(wa[p]) * __builtin_amdgcn_rcpf(fmaxf(bf_lo(wb[p]), 1e-20f)), rh = bf_hi(wa[p]) * __builtin_amdgcn_rcpf(fmaxf(bf_hi(wb[p]), 1e-20f));
;                         acc[ai][bj][m][p >> 1][(p & 1) * 2] *= rl; acc[ai][bj][m][p >> 1][(p & 1) * 2 + 1] *= rh; } }
;                 if (m == 3) asm volatile("" : "+v"(acc[ai][0][0][0]), "+v"(acc[ai][0][0][1]), "+v"(acc[ai][1][0][0]), "+v"(acc[ai][1][0][1]), "+v"(acc[ai][0][1][0]), "+v"(acc[ai][0][1][1]), "+v"(acc[ai][1][1][0]), "+v"(acc[ai][1][1][1]), "+v"(acc[ai][0][2][0]), "+v"(acc[ai][0][2][1]), "+v"(acc[ai][1][2][0]), "+v"(acc[ai][1][2][1]), "+v"(acc[ai][0][3][0]), "+v"(acc[ai][0][3][1]), "+v"(acc[ai][1][3][0]), "+v"(acc[ai][1][3][1]) :: "memory"); }
;     }
	s_add_i32 s33, s33, 2
	s_add_u32 s5, s5, 0x100
	s_addc_u32 s21, s21, 0
	s_cmp_gt_u32 s33, 29
	s_mov_b64 s[0:1], s[16:17]
	s_cbranch_scc0 .LBB0_746
	v_mov_b32_e32 v119, v167
	v_mov_b32_e32 v118, v168
	s_lshl_b32 s89, s20, 8
	s_lshl_b32 s88, s4, 8
	s_or_b32 s0, s89, s56
	v_lshl_add_u32 v118, v118, 3, s0
	s_add_i32 s0, s88, s55
	v_add_u32_e32 v120, s0, v119
	v_ashrrev_i32_e32 v121, 31, v120
	v_ashrrev_i32_e32 v119, 31, v118
	v_lshlrev_b64 v[120:121], 12, v[120:121]
	v_lshl_add_u64 v[118:119], v[120:121], 0, v[118:119]
	v_lshlrev_b64 v[162:163], 1, v[118:119]
	v_lshl_add_u64 v[138:139], s[12:13], 0, v[162:163]
	global_load_dwordx4 v[134:137], v[138:139], off
	v_lshl_add_u64 v[140:141], s[10:11], 0, v[162:163]
	global_load_dwordx4 v[118:121], v[140:141], off
	global_load_dwordx4 v[150:153], v[138:139], off offset:256
	global_load_dwordx4 v[146:149], v[140:141], off offset:256
	s_mov_b64 s[0:1], 0x20000
	v_lshl_add_u64 v[138:139], v[162:163], 0, s[0:1]
	v_lshl_add_u64 v[154:155], s[10:11], 0, v[138:139]
	v_lshl_add_u64 v[156:157], s[12:13], 0, v[138:139]
	global_load_dwordx4 v[138:141], v[154:155], off
	global_load_dwordx4 v[142:145], v[156:157], off
	s_mov_b64 s[0:1], 0x40000
	s_add_i32 s50, s50, 1
	v_readlane_b32 s2, v238, 45
	s_waitcnt vmcnt(0)
	v_lshlrev_b32_e32 v178, 16, v118
	v_and_b32_e32 v180, 0xffff0000, v134
	v_lshlrev_b32_e32 v181, 16, v135
	v_and_b32_e32 v182, 0xffff0000, v135
	v_lshlrev_b32_e32 v183, 16, v136
	v_and_b32_e32 v184, 0xffff0000, v136
	v_lshlrev_b32_e32 v185, 16, v137
	v_and_b32_e32 v186, 0xffff0000, v137
	v_lshlrev_b32_e32 v187, 16, v150
	v_and_b32_e32 v150, 0xffff0000, v150
	v_lshlrev_b32_e32 v188, 16, v151
	v_and_b32_e32 v151, 0xffff0000, v151
	v_max_f32_e32 v180, v180, v180
	v_max_f32_e32 v181, v181, v181
	v_max_f32_e32 v182, v182, v182
	v_max_f32_e32 v183, v183, v183
	v_max_f32_e32 v184, v184, v184
	v_max_f32_e32 v185, v185, v185
	v_max_f32_e32 v186, v186, v186
	v_max_f32_e32 v187, v187, v187
	v_max_f32_e32 v150, v150, v150
	v_max_f32_e32 v188, v188, v188
	v_max_f32_e32 v151, v151, v151
	v_max_f32_e32 v180, 0x1e3ce508, v180
	v_max_f32_e32 v181, 0x1e3ce508, v181
	v_max_f32_e32 v182, 0x1e3ce508, v182
	v_max_f32_e32 v183, 0x1e3ce508, v183
	v_max_f32_e32 v184, 0x1e3ce508, v184
	v_max_f32_e32 v185, 0x1e3ce508, v185
	v_max_f32_e32 v186, 0x1e3ce508, v186
	v_max_f32_e32 v187, 0x1e3ce508, v187
	v_max_f32_e32 v189, 0x1e3ce508, v150
	v_max_f32_e32 v188, 0x1e3ce508, v188
	v_max_f32_e32 v190, 0x1e3ce508, v151
	v_rcp_f32_e32 v151, v180
	v_rcp_f32_e32 v180, v181
	v_rcp_f32_e32 v181, v182
	v_rcp_f32_e32 v182, v183
	v_rcp_f32_e32 v183, v184
	v_rcp_f32_e32 v184, v185
	v_rcp_f32_e32 v185, v186
	v_rcp_f32_e32 v186, v187
	v_rcp_f32_e32 v187, v189
	v_rcp_f32_e32 v188, v188
	v_rcp_f32_e32 v189, v190
	v_and_b32_e32 v179, 0xffff0000, v118
	v_lshlrev_b32_e32 v118, 16, v119
	v_and_b32_e32 v119, 0xffff0000, v119
	v_lshlrev_b32_e32 v177, 16, v134
	v_lshlrev_b32_e32 v134, 16, v120
	v_and_b32_e32 v135, 0xffff0000, v120
	v_lshlrev_b32_e32 v120, 16, v121
	v_and_b32_e32 v121, 0xffff0000, v121
	v_lshlrev_b32_e32 v136, 16, v146
	v_and_b32_e32 v137, 0xffff0000, v146
	v_lshlrev_b32_e32 v146, 16, v147
	v_and_b32_e32 v147, 0xffff0000, v147
	v_pk_mul_f32 v[118:119], v[180:181], v[118:119]
	v_pk_mul_f32 v[134:135], v[182:183], v[134:135]
	v_pk_mul_f32 v[120:121], v[184:185], v[120:121]
	v_pk_mul_f32 v[36:37], v[36:37], v[118:119]
	v_pk_mul_f32 v[118:119], v[188:189], v[146:147]
	v_pk_mul_f32 v[30:31], v[30:31], v[134:135]
	v_pk_mul_f32 v[32:33], v[32:33], v[120:121]
	v_pk_mul_f32 v[28:29], v[28:29], v[118:119]
	global_load_dwordx4 v[118:121], v[156:157], off offset:256
	v_lshlrev_b32_e32 v134, 16, v152
	v_max_f32_e32 v134, v134, v134
	v_max_f32_e32 v134, 0x1e3ce508, v134
	v_rcp_f32_e32 v146, v134
	v_and_b32_e32 v134, 0xffff0000, v152
	v_max_f32_e32 v134, v134, v134
	v_pk_mul_f32 v[136:137], v[186:187], v[136:137]
	v_max_f32_e32 v134, 0x1e3ce508, v134
	v_pk_mul_f32 v[26:27], v[26:27], v[136:137]
	v_rcp_f32_e32 v147, v134
	global_load_dwordx4 v[134:137], v[154:155], off offset:256
	v_max_f32_e32 v177, v177, v177
	v_max_f32_e32 v177, 0x1e3ce508, v177
	v_rcp_f32_e32 v150, v177
	s_nop 0
	v_pk_mul_f32 v[150:151], v[150:151], v[178:179]
	s_nop 0
	v_pk_mul_f32 v[34:35], v[34:35], v[150:151]
	v_lshlrev_b32_e32 v150, 16, v148
	v_and_b32_e32 v151, 0xffff0000, v148
	v_lshlrev_b32_e32 v148, 16, v153
	v_max_f32_e32 v148, v148, v148
	v_max_f32_e32 v148, 0x1e3ce508, v148
	v_pk_mul_f32 v[146:147], v[146:147], v[150:151]
	v_rcp_f32_e32 v150, v148
	v_and_b32_e32 v148, 0xffff0000, v153
	v_max_f32_e32 v148, v148, v148
	v_max_f32_e32 v148, 0x1e3ce508, v148
	v_rcp_f32_e32 v151, v148
	v_pk_mul_f32 v[50:51], v[50:51], v[146:147]
	v_lshlrev_b32_e32 v146, 16, v149
	v_and_b32_e32 v147, 0xffff0000, v149
	v_pk_mul_f32 v[146:147], v[150:151], v[146:147]
	v_lshlrev_b32_e32 v148, 16, v142
	v_and_b32_e32 v142, 0xffff0000, v142
	v_pk_mul_f32 v[52:53], v[52:53], v[146:147]
	v_lshlrev_b32_e32 v146, 16, v138
	v_and_b32_e32 v147, 0xffff0000, v138
	v_lshlrev_b32_e32 v138, 16, v143
	v_max_f32_e32 v148, v148, v148
	v_max_f32_e32 v142, v142, v142
	v_max_f32_e32 v138, v138, v138
	v_max_f32_e32 v148, 0x1e3ce508, v148
	v_max_f32_e32 v142, 0x1e3ce508, v142
	v_max_f32_e32 v138, 0x1e3ce508, v138
	v_rcp_f32_e32 v148, v148
	v_rcp_f32_e32 v149, v142
	v_rcp_f32_e32 v142, v138
	v_and_b32_e32 v138, 0xffff0000, v143
	v_max_f32_e32 v138, v138, v138
	v_max_f32_e32 v138, 0x1e3ce508, v138
	v_rcp_f32_e32 v143, v138
	v_lshl_add_u64 v[150:151], v[162:163], 0, s[0:1]
	v_pk_mul_f32 v[146:147], v[148:149], v[146:147]
	v_lshl_add_u64 v[154:155], s[12:13], 0, v[150:151]
	v_pk_mul_f32 v[46:47], v[46:47], v[146:147]
	global_load_dwordx4 v[146:149], v[154:155], off
	v_lshlrev_b32_e32 v138, 16, v139
	v_and_b32_e32 v139, 0xffff0000, v139
	v_pk_mul_f32 v[138:139], v[142:143], v[138:139]
	v_lshlrev_b32_e32 v142, 16, v144
	v_max_f32_e32 v142, v142, v142
	v_max_f32_e32 v142, 0x1e3ce508, v142
	v_rcp_f32_e32 v156, v142
	v_lshl_add_u64 v[142:143], s[10:11], 0, v[150:151]
	global_load_dwordx4 v[150:153], v[142:143], off
	v_and_b32_e32 v144, 0xffff0000, v144
	v_pk_mul_f32 v[48:49], v[48:49], v[138:139]
	v_lshlrev_b32_e32 v138, 16, v140
	v_and_b32_e32 v139, 0xffff0000, v140
	v_lshlrev_b32_e32 v140, 16, v145
	v_max_f32_e32 v144, v144, v144
	v_max_f32_e32 v140, v140, v140
	v_max_f32_e32 v144, 0x1e3ce508, v144
	v_max_f32_e32 v140, 0x1e3ce508, v140
	v_rcp_f32_e32 v157, v144
	v_rcp_f32_e32 v144, v140
	v_and_b32_e32 v140, 0xffff0000, v145
	v_max_f32_e32 v140, v140, v140
	v_max_f32_e32 v140, 0x1e3ce508, v140
	v_rcp_f32_e32 v145, v140
	s_waitcnt vmcnt(3)
; __device__ __forceinline__ float bf_lo(unsigned w) { return __uint_as_float(w << 16); }
; __device__ __forceinline__ float bf_hi(unsigned w) { return __uint_as_float(w & 0xffff0000u); }
;     __device__ __forceinline__ void mid(f32x4 (&acc)[2][2][4][2], const Unit& u, int wr, int wc, int fr, int fq) const {
;         asm volatile("" : "+v"(fr), "+v"(fq));
;         const int row0 = u.pm * BM + wr * 64 + fr, col0 = u.pn * BM + wc * 32 + 8 * fq;
; #pragma unroll
;         for (int ai = 0; ai < 2; ++ai)
; #pragma unroll
;             for (int m = 0; m < 4; ++m) { const size_t off = (size_t)(row0 + ai * HALF + m * 16) * 4096 + col0;
; #pragma unroll
;                 for (int bj = 0; bj < 2; ++bj) { const u32x4 ga = *(const u32x4*)(SGA + off + bj * HALF), gb = *(const u32x4*)(SGB + off + bj * HALF);
;                     const unsigned wa[4] = {ga.x, ga.y, ga.z, ga.w}, wb[4] = {gb.x, gb.y, gb.z, gb.w};
; #pragma unroll
;                     for (int p = 0; p < 4; ++p) { const float rl = bf_lo(wa[p]) * __builtin_amdgcn_rcpf(fmaxf(bf_lo(wb[p]), 1e-20f)), rh = bf_hi(wa[p]) * __builtin_amdgcn_rcpf(fmaxf(bf_hi(wb[p]), 1e-20f));
;                         acc[ai][bj][m][p >> 1][(p & 1) * 2] *= rl; acc[ai][bj][m][p >> 1][(p & 1) * 2 + 1] *= rh; } }
;                 if (m == 3) asm volatile("" : "+v"(acc[ai][0][0][0]), "+v"(acc[ai][0][0][1]), "+v"(acc[ai][1][0][0]), "+v"(acc[ai][1][0][1]), "+v"(acc[ai][0][1][0]), "+v"(acc[ai][0][1][1]), "+v"(acc[ai][1][1][0]), "+v"(acc[ai][1][1][1]), "+v"(acc[ai][0][2][0]), "+v"(acc[ai][0][2][1]), "+v"(acc[ai][1][2][0]), "+v"(acc[ai][1][2][1]), "+v"(acc[ai][0][3][0]), "+v"(acc[ai][0][3][1]), "+v"(acc[ai][1][3][0]), "+v"(acc[ai][1][3][1]) :: "memory"); }
;     }
	v_lshlrev_b32_e32 v140, 16, v118
	v_and_b32_e32 v118, 0xffff0000, v118
	v_max_f32_e32 v140, v140, v140
	v_max_f32_e32 v118, v118, v118
	v_pk_mul_f32 v[138:139], v[156:157], v[138:139]
	v_max_f32_e32 v140, 0x1e3ce508, v140
	v_max_f32_e32 v118, 0x1e3ce508, v118
	v_pk_mul_f32 v[62:63], v[62:63], v[138:139]
	v_lshlrev_b32_e32 v138, 16, v141
	v_and_b32_e32 v139, 0xffff0000, v141
	v_rcp_f32_e32 v140, v140
	v_rcp_f32_e32 v141, v118
	v_pk_mul_f32 v[138:139], v[144:145], v[138:139]
	global_load_dwordx4 v[142:145], v[142:143], off offset:256
	v_pk_mul_f32 v[64:65], v[64:65], v[138:139]
	s_waitcnt vmcnt(3)
	v_lshlrev_b32_e32 v138, 16, v134
	v_and_b32_e32 v139, 0xffff0000, v134
	v_pk_mul_f32 v[138:139], v[140:141], v[138:139]
	v_lshlrev_b32_e32 v118, 16, v119
	v_pk_mul_f32 v[58:59], v[58:59], v[138:139]
	global_load_dwordx4 v[138:141], v[154:155], off offset:256
	v_and_b32_e32 v119, 0xffff0000, v119
	v_max_f32_e32 v118, v118, v118
	v_max_f32_e32 v119, v119, v119
	v_max_f32_e32 v118, 0x1e3ce508, v118
	v_max_f32_e32 v119, 0x1e3ce508, v119
	v_rcp_f32_e32 v118, v118
	v_rcp_f32_e32 v119, v119
	v_lshlrev_b32_e32 v134, 16, v135
	v_and_b32_e32 v135, 0xffff0000, v135
	s_mov_b64 s[0:1], 0x60000
	v_pk_mul_f32 v[118:119], v[118:119], v[134:135]
	v_lshlrev_b32_e32 v134, 16, v136
	v_pk_mul_f32 v[60:61], v[60:61], v[118:119]
	v_lshlrev_b32_e32 v118, 16, v120
	v_and_b32_e32 v119, 0xffff0000, v120
	v_max_f32_e32 v118, v118, v118
	v_max_f32_e32 v119, v119, v119
	v_max_f32_e32 v118, 0x1e3ce508, v118
	v_max_f32_e32 v119, 0x1e3ce508, v119
	v_lshlrev_b32_e32 v120, 16, v121
	v_and_b32_e32 v121, 0xffff0000, v121
	v_rcp_f32_e32 v118, v118
	v_rcp_f32_e32 v119, v119
	v_max_f32_e32 v120, v120, v120
	v_max_f32_e32 v121, v121, v121
	v_max_f32_e32 v120, 0x1e3ce508, v120
	v_max_f32_e32 v121, 0x1e3ce508, v121
	v_rcp_f32_e32 v120, v120
	v_rcp_f32_e32 v121, v121
	v_and_b32_e32 v135, 0xffff0000, v136
	v_pk_mul_f32 v[118:119], v[118:119], v[134:135]
	s_nop 0
	v_pk_mul_f32 v[82:83], v[82:83], v[118:119]
	v_lshlrev_b32_e32 v118, 16, v137
	v_and_b32_e32 v119, 0xffff0000, v137
	v_pk_mul_f32 v[118:119], v[120:121], v[118:119]
	s_waitcnt vmcnt(3)
	v_lshlrev_b32_e32 v120, 16, v146
	v_and_b32_e32 v121, 0xffff0000, v146
	v_max_f32_e32 v120, v120, v120
	v_max_f32_e32 v121, v121, v121
	v_max_f32_e32 v120, 0x1e3ce508, v120
	v_max_f32_e32 v121, 0x1e3ce508, v121
	v_rcp_f32_e32 v120, v120
	v_rcp_f32_e32 v121, v121
	v_pk_mul_f32 v[84:85], v[84:85], v[118:119]
	s_waitcnt vmcnt(2)
	v_lshlrev_b32_e32 v118, 16, v150
	v_and_b32_e32 v119, 0xffff0000, v150
	v_pk_mul_f32 v[118:119], v[120:121], v[118:119]
	v_lshlrev_b32_e32 v150, 16, v151
	v_pk_mul_f32 v[78:79], v[78:79], v[118:119]
	v_lshlrev_b32_e32 v118, 16, v147
	v_and_b32_e32 v119, 0xffff0000, v147
	v_lshl_add_u64 v[146:147], v[162:163], 0, s[0:1]
	v_lshl_add_u64 v[120:121], s[12:13], 0, v[146:147]
	v_max_f32_e32 v118, v118, v118
	v_max_f32_e32 v119, v119, v119
	global_load_dwordx4 v[134:137], v[120:121], off
	v_max_f32_e32 v118, 0x1e3ce508, v118
	v_max_f32_e32 v119, 0x1e3ce508, v119
	v_rcp_f32_e32 v118, v118
	v_rcp_f32_e32 v119, v119
	v_and_b32_e32 v151, 0xffff0000, v151
	s_mov_b64 s[0:1], 0x120000
	v_pk_mul_f32 v[150:151], v[118:119], v[150:151]
	v_lshlrev_b32_e32 v118, 16, v148
	v_max_f32_e32 v118, v118, v118
	v_max_f32_e32 v118, 0x1e3ce508, v118
	v_rcp_f32_e32 v178, v118
	v_lshl_add_u64 v[118:119], s[10:11], 0, v[146:147]
	global_load_dwordx4 v[154:157], v[118:119], off
	v_and_b32_e32 v146, 0xffff0000, v148
	v_max_f32_e32 v146, v146, v146
	v_max_f32_e32 v146, 0x1e3ce508, v146
	v_lshlrev_b32_e32 v148, 16, v149
	v_and_b32_e32 v149, 0xffff0000, v149
	v_rcp_f32_e32 v179, v146
	v_max_f32_e32 v148, v148, v148
	v_max_f32_e32 v149, v149, v149
	v_max_f32_e32 v148, 0x1e3ce508, v148
	v_max_f32_e32 v149, 0x1e3ce508, v149
	v_rcp_f32_e32 v148, v148
	v_rcp_f32_e32 v149, v149
	v_lshlrev_b32_e32 v146, 16, v152
	v_and_b32_e32 v147, 0xffff0000, v152
	v_pk_mul_f32 v[146:147], v[178:179], v[146:147]
	v_pk_mul_f32 v[80:81], v[80:81], v[150:151]
	v_pk_mul_f32 v[90:91], v[90:91], v[146:147]
	v_lshlrev_b32_e32 v146, 16, v153
	v_and_b32_e32 v147, 0xffff0000, v153
	v_pk_mul_f32 v[146:147], v[148:149], v[146:147]
	s_waitcnt vmcnt(2)
	v_lshlrev_b32_e32 v148, 16, v138
	v_and_b32_e32 v138, 0xffff0000, v138
	v_max_f32_e32 v148, v148, v148
	v_max_f32_e32 v138, v138, v138
	v_max_f32_e32 v148, 0x1e3ce508, v148
	v_max_f32_e32 v138, 0x1e3ce508, v138
	global_load_dwordx4 v[150:153], v[120:121], off offset:256
	v_rcp_f32_e32 v148, v148
	v_rcp_f32_e32 v149, v138
	v_pk_mul_f32 v[92:93], v[92:93], v[146:147]
	v_lshlrev_b32_e32 v146, 16, v142
	v_and_b32_e32 v147, 0xffff0000, v142
	v_pk_mul_f32 v[146:147], v[148:149], v[146:147]
	v_lshlrev_b32_e32 v138, 16, v139
	v_pk_mul_f32 v[110:111], v[110:111], v[146:147]
	global_load_dwordx4 v[146:149], v[118:119], off offset:256
	v_and_b32_e32 v139, 0xffff0000, v139
	v_max_f32_e32 v138, v138, v138
	v_max_f32_e32 v139, v139, v139
	v_max_f32_e32 v138, 0x1e3ce508, v138
	v_max_f32_e32 v120, 0x1e3ce508, v139
	v_rcp_f32_e32 v138, v138
	v_rcp_f32_e32 v139, v120
	v_lshlrev_b32_e32 v120, 16, v143
	v_and_b32_e32 v121, 0xffff0000, v143
	v_and_b32_e32 v119, 0xffff0000, v140
	v_pk_mul_f32 v[120:121], v[138:139], v[120:121]
	v_lshlrev_b32_e32 v138, 16, v140
	v_max_f32_e32 v138, v138, v138
	v_max_f32_e32 v119, v119, v119
	v_max_f32_e32 v118, 0x1e3ce508, v138
	v_max_f32_e32 v119, 0x1e3ce508, v119
	v_rcp_f32_e32 v118, v118
	v_rcp_f32_e32 v119, v119
	v_pk_mul_f32 v[112:113], v[112:113], v[120:121]
	v_lshlrev_b32_e32 v120, 16, v144
	v_and_b32_e32 v121, 0xffff0000, v144
	v_pk_mul_f32 v[118:119], v[118:119], v[120:121]
	v_lshlrev_b32_e32 v120, 16, v141
	v_and_b32_e32 v121, 0xffff0000, v141
	v_max_f32_e32 v120, v120, v120
	v_max_f32_e32 v121, v121, v121
	v_max_f32_e32 v120, 0x1e3ce508, v120
	v_max_f32_e32 v121, 0x1e3ce508, v121
	v_rcp_f32_e32 v120, v120
	v_rcp_f32_e32 v121, v121
	v_pk_mul_f32 v[118:119], v[106:107], v[118:119]
	v_lshlrev_b32_e32 v106, 16, v145
	v_and_b32_e32 v107, 0xffff0000, v145
	v_pk_mul_f32 v[106:107], v[120:121], v[106:107]
	s_waitcnt vmcnt(3)
; __device__ __forceinline__ float bf_lo(unsigned w) { return __uint_as_float(w << 16); }
; __device__ __forceinline__ float bf_hi(unsigned w) { return __uint_as_float(w & 0xffff0000u); }
;     __device__ __forceinline__ void mid(f32x4 (&acc)[2][2][4][2], const Unit& u, int wr, int wc, int fr, int fq) const {
;         asm volatile("" : "+v"(fr), "+v"(fq));
;         const int row0 = u.pm * BM + wr * 64 + fr, col0 = u.pn * BM + wc * 32 + 8 * fq;
; #pragma unroll
;         for (int ai = 0; ai < 2; ++ai)
; #pragma unroll
;             for (int m = 0; m < 4; ++m) { const size_t off = (size_t)(row0 + ai * HALF + m * 16) * 4096 + col0;
; #pragma unroll
;                 for (int bj = 0; bj < 2; ++bj) { const u32x4 ga = *(const u32x4*)(SGA + off + bj * HALF), gb = *(const u32x4*)(SGB + off + bj * HALF);
;                     const unsigned wa[4] = {ga.x, ga.y, ga.z, ga.w}, wb[4] = {gb.x, gb.y, gb.z, gb.w};
; #pragma unroll
;                     for (int p = 0; p < 4; ++p) { const float rl = bf_lo(wa[p]) * __builtin_amdgcn_rcpf(fmaxf(bf_lo(wb[p]), 1e-20f)), rh = bf_hi(wa[p]) * __builtin_amdgcn_rcpf(fmaxf(bf_hi(wb[p]), 1e-20f));
;                         acc[ai][bj][m][p >> 1][(p & 1) * 2] *= rl; acc[ai][bj][m][p >> 1][(p & 1) * 2 + 1] *= rh; } }
;                 if (m == 3) asm volatile("" : "+v"(acc[ai][0][0][0]), "+v"(acc[ai][0][0][1]), "+v"(acc[ai][1][0][0]), "+v"(acc[ai][1][0][1]), "+v"(acc[ai][0][1][0]), "+v"(acc[ai][0][1][1]), "+v"(acc[ai][1][1][0]), "+v"(acc[ai][1][1][1]), "+v"(acc[ai][0][2][0]), "+v"(acc[ai][0][2][1]), "+v"(acc[ai][1][2][0]), "+v"(acc[ai][1][2][1]), "+v"(acc[ai][0][3][0]), "+v"(acc[ai][0][3][1]), "+v"(acc[ai][1][3][0]), "+v"(acc[ai][1][3][1]) :: "memory"); }
;     }
	v_lshlrev_b32_e32 v120, 16, v134
	v_max_f32_e32 v120, v120, v120
	v_max_f32_e32 v120, 0x1e3ce508, v120
	v_rcp_f32_e32 v138, v120
	v_and_b32_e32 v120, 0xffff0000, v134
	v_max_f32_e32 v120, v120, v120
	v_max_f32_e32 v120, 0x1e3ce508, v120
	v_rcp_f32_e32 v139, v120
	v_pk_mul_f32 v[120:121], v[108:109], v[106:107]
	v_lshlrev_b32_e32 v108, 16, v135
	v_and_b32_e32 v109, 0xffff0000, v135
	v_max_f32_e32 v108, v108, v108
	v_max_f32_e32 v109, v109, v109
	v_max_f32_e32 v108, 0x1e3ce508, v108
	v_max_f32_e32 v109, 0x1e3ce508, v109
	v_rcp_f32_e32 v108, v108
	v_rcp_f32_e32 v109, v109
	s_waitcnt vmcnt(2)
	v_lshlrev_b32_e32 v106, 16, v154
	v_and_b32_e32 v107, 0xffff0000, v154
	v_pk_mul_f32 v[106:107], v[138:139], v[106:107]
	v_lshl_add_u64 v[140:141], v[162:163], 0, s[0:1]
	v_pk_mul_f32 v[106:107], v[130:131], v[106:107]
	v_lshlrev_b32_e32 v130, 16, v155
	v_and_b32_e32 v131, 0xffff0000, v155
	v_pk_mul_f32 v[108:109], v[108:109], v[130:131]
	v_lshlrev_b32_e32 v130, 16, v136
	v_and_b32_e32 v131, 0xffff0000, v136
	v_max_f32_e32 v130, v130, v130
	v_max_f32_e32 v131, v131, v131
	v_max_f32_e32 v130, 0x1e3ce508, v130
	v_max_f32_e32 v131, 0x1e3ce508, v131
	v_rcp_f32_e32 v130, v130
	v_rcp_f32_e32 v131, v131
	v_pk_mul_f32 v[108:109], v[132:133], v[108:109]
	v_lshlrev_b32_e32 v132, 16, v156
	v_and_b32_e32 v133, 0xffff0000, v156
	v_pk_mul_f32 v[130:131], v[130:131], v[132:133]
	v_lshlrev_b32_e32 v132, 16, v137
	v_and_b32_e32 v133, 0xffff0000, v137
	v_max_f32_e32 v132, v132, v132
	v_max_f32_e32 v133, v133, v133
	v_max_f32_e32 v132, 0x1e3ce508, v132
	v_max_f32_e32 v133, 0x1e3ce508, v133
	v_rcp_f32_e32 v132, v132
	v_rcp_f32_e32 v133, v133
	v_pk_mul_f32 v[114:115], v[114:115], v[130:131]
	v_lshlrev_b32_e32 v130, 16, v157
	v_and_b32_e32 v131, 0xffff0000, v157
	v_pk_mul_f32 v[130:131], v[132:133], v[130:131]
	s_waitcnt vmcnt(1)
	v_lshlrev_b32_e32 v132, 16, v150
	v_and_b32_e32 v133, 0xffff0000, v150
	v_max_f32_e32 v132, v132, v132
	v_max_f32_e32 v133, v133, v133
	v_max_f32_e32 v132, 0x1e3ce508, v132
	v_max_f32_e32 v133, 0x1e3ce508, v133
	v_rcp_f32_e32 v132, v132
	v_rcp_f32_e32 v133, v133
	v_pk_mul_f32 v[116:117], v[116:117], v[130:131]
	s_waitcnt vmcnt(0)
	v_lshlrev_b32_e32 v130, 16, v146
	v_and_b32_e32 v131, 0xffff0000, v146
	v_pk_mul_f32 v[130:131], v[132:133], v[130:131]
	v_lshlrev_b32_e32 v132, 16, v151
	v_and_b32_e32 v133, 0xffff0000, v151
	v_max_f32_e32 v132, v132, v132
	v_max_f32_e32 v133, v133, v133
	v_max_f32_e32 v132, 0x1e3ce508, v132
	v_max_f32_e32 v133, 0x1e3ce508, v133
	v_rcp_f32_e32 v132, v132
	v_rcp_f32_e32 v133, v133
	v_pk_mul_f32 v[122:123], v[122:123], v[130:131]
	v_lshlrev_b32_e32 v130, 16, v147
	v_and_b32_e32 v131, 0xffff0000, v147
	v_pk_mul_f32 v[130:131], v[132:133], v[130:131]
	v_lshlrev_b32_e32 v132, 16, v152
	v_and_b32_e32 v133, 0xffff0000, v152
	v_max_f32_e32 v132, v132, v132
	v_max_f32_e32 v133, v133, v133
	v_max_f32_e32 v132, 0x1e3ce508, v132
	v_max_f32_e32 v133, 0x1e3ce508, v133
	v_rcp_f32_e32 v132, v132
	v_rcp_f32_e32 v133, v133
	v_pk_mul_f32 v[124:125], v[124:125], v[130:131]
	v_lshlrev_b32_e32 v130, 16, v148
	v_and_b32_e32 v131, 0xffff0000, v148
	v_pk_mul_f32 v[130:131], v[132:133], v[130:131]
	v_lshlrev_b32_e32 v132, 16, v153
	v_and_b32_e32 v133, 0xffff0000, v153
	v_max_f32_e32 v132, v132, v132
	v_max_f32_e32 v133, v133, v133
	v_max_f32_e32 v132, 0x1e3ce508, v132
	v_max_f32_e32 v133, 0x1e3ce508, v133
	v_rcp_f32_e32 v132, v132
	v_rcp_f32_e32 v133, v133
	v_pk_mul_f32 v[126:127], v[126:127], v[130:131]
	v_lshlrev_b32_e32 v130, 16, v149
	v_and_b32_e32 v131, 0xffff0000, v149
	v_pk_mul_f32 v[130:131], v[132:133], v[130:131]
	v_lshl_add_u64 v[154:155], s[12:13], 0, v[140:141]
	v_pk_mul_f32 v[128:129], v[128:129], v[130:131]
	v_lshl_add_u64 v[130:131], v[162:163], 0, s[8:9]
	v_lshl_add_u64 v[132:133], s[12:13], 0, v[130:131]
	global_load_dwordx4 v[150:153], v[132:133], off
	v_lshl_add_u64 v[130:131], s[10:11], 0, v[130:131]
	global_load_dwordx4 v[146:149], v[130:131], off
	global_load_dwordx4 v[142:145], v[132:133], off offset:256
	global_load_dwordx4 v[134:137], v[130:131], off offset:256
	s_mov_b64 s[0:1], 0x140000
	s_waitcnt vmcnt(3)
	v_lshlrev_b32_e32 v130, 16, v150
	v_and_b32_e32 v131, 0xffff0000, v150
	v_max_f32_e32 v130, v130, v130
	v_max_f32_e32 v131, v131, v131
	v_max_f32_e32 v130, 0x1e3ce508, v130
	v_max_f32_e32 v131, 0x1e3ce508, v131
	v_rcp_f32_e32 v130, v130
	v_rcp_f32_e32 v131, v131
	s_waitcnt vmcnt(2)
	v_lshlrev_b32_e32 v132, 16, v146
	v_and_b32_e32 v133, 0xffff0000, v146
	v_lshlrev_b32_e32 v146, 16, v147
	v_pk_mul_f32 v[130:131], v[130:131], v[132:133]
	v_and_b32_e32 v147, 0xffff0000, v147
	v_pk_mul_f32 v[102:103], v[102:103], v[130:131]
	v_lshlrev_b32_e32 v130, 16, v151
	v_max_f32_e32 v130, v130, v130
	v_max_f32_e32 v130, 0x1e3ce508, v130
	v_rcp_f32_e32 v138, v130
	v_and_b32_e32 v130, 0xffff0000, v151
	v_max_f32_e32 v130, v130, v130
	v_max_f32_e32 v130, 0x1e3ce508, v130
	v_rcp_f32_e32 v139, v130
	global_load_dwordx4 v[130:133], v[154:155], off
	v_lshl_add_u64 v[150:151], s[10:11], 0, v[140:141]
	v_pk_mul_f32 v[146:147], v[138:139], v[146:147]
	v_lshlrev_b32_e32 v138, 16, v152
	v_max_f32_e32 v138, v138, v138
	v_max_f32_e32 v138, 0x1e3ce508, v138
	v_rcp_f32_e32 v156, v138
	global_load_dwordx4 v[138:141], v[150:151], off
	v_and_b32_e32 v152, 0xffff0000, v152
	v_pk_mul_f32 v[104:105], v[104:105], v[146:147]
	v_lshlrev_b32_e32 v146, 16, v148
	v_and_b32_e32 v147, 0xffff0000, v148
	v_lshlrev_b32_e32 v148, 16, v153
	v_max_f32_e32 v152, v152, v152
	v_max_f32_e32 v148, v148, v148
	v_max_f32_e32 v152, 0x1e3ce508, v152
	v_max_f32_e32 v148, 0x1e3ce508, v148
	v_rcp_f32_e32 v157, v152
	v_rcp_f32_e32 v152, v148
	v_and_b32_e32 v148, 0xffff0000, v153
	v_max_f32_e32 v148, v148, v148
	v_max_f32_e32 v148, 0x1e3ce508, v148
	v_rcp_f32_e32 v153, v148
	s_waitcnt vmcnt(3)
; __device__ __forceinline__ float bf_lo(unsigned w) { return __uint_as_float(w << 16); }
; __device__ __forceinline__ float bf_hi(unsigned w) { return __uint_as_float(w & 0xffff0000u); }
;     __device__ __forceinline__ void mid(f32x4 (&acc)[2][2][4][2], const Unit& u, int wr, int wc, int fr, int fq) const {
;         asm volatile("" : "+v"(fr), "+v"(fq));
;         const int row0 = u.pm * BM + wr * 64 + fr, col0 = u.pn * BM + wc * 32 + 8 * fq;
; #pragma unroll
;         for (int ai = 0; ai < 2; ++ai)
; #pragma unroll
;             for (int m = 0; m < 4; ++m) { const size_t off = (size_t)(row0 + ai * HALF + m * 16) * 4096 + col0;
; #pragma unroll
;                 for (int bj = 0; bj < 2; ++bj) { const u32x4 ga = *(const u32x4*)(SGA + off + bj * HALF), gb = *(const u32x4*)(SGB + off + bj * HALF);
;                     const unsigned wa[4] = {ga.x, ga.y, ga.z, ga.w}, wb[4] = {gb.x, gb.y, gb.z, gb.w};
; #pragma unroll
;                     for (int p = 0; p < 4; ++p) { const float rl = bf_lo(wa[p]) * __builtin_amdgcn_rcpf(fmaxf(bf_lo(wb[p]), 1e-20f)), rh = bf_hi(wa[p]) * __builtin_amdgcn_rcpf(fmaxf(bf_hi(wb[p]), 1e-20f));
;                         acc[ai][bj][m][p >> 1][(p & 1) * 2] *= rl; acc[ai][bj][m][p >> 1][(p & 1) * 2 + 1] *= rh; } }
;                 if (m == 3) asm volatile("" : "+v"(acc[ai][0][0][0]), "+v"(acc[ai][0][0][1]), "+v"(acc[ai][1][0][0]), "+v"(acc[ai][1][0][1]), "+v"(acc[ai][0][1][0]), "+v"(acc[ai][0][1][1]), "+v"(acc[ai][1][1][0]), "+v"(acc[ai][1][1][1]), "+v"(acc[ai][0][2][0]), "+v"(acc[ai][0][2][1]), "+v"(acc[ai][1][2][0]), "+v"(acc[ai][1][2][1]), "+v"(acc[ai][0][3][0]), "+v"(acc[ai][0][3][1]), "+v"(acc[ai][1][3][0]), "+v"(acc[ai][1][3][1]) :: "memory"); }
;     }
	v_lshlrev_b32_e32 v148, 16, v142
	v_and_b32_e32 v142, 0xffff0000, v142
	v_max_f32_e32 v148, v148, v148
	v_max_f32_e32 v142, v142, v142
	v_pk_mul_f32 v[146:147], v[156:157], v[146:147]
	v_max_f32_e32 v148, 0x1e3ce508, v148
	v_max_f32_e32 v142, 0x1e3ce508, v142
	v_pk_mul_f32 v[98:99], v[98:99], v[146:147]
	v_lshlrev_b32_e32 v146, 16, v149
	v_and_b32_e32 v147, 0xffff0000, v149
	v_rcp_f32_e32 v148, v148
	v_rcp_f32_e32 v149, v142
	v_pk_mul_f32 v[146:147], v[152:153], v[146:147]
	global_load_dwordx4 v[150:153], v[150:151], off offset:256
	v_pk_mul_f32 v[100:101], v[100:101], v[146:147]
	s_waitcnt vmcnt(3)
	v_lshlrev_b32_e32 v146, 16, v134
	v_and_b32_e32 v147, 0xffff0000, v134
	v_pk_mul_f32 v[146:147], v[148:149], v[146:147]
	v_lshlrev_b32_e32 v134, 16, v143
	v_pk_mul_f32 v[94:95], v[94:95], v[146:147]
	global_load_dwordx4 v[146:149], v[154:155], off offset:256
	v_max_f32_e32 v134, v134, v134
	v_max_f32_e32 v134, 0x1e3ce508, v134
	v_rcp_f32_e32 v142, v134
	v_and_b32_e32 v134, 0xffff0000, v143
	v_max_f32_e32 v134, v134, v134
	v_max_f32_e32 v134, 0x1e3ce508, v134
	v_rcp_f32_e32 v143, v134
	v_lshlrev_b32_e32 v134, 16, v135
	v_and_b32_e32 v135, 0xffff0000, v135
	v_pk_mul_f32 v[134:135], v[142:143], v[134:135]
	s_nop 0
	v_pk_mul_f32 v[96:97], v[96:97], v[134:135]
	v_lshlrev_b32_e32 v134, 16, v144
	v_and_b32_e32 v135, 0xffff0000, v144
	v_max_f32_e32 v134, v134, v134
	v_max_f32_e32 v135, v135, v135
	v_max_f32_e32 v134, 0x1e3ce508, v134
	v_max_f32_e32 v135, 0x1e3ce508, v135
	v_rcp_f32_e32 v134, v134
	v_rcp_f32_e32 v135, v135
	v_lshlrev_b32_e32 v142, 16, v136
	v_and_b32_e32 v143, 0xffff0000, v136
	v_lshlrev_b32_e32 v136, 16, v145
	v_max_f32_e32 v136, v136, v136
	v_max_f32_e32 v136, 0x1e3ce508, v136
	v_pk_mul_f32 v[134:135], v[134:135], v[142:143]
	v_rcp_f32_e32 v142, v136
	v_and_b32_e32 v136, 0xffff0000, v145
	v_max_f32_e32 v136, v136, v136
	v_max_f32_e32 v136, 0x1e3ce508, v136
	v_rcp_f32_e32 v143, v136
	v_pk_mul_f32 v[86:87], v[86:87], v[134:135]
	v_lshlrev_b32_e32 v134, 16, v137
	v_and_b32_e32 v135, 0xffff0000, v137
	v_pk_mul_f32 v[134:135], v[142:143], v[134:135]
	s_waitcnt vmcnt(3)
	v_lshlrev_b32_e32 v136, 16, v130
	v_and_b32_e32 v130, 0xffff0000, v130
	v_max_f32_e32 v130, v130, v130
	v_max_f32_e32 v130, 0x1e3ce508, v130
	v_rcp_f32_e32 v137, v130
	v_lshlrev_b32_e32 v130, 16, v131
	v_max_f32_e32 v136, v136, v136
	v_max_f32_e32 v130, v130, v130
	v_max_f32_e32 v136, 0x1e3ce508, v136
	v_max_f32_e32 v130, 0x1e3ce508, v130
	v_rcp_f32_e32 v136, v136
	v_rcp_f32_e32 v142, v130
	v_and_b32_e32 v130, 0xffff0000, v131
	v_max_f32_e32 v130, v130, v130
	v_max_f32_e32 v130, 0x1e3ce508, v130
	v_pk_mul_f32 v[88:89], v[88:89], v[134:135]
	s_waitcnt vmcnt(2)
	v_lshlrev_b32_e32 v134, 16, v138
	v_and_b32_e32 v135, 0xffff0000, v138
	v_rcp_f32_e32 v143, v130
	v_lshl_add_u64 v[144:145], v[162:163], 0, s[0:1]
	v_pk_mul_f32 v[134:135], v[136:137], v[134:135]
	v_lshl_add_u64 v[130:131], s[12:13], 0, v[144:145]
	v_pk_mul_f32 v[74:75], v[74:75], v[134:135]
	global_load_dwordx4 v[134:137], v[130:131], off
	v_lshlrev_b32_e32 v138, 16, v139
	v_and_b32_e32 v139, 0xffff0000, v139
	v_pk_mul_f32 v[154:155], v[142:143], v[138:139]
	v_lshlrev_b32_e32 v138, 16, v132
	v_max_f32_e32 v138, v138, v138
	v_and_b32_e32 v132, 0xffff0000, v132
	v_max_f32_e32 v138, 0x1e3ce508, v138
	v_max_f32_e32 v132, v132, v132
	v_rcp_f32_e32 v156, v138
	v_lshl_add_u64 v[138:139], s[10:11], 0, v[144:145]
	v_max_f32_e32 v132, 0x1e3ce508, v132
	global_load_dwordx4 v[142:145], v[138:139], off
	v_rcp_f32_e32 v157, v132
	v_lshlrev_b32_e32 v132, 16, v133
	v_and_b32_e32 v133, 0xffff0000, v133
	v_max_f32_e32 v132, v132, v132
	v_max_f32_e32 v133, v133, v133
	v_max_f32_e32 v132, 0x1e3ce508, v132
	v_max_f32_e32 v133, 0x1e3ce508, v133
	v_rcp_f32_e32 v132, v132
	v_rcp_f32_e32 v133, v133
	v_pk_mul_f32 v[76:77], v[76:77], v[154:155]
	v_lshlrev_b32_e32 v154, 16, v140
	v_and_b32_e32 v155, 0xffff0000, v140
	v_lshlrev_b32_e32 v140, 16, v141
	v_and_b32_e32 v141, 0xffff0000, v141
	v_pk_mul_f32 v[132:133], v[132:133], v[140:141]
	s_waitcnt vmcnt(2)
	v_lshlrev_b32_e32 v140, 16, v146
	v_and_b32_e32 v141, 0xffff0000, v146
	v_max_f32_e32 v140, v140, v140
	v_max_f32_e32 v141, v141, v141
	v_max_f32_e32 v140, 0x1e3ce508, v140
	v_max_f32_e32 v141, 0x1e3ce508, v141
	v_rcp_f32_e32 v140, v140
	v_rcp_f32_e32 v141, v141
	v_pk_mul_f32 v[72:73], v[72:73], v[132:133]
	v_lshlrev_b32_e32 v132, 16, v150
	v_and_b32_e32 v133, 0xffff0000, v150
	v_pk_mul_f32 v[132:133], v[140:141], v[132:133]
	v_lshlrev_b32_e32 v140, 16, v147
	v_and_b32_e32 v141, 0xffff0000, v147
	v_max_f32_e32 v140, v140, v140
	v_max_f32_e32 v141, v141, v141
	v_max_f32_e32 v140, 0x1e3ce508, v140
	v_max_f32_e32 v141, 0x1e3ce508, v141
	v_rcp_f32_e32 v140, v140
	v_rcp_f32_e32 v141, v141
	v_pk_mul_f32 v[66:67], v[66:67], v[132:133]
	v_lshlrev_b32_e32 v132, 16, v151
	v_and_b32_e32 v133, 0xffff0000, v151
	v_pk_mul_f32 v[132:133], v[140:141], v[132:133]
	v_lshlrev_b32_e32 v140, 16, v148
	v_pk_mul_f32 v[68:69], v[68:69], v[132:133]
	global_load_dwordx4 v[130:133], v[130:131], off offset:256
	v_max_f32_e32 v140, v140, v140
	v_max_f32_e32 v140, 0x1e3ce508, v140
	v_rcp_f32_e32 v146, v140
	v_and_b32_e32 v140, 0xffff0000, v148
	v_max_f32_e32 v140, v140, v140
	v_max_f32_e32 v140, 0x1e3ce508, v140
	v_rcp_f32_e32 v147, v140
	global_load_dwordx4 v[138:141], v[138:139], off offset:256
	v_lshlrev_b32_e32 v148, 16, v149
	v_and_b32_e32 v149, 0xffff0000, v149
	v_max_f32_e32 v148, v148, v148
	v_max_f32_e32 v149, v149, v149
	v_max_f32_e32 v148, 0x1e3ce508, v148
	v_max_f32_e32 v149, 0x1e3ce508, v149
	v_rcp_f32_e32 v148, v148
	v_rcp_f32_e32 v149, v149
	v_lshlrev_b32_e32 v150, 16, v152
	v_and_b32_e32 v151, 0xffff0000, v152
	v_pk_mul_f32 v[146:147], v[146:147], v[150:151]
	s_mov_b64 s[0:1], 0x160000
	v_pk_mul_f32 v[54:55], v[54:55], v[146:147]
	v_lshlrev_b32_e32 v146, 16, v153
	v_and_b32_e32 v147, 0xffff0000, v153
	v_pk_mul_f32 v[146:147], v[148:149], v[146:147]
	v_pk_mul_f32 v[154:155], v[156:157], v[154:155]
	s_waitcnt vmcnt(3)
; __device__ __forceinline__ float bf_lo(unsigned w) { return __uint_as_float(w << 16); }
; __device__ __forceinline__ float bf_hi(unsigned w) { return __uint_as_float(w & 0xffff0000u); }
;     __device__ bool next(int i, Unit& u) const { if (i > 1) return false; const int xcd = c & 7, idx = c >> 3; u.pm = 16 * i + 4 * (xcd >> 1) + (idx & 3); u.pn = 8 * (xcd & 1) + (idx >> 2); return true; }
;     __host__ __device__ bool next(int i, Unit& u) const {
;         const long L = (long)i * G + c; if (L >= nwg) return false;
;         int wgid = (int)L; { const int q = nwg / NXCD, r = nwg % NXCD, xcd = wgid % NXCD, off = wgid / NXCD; wgid = (xcd < r ? xcd * (q + 1) : r * (q + 1) + (xcd - r) * q) + off; }
;     __device__ __forceinline__ void mid(f32x4 (&acc)[2][2][4][2], const Unit& u, int wr, int wc, int fr, int fq) const {
;         asm volatile("" : "+v"(fr), "+v"(fq));
;         const int row0 = u.pm * BM + wr * 64 + fr, col0 = u.pn * BM + wc * 32 + 8 * fq;
; #pragma unroll
;         for (int ai = 0; ai < 2; ++ai)
; #pragma unroll
;             for (int m = 0; m < 4; ++m) { const size_t off = (size_t)(row0 + ai * HALF + m * 16) * 4096 + col0;
; #pragma unroll
;                 for (int bj = 0; bj < 2; ++bj) { const u32x4 ga = *(const u32x4*)(SGA + off + bj * HALF), gb = *(const u32x4*)(SGB + off + bj * HALF);
;                     const unsigned wa[4] = {ga.x, ga.y, ga.z, ga.w}, wb[4] = {gb.x, gb.y, gb.z, gb.w};
; #pragma unroll
;                     for (int p = 0; p < 4; ++p) { const float rl = bf_lo(wa[p]) * __builtin_amdgcn_rcpf(fmaxf(bf_lo(wb[p]), 1e-20f)), rh = bf_hi(wa[p]) * __builtin_amdgcn_rcpf(fmaxf(bf_hi(wb[p]), 1e-20f));
;                         acc[ai][bj][m][p >> 1][(p & 1) * 2] *= rl; acc[ai][bj][m][p >> 1][(p & 1) * 2 + 1] *= rh; } }
;                 if (m == 3) asm volatile("" : "+v"(acc[ai][0][0][0]), "+v"(acc[ai][0][0][1]), "+v"(acc[ai][1][0][0]), "+v"(acc[ai][1][0][1]), "+v"(acc[ai][0][1][0]), "+v"(acc[ai][0][1][1]), "+v"(acc[ai][1][1][0]), "+v"(acc[ai][1][1][1]), "+v"(acc[ai][0][2][0]), "+v"(acc[ai][0][2][1]), "+v"(acc[ai][1][2][0]), "+v"(acc[ai][1][2][1]), "+v"(acc[ai][0][3][0]), "+v"(acc[ai][0][3][1]), "+v"(acc[ai][1][3][0]), "+v"(acc[ai][1][3][1]) :: "memory"); }
;     }
	v_lshlrev_b32_e32 v148, 16, v134
	v_and_b32_e32 v134, 0xffff0000, v134
	v_max_f32_e32 v148, v148, v148
	v_max_f32_e32 v134, v134, v134
	v_max_f32_e32 v148, 0x1e3ce508, v148
	v_max_f32_e32 v134, 0x1e3ce508, v134
	v_rcp_f32_e32 v148, v148
	v_rcp_f32_e32 v149, v134
	v_pk_mul_f32 v[56:57], v[56:57], v[146:147]
	v_lshl_add_u64 v[150:151], v[162:163], 0, s[0:1]
	v_pk_mul_f32 v[70:71], v[70:71], v[154:155]
	v_lshlrev_b32_e32 v134, 16, v135
	s_waitcnt vmcnt(2)
	v_lshlrev_b32_e32 v146, 16, v142
	v_and_b32_e32 v147, 0xffff0000, v142
	v_pk_mul_f32 v[146:147], v[148:149], v[146:147]
	v_and_b32_e32 v135, 0xffff0000, v135
	v_lshl_add_u64 v[154:155], s[12:13], 0, v[150:151]
	v_pk_mul_f32 v[42:43], v[42:43], v[146:147]
	v_max_f32_e32 v134, v134, v134
	v_max_f32_e32 v135, v135, v135
	global_load_dwordx4 v[146:149], v[154:155], off
	v_max_f32_e32 v134, 0x1e3ce508, v134
	v_max_f32_e32 v135, 0x1e3ce508, v135
	v_rcp_f32_e32 v134, v134
	v_rcp_f32_e32 v135, v135
	v_lshlrev_b32_e32 v142, 16, v143
	v_and_b32_e32 v143, 0xffff0000, v143
	s_mul_i32 s0, s50, s63
	v_pk_mul_f32 v[142:143], v[134:135], v[142:143]
	v_lshlrev_b32_e32 v134, 16, v136
	v_max_f32_e32 v134, v134, v134
	v_max_f32_e32 v134, 0x1e3ce508, v134
	v_rcp_f32_e32 v156, v134
	v_lshl_add_u64 v[134:135], s[10:11], 0, v[150:151]
	global_load_dwordx4 v[150:153], v[134:135], off
	v_and_b32_e32 v136, 0xffff0000, v136
	v_max_f32_e32 v136, v136, v136
	v_max_f32_e32 v136, 0x1e3ce508, v136
	v_rcp_f32_e32 v157, v136
	v_lshlrev_b32_e32 v136, 16, v137
	v_and_b32_e32 v137, 0xffff0000, v137
	v_max_f32_e32 v136, v136, v136
	v_max_f32_e32 v137, v137, v137
	v_max_f32_e32 v136, 0x1e3ce508, v136
	v_max_f32_e32 v137, 0x1e3ce508, v137
	v_rcp_f32_e32 v136, v136
	v_rcp_f32_e32 v137, v137
	v_pk_mul_f32 v[44:45], v[44:45], v[142:143]
	v_lshlrev_b32_e32 v142, 16, v144
	v_and_b32_e32 v143, 0xffff0000, v144
	v_pk_mul_f32 v[142:143], v[156:157], v[142:143]
	s_mul_hi_u32 s1, s50, s2
	v_pk_mul_f32 v[38:39], v[38:39], v[142:143]
	v_lshlrev_b32_e32 v142, 16, v145
	v_and_b32_e32 v143, 0xffff0000, v145
	v_pk_mul_f32 v[136:137], v[136:137], v[142:143]
	s_waitcnt vmcnt(3)
	v_lshlrev_b32_e32 v142, 16, v130
	v_and_b32_e32 v130, 0xffff0000, v130
	v_max_f32_e32 v142, v142, v142
	v_max_f32_e32 v130, v130, v130
	v_max_f32_e32 v142, 0x1e3ce508, v142
	v_max_f32_e32 v130, 0x1e3ce508, v130
	v_rcp_f32_e32 v142, v142
	v_rcp_f32_e32 v143, v130
	v_lshlrev_b32_e32 v130, 16, v131
	v_and_b32_e32 v131, 0xffff0000, v131
	v_pk_mul_f32 v[40:41], v[40:41], v[136:137]
	s_waitcnt vmcnt(2)
	v_lshlrev_b32_e32 v136, 16, v138
	v_and_b32_e32 v137, 0xffff0000, v138
	v_max_f32_e32 v130, v130, v130
	v_max_f32_e32 v131, v131, v131
	v_pk_mul_f32 v[136:137], v[142:143], v[136:137]
	v_max_f32_e32 v130, 0x1e3ce508, v130
	global_load_dwordx4 v[142:145], v[154:155], off offset:256
	v_max_f32_e32 v131, 0x1e3ce508, v131
	v_rcp_f32_e32 v130, v130
	v_rcp_f32_e32 v131, v131
	v_pk_mul_f32 v[22:23], v[22:23], v[136:137]
	v_lshlrev_b32_e32 v136, 16, v139
	v_and_b32_e32 v137, 0xffff0000, v139
	v_pk_mul_f32 v[130:131], v[130:131], v[136:137]
	v_lshlrev_b32_e32 v136, 16, v132
	v_max_f32_e32 v138, v136, v136
	global_load_dwordx4 v[134:137], v[134:135], off offset:256
	v_and_b32_e32 v132, 0xffff0000, v132
	v_max_f32_e32 v132, v132, v132
	v_max_f32_e32 v132, 0x1e3ce508, v132
	v_max_f32_e32 v138, 0x1e3ce508, v138
	v_rcp_f32_e32 v139, v132
	v_lshlrev_b32_e32 v132, 16, v133
	v_and_b32_e32 v133, 0xffff0000, v133
	v_rcp_f32_e32 v138, v138
	v_max_f32_e32 v132, v132, v132
	v_max_f32_e32 v133, v133, v133
	v_max_f32_e32 v132, 0x1e3ce508, v132
	v_max_f32_e32 v133, 0x1e3ce508, v133
	v_rcp_f32_e32 v132, v132
	v_rcp_f32_e32 v133, v133
	v_pk_mul_f32 v[24:25], v[24:25], v[130:131]
	v_lshlrev_b32_e32 v130, 16, v140
	v_and_b32_e32 v131, 0xffff0000, v140
	v_pk_mul_f32 v[130:131], v[138:139], v[130:131]
	s_add_i32 s1, s1, s0
	v_pk_mul_f32 v[130:131], v[14:15], v[130:131]
	v_lshlrev_b32_e32 v14, 16, v141
	v_and_b32_e32 v15, 0xffff0000, v141
	v_pk_mul_f32 v[14:15], v[132:133], v[14:15]
	s_waitcnt vmcnt(3)
; __device__ __forceinline__ float bf_lo(unsigned w) { return __uint_as_float(w << 16); }
; __device__ __forceinline__ float bf_hi(unsigned w) { return __uint_as_float(w & 0xffff0000u); }
;     __device__ bool next(int i, Unit& u) const { if (i > 1) return false; const int xcd = c & 7, idx = c >> 3; u.pm = 16 * i + 4 * (xcd >> 1) + (idx & 3); u.pn = 8 * (xcd & 1) + (idx >> 2); return true; }
;     __host__ __device__ bool next(int i, Unit& u) const {
;         const long L = (long)i * G + c; if (L >= nwg) return false;
;         int wgid = (int)L; { const int q = nwg / NXCD, r = nwg % NXCD, xcd = wgid % NXCD, off = wgid / NXCD; wgid = (xcd < r ? xcd * (q + 1) : r * (q + 1) + (xcd - r) * q) + off; }
;     __device__ __forceinline__ void mid(f32x4 (&acc)[2][2][4][2], const Unit& u, int wr, int wc, int fr, int fq) const {
;     ...
;                 for (int bj = 0; bj < 2; ++bj) { const u32x4 ga = *(const u32x4*)(SGA + off + bj * HALF), gb = *(const u32x4*)(SGB + off + bj * HALF);
;                     const unsigned wa[4] = {ga.x, ga.y, ga.z, ga.w}, wb[4] = {gb.x, gb.y, gb.z, gb.w};
; #pragma unroll
;                     for (int p = 0; p < 4; ++p) { const float rl = bf_lo(wa[p]) * __builtin_amdgcn_rcpf(fmaxf(bf_lo(wb[p]), 1e-20f)), rh = bf_hi(wa[p]) * __builtin_amdgcn_rcpf(fmaxf(bf_hi(wb[p]), 1e-20f));
;                         acc[ai][bj][m][p >> 1][(p & 1) * 2] *= rl; acc[ai][bj][m][p >> 1][(p & 1) * 2 + 1] *= rh; } }
;                 if (m == 3) asm volatile("" : "+v"(acc[ai][0][0][0]), "+v"(acc[ai][0][0][1]), "+v"(acc[ai][1][0][0]), "+v"(acc[ai][1][0][1]), "+v"(acc[ai][0][1][0]), "+v"(acc[ai][0][1][1]), "+v"(acc[ai][1][1][0]), "+v"(acc[ai][1][1][1]), "+v"(acc[ai][0][2][0]), "+v"(acc[ai][0][2][1]), "+v"(acc[ai][1][2][0]), "+v"(acc[ai][1][2][1]), "+v"(acc[ai][0][3][0]), "+v"(acc[ai][0][3][1]), "+v"(acc[ai][1][3][0]), "+v"(acc[ai][1][3][1]) :: "memory"); }
	v_lshlrev_b32_e32 v132, 16, v146
	v_max_f32_e32 v132, v132, v132
	v_max_f32_e32 v132, 0x1e3ce508, v132
	v_rcp_f32_e32 v138, v132
	v_and_b32_e32 v132, 0xffff0000, v146
	v_max_f32_e32 v132, v132, v132
	v_max_f32_e32 v132, 0x1e3ce508, v132
	v_rcp_f32_e32 v139, v132
	v_pk_mul_f32 v[132:133], v[16:17], v[14:15]
	v_lshlrev_b32_e32 v16, 16, v147
	v_and_b32_e32 v17, 0xffff0000, v147
	v_max_f32_e32 v16, v16, v16
	v_max_f32_e32 v17, v17, v17
	v_max_f32_e32 v16, 0x1e3ce508, v16
	v_max_f32_e32 v17, 0x1e3ce508, v17
	v_rcp_f32_e32 v16, v16
	v_rcp_f32_e32 v17, v17
	s_waitcnt vmcnt(2)
	v_lshlrev_b32_e32 v14, 16, v150
	v_and_b32_e32 v15, 0xffff0000, v150
	v_pk_mul_f32 v[14:15], v[138:139], v[14:15]
	s_mul_i32 s0, s50, s2
	v_pk_mul_f32 v[14:15], v[18:19], v[14:15]
	v_lshlrev_b32_e32 v18, 16, v151
	v_and_b32_e32 v19, 0xffff0000, v151
	v_pk_mul_f32 v[16:17], v[16:17], v[18:19]
	v_lshlrev_b32_e32 v18, 16, v148
	v_and_b32_e32 v19, 0xffff0000, v148
	v_max_f32_e32 v18, v18, v18
	v_max_f32_e32 v19, v19, v19
	v_max_f32_e32 v18, 0x1e3ce508, v18
	v_max_f32_e32 v19, 0x1e3ce508, v19
	v_rcp_f32_e32 v18, v18
	v_rcp_f32_e32 v19, v19
	v_pk_mul_f32 v[16:17], v[20:21], v[16:17]
	v_lshlrev_b32_e32 v20, 16, v152
	v_and_b32_e32 v21, 0xffff0000, v152
	v_pk_mul_f32 v[18:19], v[18:19], v[20:21]
	v_lshlrev_b32_e32 v20, 16, v149
	v_and_b32_e32 v21, 0xffff0000, v149
	v_max_f32_e32 v20, v20, v20
	v_max_f32_e32 v21, v21, v21
	v_max_f32_e32 v20, 0x1e3ce508, v20
	v_max_f32_e32 v21, 0x1e3ce508, v21
	v_rcp_f32_e32 v20, v20
	v_rcp_f32_e32 v21, v21
	v_pk_mul_f32 v[10:11], v[10:11], v[18:19]
	v_lshlrev_b32_e32 v18, 16, v153
	v_and_b32_e32 v19, 0xffff0000, v153
	v_pk_mul_f32 v[18:19], v[20:21], v[18:19]
	s_waitcnt vmcnt(1)
	v_lshlrev_b32_e32 v20, 16, v142
	v_and_b32_e32 v21, 0xffff0000, v142
	v_max_f32_e32 v20, v20, v20
	v_max_f32_e32 v21, v21, v21
	v_max_f32_e32 v20, 0x1e3ce508, v20
	v_max_f32_e32 v21, 0x1e3ce508, v21
	v_rcp_f32_e32 v20, v20
	v_rcp_f32_e32 v21, v21
	v_pk_mul_f32 v[12:13], v[12:13], v[18:19]
	s_waitcnt vmcnt(0)
	v_lshlrev_b32_e32 v18, 16, v134
	v_and_b32_e32 v19, 0xffff0000, v134
	v_pk_mul_f32 v[18:19], v[20:21], v[18:19]
	v_lshlrev_b32_e32 v20, 16, v143
	v_and_b32_e32 v21, 0xffff0000, v143
	v_max_f32_e32 v20, v20, v20
	v_max_f32_e32 v21, v21, v21
	v_max_f32_e32 v20, 0x1e3ce508, v20
	v_max_f32_e32 v21, 0x1e3ce508, v21
	v_rcp_f32_e32 v20, v20
	v_rcp_f32_e32 v21, v21
	v_pk_mul_f32 v[6:7], v[6:7], v[18:19]
	v_lshlrev_b32_e32 v18, 16, v135
	v_and_b32_e32 v19, 0xffff0000, v135
	v_pk_mul_f32 v[18:19], v[20:21], v[18:19]
	v_lshlrev_b32_e32 v20, 16, v144
	v_and_b32_e32 v21, 0xffff0000, v144
	v_max_f32_e32 v20, v20, v20
	v_max_f32_e32 v21, v21, v21
	v_max_f32_e32 v20, 0x1e3ce508, v20
	v_max_f32_e32 v21, 0x1e3ce508, v21
	v_rcp_f32_e32 v20, v20
	v_rcp_f32_e32 v21, v21
	v_pk_mul_f32 v[8:9], v[8:9], v[18:19]
	v_lshlrev_b32_e32 v18, 16, v136
	v_and_b32_e32 v19, 0xffff0000, v136
	v_pk_mul_f32 v[18:19], v[20:21], v[18:19]
	v_lshlrev_b32_e32 v20, 16, v145
	v_and_b32_e32 v21, 0xffff0000, v145
	v_max_f32_e32 v20, v20, v20
	v_max_f32_e32 v21, v21, v21
	v_max_f32_e32 v20, 0x1e3ce508, v20
	v_max_f32_e32 v21, 0x1e3ce508, v21
	v_rcp_f32_e32 v20, v20
	v_rcp_f32_e32 v21, v21
	v_pk_mul_f32 v[2:3], v[2:3], v[18:19]
	v_lshlrev_b32_e32 v18, 16, v137
	v_and_b32_e32 v19, 0xffff0000, v137
	v_pk_mul_f32 v[18:19], v[20:21], v[18:19]
	v_readlane_b32 s2, v238, 44
	v_pk_mul_f32 v[4:5], v[4:5], v[18:19]
	s_add_u32 s2, s0, s2
	s_addc_u32 s3, s1, s28
	v_cmp_gt_i64_e32 vcc, s[2:3], v[160:161]
	v_cmp_lt_i64_e64 s[0:1], s[2:3], v[158:159]
	s_cbranch_vccnz .LBB0_753
	s_ashr_i32 s3, s2, 31
	s_lshr_b32 s3, s3, 29
	s_add_i32 s4, s2, s3
	s_and_b32 s3, s4, -8
	s_sub_i32 s5, s2, s3
	s_cmp_gt_i32 s5, -1
	s_mov_b64 s[2:3], -1
	s_cbranch_scc0 .LBB0_750
	s_lshl_b32 s16, s5, 6
	s_mov_b64 s[2:3], 0

.LBB0_754:
	s_add_u32 s2, s30, 0x100
	s_addc_u32 s3, s31, 0
	s_cmp_eq_u32 s37, 60
	s_cselect_b32 s26, s33, s2
	s_cselect_b32 s27, s5, s3
	s_cselect_b32 s24, s36, s34
	s_cselect_b32 s25, s21, s35
	s_add_u32 s16, s26, 0x80
	s_addc_u32 s17, s27, 0
	s_add_u32 s30, s30, 0x100080
	s_addc_u32 s31, s31, 0
	s_mov_b32 m0, s76
	ds_read_b128 v[206:209], v174 offset:6144
	global_load_lds_dwordx4 v1, s[30:31]
	s_mov_b32 m0, s77
	ds_read_b128 v[210:213], v174 offset:7168
	global_load_lds_dwordx4 v165, s[30:31]
	ds_read_b128 v[18:21], v172
	ds_read_b128 v[134:137], v172 offset:1024
	ds_read_b128 v[138:141], v172 offset:2048
	ds_read_b128 v[142:145], v172 offset:3072
	ds_read_b128 v[146:149], v173
	ds_read_b128 v[150:153], v173 offset:1024
	ds_read_b128 v[154:157], v173 offset:2048
	ds_read_b128 v[178:181], v173 offset:3072
	ds_read_b128 v[182:185], v174
	ds_read_b128 v[186:189], v174 offset:1024
	ds_read_b128 v[190:193], v174 offset:2048
	ds_read_b128 v[194:197], v174 offset:3072
	ds_read_b128 v[198:201], v174 offset:4096
	ds_read_b128 v[202:205], v174 offset:5120
	s_waitcnt vmcnt(8)
	s_waitcnt lgkmcnt(0)
	s_setprio 1
	s_waitcnt lgkmcnt(0)
	s_barrier
	v_mfma_f32_16x16x32_bf16 v[34:37], v[18:21], v[182:185], v[34:37]
	v_mfma_f32_16x16x32_bf16 v[30:33], v[138:141], v[182:185], v[30:33]
	v_mfma_f32_16x16x32_bf16 v[46:49], v[18:21], v[190:193], v[46:49]
	v_mfma_f32_16x16x32_bf16 v[62:65], v[138:141], v[190:193], v[62:65]
	v_mfma_f32_16x16x32_bf16 v[78:81], v[18:21], v[198:201], v[78:81]
	v_mfma_f32_16x16x32_bf16 v[90:93], v[138:141], v[198:201], v[90:93]
	v_mfma_f32_16x16x32_bf16 v[106:109], v[18:21], v[206:209], v[106:109]
	v_mfma_f32_16x16x32_bf16 v[114:117], v[138:141], v[206:209], v[114:117]
	v_mfma_f32_16x16x32_bf16 v[26:29], v[146:149], v[182:185], v[26:29]
	v_mfma_f32_16x16x32_bf16 v[50:53], v[154:157], v[182:185], v[50:53]
	v_mfma_f32_16x16x32_bf16 v[58:61], v[146:149], v[190:193], v[58:61]
	v_mfma_f32_16x16x32_bf16 v[82:85], v[154:157], v[190:193], v[82:85]
	v_mfma_f32_16x16x32_bf16 v[110:113], v[146:149], v[198:201], v[110:113]
	v_mfma_f32_16x16x32_bf16 v[118:121], v[154:157], v[198:201], v[118:121]
	v_mfma_f32_16x16x32_bf16 v[122:125], v[146:149], v[206:209], v[122:125]
	v_mfma_f32_16x16x32_bf16 v[126:129], v[154:157], v[206:209], v[126:129]
	v_mfma_f32_16x16x32_bf16 v[34:37], v[134:137], v[186:189], v[34:37]
	v_mfma_f32_16x16x32_bf16 v[30:33], v[142:145], v[186:189], v[30:33]
	v_mfma_f32_16x16x32_bf16 v[46:49], v[134:137], v[194:197], v[46:49]
	v_mfma_f32_16x16x32_bf16 v[62:65], v[142:145], v[194:197], v[62:65]
	v_mfma_f32_16x16x32_bf16 v[78:81], v[134:137], v[202:205], v[78:81]
	v_mfma_f32_16x16x32_bf16 v[90:93], v[142:145], v[202:205], v[90:93]
	v_mfma_f32_16x16x32_bf16 v[106:109], v[134:137], v[210:213], v[106:109]
	v_mfma_f32_16x16x32_bf16 v[114:117], v[142:145], v[210:213], v[114:117]
	v_mfma_f32_16x16x32_bf16 v[26:29], v[150:153], v[186:189], v[26:29]
	v_mfma_f32_16x16x32_bf16 v[50:53], v[178:181], v[186:189], v[50:53]
	v_mfma_f32_16x16x32_bf16 v[58:61], v[150:153], v[194:197], v[58:61]
	v_mfma_f32_16x16x32_bf16 v[82:85], v[178:181], v[194:197], v[82:85]
	v_mfma_f32_16x16x32_bf16 v[110:113], v[150:153], v[202:205], v[110:113]
	v_mfma_f32_16x16x32_bf16 v[118:121], v[178:181], v[202:205], v[118:121]
	v_mfma_f32_16x16x32_bf16 v[122:125], v[150:153], v[210:213], v[122:125]
	v_mfma_f32_16x16x32_bf16 v[126:129], v[178:181], v[210:213], v[126:129]
	s_setprio 0
	s_barrier
	s_mov_b32 m0, s80
	s_mov_b64 s[30:31], s[24:25]
	ds_read_b128 v[190:193], v174 offset:18432
	global_load_lds_dwordx4 v164, s[30:31]
	s_mov_b32 m0, s81
	ds_read_b128 v[194:197], v174 offset:19456
	global_load_lds_dwordx4 v166, s[30:31]
	s_add_u32 s30, s24, 0x100000
	s_addc_u32 s31, s25, 0
	s_mov_b32 m0, s82
	ds_read_b128 v[198:201], v174 offset:20480
	global_load_lds_dwordx4 v164, s[30:31]
	s_mov_b32 m0, s83
	ds_read_b128 v[202:205], v174 offset:21504
	global_load_lds_dwordx4 v166, s[30:31]
	s_mov_b64 s[30:31], s[26:27]
	s_mov_b32 m0, s46
	ds_read_b128 v[206:209], v174 offset:22528
	global_load_lds_dwordx4 v1, s[30:31]
	s_mov_b32 m0, s47
	ds_read_b128 v[210:213], v174 offset:23552
	global_load_lds_dwordx4 v165, s[30:31]
	ds_read_b128 v[182:185], v174 offset:16384
	ds_read_b128 v[186:189], v174 offset:17408
	s_waitcnt vmcnt(8)
	s_waitcnt lgkmcnt(0)
	s_setprio 1
	s_waitcnt lgkmcnt(0)
	s_barrier
	v_mfma_f32_16x16x32_bf16 v[102:105], v[18:21], v[182:185], v[102:105]
	v_mfma_f32_16x16x32_bf16 v[98:101], v[138:141], v[182:185], v[98:101]
	v_mfma_f32_16x16x32_bf16 v[74:77], v[18:21], v[190:193], v[74:77]
	v_mfma_f32_16x16x32_bf16 v[70:73], v[138:141], v[190:193], v[70:73]
	v_mfma_f32_16x16x32_bf16 v[42:45], v[18:21], v[198:201], v[42:45]
	v_mfma_f32_16x16x32_bf16 v[38:41], v[138:141], v[198:201], v[38:41]
	v_mfma_f32_16x16x32_bf16 v[14:17], v[18:21], v[206:209], v[14:17]
	v_mfma_f32_16x16x32_bf16 v[10:13], v[138:141], v[206:209], v[10:13]
	v_mfma_f32_16x16x32_bf16 v[18:21], v[146:149], v[182:185], v[94:97]
	v_mfma_f32_16x16x32_bf16 v[86:89], v[154:157], v[182:185], v[86:89]
	v_mfma_f32_16x16x32_bf16 v[66:69], v[146:149], v[190:193], v[66:69]
	v_mfma_f32_16x16x32_bf16 v[54:57], v[154:157], v[190:193], v[54:57]
	v_mfma_f32_16x16x32_bf16 v[22:25], v[146:149], v[198:201], v[22:25]
	v_mfma_f32_16x16x32_bf16 v[94:97], v[154:157], v[198:201], v[130:133]
	v_mfma_f32_16x16x32_bf16 v[6:9], v[146:149], v[206:209], v[6:9]
	v_mfma_f32_16x16x32_bf16 v[2:5], v[154:157], v[206:209], v[2:5]
	v_mfma_f32_16x16x32_bf16 v[102:105], v[134:137], v[186:189], v[102:105]
	v_mfma_f32_16x16x32_bf16 v[98:101], v[142:145], v[186:189], v[98:101]
	v_mfma_f32_16x16x32_bf16 v[74:77], v[134:137], v[194:197], v[74:77]
	v_mfma_f32_16x16x32_bf16 v[70:73], v[142:145], v[194:197], v[70:73]
	v_mfma_f32_16x16x32_bf16 v[42:45], v[134:137], v[202:205], v[42:45]
	v_mfma_f32_16x16x32_bf16 v[38:41], v[142:145], v[202:205], v[38:41]
	v_mfma_f32_16x16x32_bf16 v[14:17], v[134:137], v[210:213], v[14:17]
	v_mfma_f32_16x16x32_bf16 v[10:13], v[142:145], v[210:213], v[10:13]
	v_mfma_f32_16x16x32_bf16 v[86:89], v[178:181], v[186:189], v[86:89]
	v_mfma_f32_16x16x32_bf16 v[66:69], v[150:153], v[194:197], v[66:69]
	v_mfma_f32_16x16x32_bf16 v[54:57], v[178:181], v[194:197], v[54:57]
	v_mfma_f32_16x16x32_bf16 v[22:25], v[150:153], v[202:205], v[22:25]
	v_mfma_f32_16x16x32_bf16 v[130:133], v[178:181], v[202:205], v[94:97]
	v_mfma_f32_16x16x32_bf16 v[6:9], v[150:153], v[210:213], v[6:9]
	v_mfma_f32_16x16x32_bf16 v[2:5], v[178:181], v[210:213], v[2:5]
	v_mfma_f32_16x16x32_bf16 v[18:21], v[150:153], v[186:189], v[18:21]
	s_setprio 0
	s_barrier
	s_add_u32 s26, s26, 0x100000
	s_addc_u32 s27, s27, 0
	s_mov_b32 m0, s48
	ds_read_b128 v[206:209], v174 offset:38912
	global_load_lds_dwordx4 v1, s[26:27]
	s_mov_b32 m0, s49
	ds_read_b128 v[210:213], v174 offset:39936
	global_load_lds_dwordx4 v165, s[26:27]
	ds_read_b128 v[94:97], v175
	ds_read_b128 v[134:137], v175 offset:1024
	ds_read_b128 v[138:141], v175 offset:2048
	ds_read_b128 v[142:145], v175 offset:3072
	ds_read_b128 v[146:149], v176
	ds_read_b128 v[150:153], v176 offset:1024
	ds_read_b128 v[154:157], v176 offset:2048
	ds_read_b128 v[178:181], v176 offset:3072
	ds_read_b128 v[182:185], v174 offset:32768
	ds_read_b128 v[186:189], v174 offset:33792
	ds_read_b128 v[190:193], v174 offset:34816
	ds_read_b128 v[194:197], v174 offset:35840
	ds_read_b128 v[198:201], v174 offset:36864
	ds_read_b128 v[202:205], v174 offset:37888
	s_waitcnt vmcnt(8)
	s_waitcnt lgkmcnt(0)
	s_setprio 1
	s_waitcnt lgkmcnt(0)
	s_barrier
	v_mfma_f32_16x16x32_bf16 v[34:37], v[94:97], v[182:185], v[34:37]
	v_mfma_f32_16x16x32_bf16 v[30:33], v[138:141], v[182:185], v[30:33]
	v_mfma_f32_16x16x32_bf16 v[46:49], v[94:97], v[190:193], v[46:49]
	v_mfma_f32_16x16x32_bf16 v[62:65], v[138:141], v[190:193], v[62:65]
	v_mfma_f32_16x16x32_bf16 v[78:81], v[94:97], v[198:201], v[78:81]
	v_mfma_f32_16x16x32_bf16 v[90:93], v[138:141], v[198:201], v[90:93]
	v_mfma_f32_16x16x32_bf16 v[106:109], v[94:97], v[206:209], v[106:109]
	v_mfma_f32_16x16x32_bf16 v[114:117], v[138:141], v[206:209], v[114:117]
	v_mfma_f32_16x16x32_bf16 v[26:29], v[146:149], v[182:185], v[26:29]
	v_mfma_f32_16x16x32_bf16 v[50:53], v[154:157], v[182:185], v[50:53]
	v_mfma_f32_16x16x32_bf16 v[58:61], v[146:149], v[190:193], v[58:61]
	v_mfma_f32_16x16x32_bf16 v[82:85], v[154:157], v[190:193], v[82:85]
	v_mfma_f32_16x16x32_bf16 v[110:113], v[146:149], v[198:201], v[110:113]
	v_mfma_f32_16x16x32_bf16 v[118:121], v[154:157], v[198:201], v[118:121]
	v_mfma_f32_16x16x32_bf16 v[122:125], v[146:149], v[206:209], v[122:125]
	v_mfma_f32_16x16x32_bf16 v[126:129], v[154:157], v[206:209], v[126:129]
	v_mfma_f32_16x16x32_bf16 v[34:37], v[134:137], v[186:189], v[34:37]
	v_mfma_f32_16x16x32_bf16 v[30:33], v[142:145], v[186:189], v[30:33]
	v_mfma_f32_16x16x32_bf16 v[46:49], v[134:137], v[194:197], v[46:49]
	v_mfma_f32_16x16x32_bf16 v[62:65], v[142:145], v[194:197], v[62:65]
	v_mfma_f32_16x16x32_bf16 v[78:81], v[134:137], v[202:205], v[78:81]
	v_mfma_f32_16x16x32_bf16 v[90:93], v[142:145], v[202:205], v[90:93]
	v_mfma_f32_16x16x32_bf16 v[106:109], v[134:137], v[210:213], v[106:109]
	v_mfma_f32_16x16x32_bf16 v[114:117], v[142:145], v[210:213], v[114:117]
	v_mfma_f32_16x16x32_bf16 v[26:29], v[150:153], v[186:189], v[26:29]
	v_mfma_f32_16x16x32_bf16 v[50:53], v[178:181], v[186:189], v[50:53]
	v_mfma_f32_16x16x32_bf16 v[58:61], v[150:153], v[194:197], v[58:61]
	v_mfma_f32_16x16x32_bf16 v[82:85], v[178:181], v[194:197], v[82:85]
	v_mfma_f32_16x16x32_bf16 v[110:113], v[150:153], v[202:205], v[110:113]
	v_mfma_f32_16x16x32_bf16 v[118:121], v[178:181], v[202:205], v[118:121]
	v_mfma_f32_16x16x32_bf16 v[122:125], v[150:153], v[210:213], v[122:125]
	v_mfma_f32_16x16x32_bf16 v[126:129], v[178:181], v[210:213], v[126:129]
	s_setprio 0
	s_barrier
	s_add_u32 s26, s24, 0x80
	s_mov_b32 m0, s84
	s_addc_u32 s27, s25, 0
	s_add_u32 s24, s24, 0x100080
	global_load_lds_dwordx4 v164, s[26:27]
	s_mov_b32 m0, s85
	s_addc_u32 s25, s25, 0
	global_load_lds_dwordx4 v166, s[26:27]
	s_mov_b32 m0, s86
	ds_read_b128 v[198:201], v174 offset:53248
	global_load_lds_dwordx4 v164, s[24:25]
	s_mov_b32 m0, s87
	ds_read_b128 v[202:205], v174 offset:54272
	global_load_lds_dwordx4 v166, s[24:25]
	s_mov_b32 m0, s57
	ds_read_b128 v[206:209], v174 offset:55296
	global_load_lds_dwordx4 v1, s[16:17]
	s_mov_b32 m0, s62
	ds_read_b128 v[210:213], v174 offset:56320
	global_load_lds_dwordx4 v165, s[16:17]
	ds_read_b128 v[182:185], v174 offset:49152
	ds_read_b128 v[186:189], v174 offset:50176
	ds_read_b128 v[190:193], v174 offset:51200
	ds_read_b128 v[194:197], v174 offset:52224
	s_waitcnt vmcnt(8)
	s_waitcnt lgkmcnt(0)
	s_setprio 1
	s_waitcnt lgkmcnt(0)
	s_barrier
	v_mfma_f32_16x16x32_bf16 v[18:21], v[146:149], v[182:185], v[18:21]
	v_mfma_f32_16x16x32_bf16 v[102:105], v[94:97], v[182:185], v[102:105]
	v_mfma_f32_16x16x32_bf16 v[74:77], v[94:97], v[190:193], v[74:77]
	v_mfma_f32_16x16x32_bf16 v[42:45], v[94:97], v[198:201], v[42:45]
	v_mfma_f32_16x16x32_bf16 v[14:17], v[94:97], v[206:209], v[14:17]
	v_mfma_f32_16x16x32_bf16 v[94:97], v[150:153], v[186:189], v[18:21]
	v_mfma_f32_16x16x32_bf16 v[18:21], v[154:157], v[182:185], v[86:89]
	v_mfma_f32_16x16x32_bf16 v[86:89], v[178:181], v[186:189], v[18:21]
	v_mfma_f32_16x16x32_bf16 v[18:21], v[146:149], v[190:193], v[66:69]
	v_mfma_f32_16x16x32_bf16 v[66:69], v[150:153], v[194:197], v[18:21]
	v_mfma_f32_16x16x32_bf16 v[18:21], v[154:157], v[190:193], v[54:57]
	v_mfma_f32_16x16x32_bf16 v[54:57], v[178:181], v[194:197], v[18:21]
	v_mfma_f32_16x16x32_bf16 v[18:21], v[146:149], v[198:201], v[22:25]
	v_mfma_f32_16x16x32_bf16 v[98:101], v[138:141], v[182:185], v[98:101]
	v_mfma_f32_16x16x32_bf16 v[70:73], v[138:141], v[190:193], v[70:73]
	v_mfma_f32_16x16x32_bf16 v[38:41], v[138:141], v[198:201], v[38:41]
	v_mfma_f32_16x16x32_bf16 v[10:13], v[138:141], v[206:209], v[10:13]
	v_mfma_f32_16x16x32_bf16 v[22:25], v[150:153], v[202:205], v[18:21]
	v_mfma_f32_16x16x32_bf16 v[18:21], v[154:157], v[198:201], v[130:133]
	v_mfma_f32_16x16x32_bf16 v[6:9], v[146:149], v[206:209], v[6:9]
	v_mfma_f32_16x16x32_bf16 v[2:5], v[154:157], v[206:209], v[2:5]
	v_mfma_f32_16x16x32_bf16 v[102:105], v[134:137], v[186:189], v[102:105]
	v_mfma_f32_16x16x32_bf16 v[98:101], v[142:145], v[186:189], v[98:101]
	v_mfma_f32_16x16x32_bf16 v[74:77], v[134:137], v[194:197], v[74:77]
	v_mfma_f32_16x16x32_bf16 v[70:73], v[142:145], v[194:197], v[70:73]
	v_mfma_f32_16x16x32_bf16 v[42:45], v[134:137], v[202:205], v[42:45]
	v_mfma_f32_16x16x32_bf16 v[38:41], v[142:145], v[202:205], v[38:41]
	v_mfma_f32_16x16x32_bf16 v[14:17], v[134:137], v[210:213], v[14:17]
	v_mfma_f32_16x16x32_bf16 v[10:13], v[142:145], v[210:213], v[10:13]
	v_mfma_f32_16x16x32_bf16 v[130:133], v[178:181], v[202:205], v[18:21]
	v_mfma_f32_16x16x32_bf16 v[6:9], v[150:153], v[210:213], v[6:9]
	v_mfma_f32_16x16x32_bf16 v[2:5], v[178:181], v[210:213], v[2:5]
	s_setprio 0
	s_barrier
	s_add_i32 s37, s37, 2
	s_add_u32 s34, s34, 0x100
	s_addc_u32 s35, s35, 0
	s_cmp_gt_u32 s37, 61
	s_mov_b64 s[30:31], s[2:3]
	s_cbranch_scc0 .LBB0_754
	s_nop 0
	s_nop 0
	s_nop 0
	s_nop 0
	s_nop 0
	s_nop 0
	s_nop 0
	s_nop 0
	s_nop 0
	s_nop 0
	s_nop 0
	s_nop 0
	s_nop 0
	s_nop 0
	s_and_b64 vcc, exec, s[18:19]
	s_cbranch_vccz .LBB0_757
	s_barrier

; #define PG8_STAGE(bufoff, gbase, voff) do { const char* _gb = (const char*)(gbase); asm volatile("" : "+s"(_gb)); _Pragma("unroll") for (int _i = 0; _i < 2; ++_i) { asm volatile("" : "+v"((voff)[_i])); \
;         __builtin_amdgcn_global_load_lds((const unsigned*)(_gb + (voff)[_i]), (PG8_LAS unsigned*)(lds + (bufoff) + ldsw + _i * 8192), 16, 0, 0); } } while (0)
; #define PG8_LDA(dst, b, h) do { _Pragma("unroll") for (int m = 0; m < 4; ++m) _Pragma("unroll") for (int k = 0; k < 2; ++k) dst[m][k] = *(const PG8_LAS bf16x8*)(lds + PG8_SA(b, h) + aoff + m * 2048 + k * 1024); } while (0)
; #define PG8_LDB(dst, b, h) do { _Pragma("unroll") for (int n = 0; n < 2; ++n) _Pragma("unroll") for (int k = 0; k < 2; ++k) dst[n][k] = *(const PG8_LAS bf16x8*)(lds + PG8_SB(b, h) + boff + n * 2048 + k * 1024); } while (0)
; #define PG8_WAIT_V(n) asm volatile("s_waitcnt vmcnt(" #n ")" ::: "memory")
; #define PG8_WAIT_L(n) asm volatile("s_waitcnt lgkmcnt(" #n ")" ::: "memory")
; #define PG8_BAR __builtin_amdgcn_s_barrier()
; #define PG8_SCHED __builtin_amdgcn_sched_barrier(0)
; #define PG8_LDA(dst, b, h) do { _Pragma("unroll") for (int m = 0; m < 4; ++m) _Pragma("unroll") for (int k = 0; k < 2; ++k) dst[m][k] = *(const PG8_LAS bf16x8*)(lds + PG8_SA(b, h) + aoff + m * 2048 + k * 1024); } while (0)
; #define PG8_BAR __builtin_amdgcn_s_barrier()
; template <class Epi, class Sched, bool ALIGN_EPI = false, bool SP2 = false>
; __device__ __forceinline__ void gemm_phase(PG8_LAS unsigned char* lds, const Gemm g, const Sched& S, const Epi& E) {
;     ...
;             const bool last = (t == nt - 2);
;             const char* a1 = cA + (size_t)(t + 1) * kstep;
;             const char* a2 = last ? nA : cA + (size_t)(t + 2) * kstep; const char* b2 = last ? nB : cB + (size_t)(t + 2) * kstep;
;             const char* a3 = a2 + kstep; const char* b3 = b2 + kstep;
;             if (last && has_next) S.a_ready(nxt);
;             if constexpr (SP2) {
;             PG8_LDB(B0, 0, 0); PG8_LDB(B1, 0, 1); PG8_SCHED; PG8_LDA(At, 0, 0); PG8_STAGE(PG8_SA(1, 1), a1 + hstep, voffA);
;             PG8_WAIT_V(8); PG8_WAIT_L(0); PG8_BAR; PG8_MMA2(0); PG8_BAR; PG8_SCHED;
;             PG8_LDA(At, 0, 1); PG8_STAGE(PG8_SB(0, 0), b2, voffB); PG8_STAGE(PG8_SB(0, 1), b2 + hstep, voffB); PG8_STAGE(PG8_SA(0, 0), a2, voffA);
;             PG8_WAIT_V(8); PG8_WAIT_L(0); PG8_BAR; PG8_MMA2(1); PG8_BAR; PG8_SCHED;
.LBB0_833:
	s_add_u32 s24, s16, 0x100
	s_addc_u32 s25, s17, 0
	s_cmp_eq_u32 s87, 60
	s_cselect_b32 s28, s83, s24
	s_cselect_b32 s29, s55, s25
	s_cselect_b32 s26, s84, s85
	s_cselect_b32 s27, s53, s86
	s_add_u32 s2, s28, 0x80
	s_addc_u32 s3, s29, 0
	s_add_u32 s16, s16, 0x100080
	s_addc_u32 s17, s17, 0
	s_add_i32 m0, s69, 0xc000
	ds_read_b128 v[200:203], v182 offset:6144
	global_load_lds_dwordx4 v1, s[16:17]
	s_add_i32 m0, s69, 0xe000
	ds_read_b128 v[204:207], v182 offset:7168
	global_load_lds_dwordx4 v175, s[16:17]
	ds_read_b128 v[130:133], v180
	ds_read_b128 v[134:137], v180 offset:1024
	ds_read_b128 v[138:141], v180 offset:2048
	ds_read_b128 v[142:145], v180 offset:3072
	ds_read_b128 v[146:149], v181
	ds_read_b128 v[150:153], v181 offset:1024
	ds_read_b128 v[154:157], v181 offset:2048
	ds_read_b128 v[158:161], v181 offset:3072
	ds_read_b128 v[166:169], v182
	ds_read_b128 v[170:173], v182 offset:1024
	ds_read_b128 v[184:187], v182 offset:2048
	ds_read_b128 v[188:191], v182 offset:3072
	ds_read_b128 v[192:195], v182 offset:4096
	ds_read_b128 v[196:199], v182 offset:5120
	s_waitcnt vmcnt(8)
	s_waitcnt lgkmcnt(0)
	s_setprio 1
	s_waitcnt lgkmcnt(0)
	s_barrier
	v_mfma_f32_16x16x32_bf16 v[126:129], v[130:133], v[166:169], v[126:129]
	v_mfma_f32_16x16x32_bf16 v[122:125], v[138:141], v[166:169], v[122:125]
	v_mfma_f32_16x16x32_bf16 v[110:113], v[130:133], v[184:187], v[110:113]
	v_mfma_f32_16x16x32_bf16 v[106:109], v[138:141], v[184:187], v[106:109]
	v_mfma_f32_16x16x32_bf16 v[94:97], v[130:133], v[192:195], v[94:97]
	v_mfma_f32_16x16x32_bf16 v[90:93], v[138:141], v[192:195], v[90:93]
	v_mfma_f32_16x16x32_bf16 v[78:81], v[130:133], v[200:203], v[78:81]
	v_mfma_f32_16x16x32_bf16 v[74:77], v[138:141], v[200:203], v[74:77]
	v_mfma_f32_16x16x32_bf16 v[118:121], v[146:149], v[166:169], v[118:121]
	v_mfma_f32_16x16x32_bf16 v[114:117], v[154:157], v[166:169], v[114:117]
	v_mfma_f32_16x16x32_bf16 v[102:105], v[146:149], v[184:187], v[102:105]
	v_mfma_f32_16x16x32_bf16 v[98:101], v[154:157], v[184:187], v[98:101]
	v_mfma_f32_16x16x32_bf16 v[86:89], v[146:149], v[192:195], v[86:89]
	v_mfma_f32_16x16x32_bf16 v[82:85], v[154:157], v[192:195], v[82:85]
	v_mfma_f32_16x16x32_bf16 v[70:73], v[146:149], v[200:203], v[70:73]
	v_mfma_f32_16x16x32_bf16 v[66:69], v[154:157], v[200:203], v[66:69]
	v_mfma_f32_16x16x32_bf16 v[126:129], v[134:137], v[170:173], v[126:129]
	v_mfma_f32_16x16x32_bf16 v[122:125], v[142:145], v[170:173], v[122:125]
	v_mfma_f32_16x16x32_bf16 v[110:113], v[134:137], v[188:191], v[110:113]
	v_mfma_f32_16x16x32_bf16 v[106:109], v[142:145], v[188:191], v[106:109]
	v_mfma_f32_16x16x32_bf16 v[94:97], v[134:137], v[196:199], v[94:97]
	v_mfma_f32_16x16x32_bf16 v[90:93], v[142:145], v[196:199], v[90:93]
	v_mfma_f32_16x16x32_bf16 v[78:81], v[134:137], v[204:207], v[78:81]
	v_mfma_f32_16x16x32_bf16 v[74:77], v[142:145], v[204:207], v[74:77]
	v_mfma_f32_16x16x32_bf16 v[118:121], v[150:153], v[170:173], v[118:121]
	v_mfma_f32_16x16x32_bf16 v[114:117], v[158:161], v[170:173], v[114:117]
	v_mfma_f32_16x16x32_bf16 v[102:105], v[150:153], v[188:191], v[102:105]
	v_mfma_f32_16x16x32_bf16 v[98:101], v[158:161], v[188:191], v[98:101]
	v_mfma_f32_16x16x32_bf16 v[86:89], v[150:153], v[196:199], v[86:89]
	v_mfma_f32_16x16x32_bf16 v[82:85], v[158:161], v[196:199], v[82:85]
	v_mfma_f32_16x16x32_bf16 v[70:73], v[150:153], v[204:207], v[70:73]
	v_mfma_f32_16x16x32_bf16 v[66:69], v[158:161], v[204:207], v[66:69]
	s_setprio 0
	s_barrier
	s_add_i32 s88, s81, s73
	s_mov_b64 s[16:17], s[26:27]
	s_mov_b32 m0, s88
	ds_read_b128 v[184:187], v182 offset:18432
	global_load_lds_dwordx4 v174, s[16:17]
	s_add_i32 m0, s88, 0x2000
	ds_read_b128 v[188:191], v182 offset:19456
	global_load_lds_dwordx4 v176, s[16:17]
	s_add_u32 s16, s26, 0x100000
	s_addc_u32 s17, s27, 0
	s_add_i32 s88, s82, s73
	s_mov_b32 m0, s88
	ds_read_b128 v[192:195], v182 offset:20480
	global_load_lds_dwordx4 v174, s[16:17]
	s_add_i32 m0, s88, 0x2000
	ds_read_b128 v[196:199], v182 offset:21504
	global_load_lds_dwordx4 v176, s[16:17]
	s_mov_b64 s[16:17], s[28:29]
	s_mov_b32 m0, s69
	ds_read_b128 v[200:203], v182 offset:22528
	global_load_lds_dwordx4 v1, s[16:17]
	s_mov_b32 m0, s71
	ds_read_b128 v[204:207], v182 offset:23552
	global_load_lds_dwordx4 v175, s[16:17]
	ds_read_b128 v[166:169], v182 offset:16384
	ds_read_b128 v[170:173], v182 offset:17408
	s_waitcnt vmcnt(8)
	s_waitcnt lgkmcnt(0)
	s_setprio 1
	s_waitcnt lgkmcnt(0)
	s_barrier
	v_mfma_f32_16x16x32_bf16 v[62:65], v[130:133], v[166:169], v[62:65]
	v_mfma_f32_16x16x32_bf16 v[58:61], v[138:141], v[166:169], v[58:61]
	v_mfma_f32_16x16x32_bf16 v[46:49], v[130:133], v[184:187], v[46:49]
	v_mfma_f32_16x16x32_bf16 v[42:45], v[138:141], v[184:187], v[42:45]
	v_mfma_f32_16x16x32_bf16 v[30:33], v[130:133], v[192:195], v[30:33]
	v_mfma_f32_16x16x32_bf16 v[26:29], v[138:141], v[192:195], v[26:29]
	v_mfma_f32_16x16x32_bf16 v[14:17], v[130:133], v[200:203], v[14:17]
	v_mfma_f32_16x16x32_bf16 v[10:13], v[138:141], v[200:203], v[10:13]
	v_mfma_f32_16x16x32_bf16 v[54:57], v[146:149], v[166:169], v[54:57]
	v_mfma_f32_16x16x32_bf16 v[50:53], v[154:157], v[166:169], v[50:53]
	v_mfma_f32_16x16x32_bf16 v[38:41], v[146:149], v[184:187], v[38:41]
	v_mfma_f32_16x16x32_bf16 v[34:37], v[154:157], v[184:187], v[34:37]
	v_mfma_f32_16x16x32_bf16 v[22:25], v[146:149], v[192:195], v[22:25]
	v_mfma_f32_16x16x32_bf16 v[18:21], v[154:157], v[192:195], v[18:21]
	v_mfma_f32_16x16x32_bf16 v[6:9], v[146:149], v[200:203], v[6:9]
	v_mfma_f32_16x16x32_bf16 v[2:5], v[154:157], v[200:203], v[2:5]
	v_mfma_f32_16x16x32_bf16 v[62:65], v[134:137], v[170:173], v[62:65]
	v_mfma_f32_16x16x32_bf16 v[58:61], v[142:145], v[170:173], v[58:61]
	v_mfma_f32_16x16x32_bf16 v[46:49], v[134:137], v[188:191], v[46:49]
	v_mfma_f32_16x16x32_bf16 v[42:45], v[142:145], v[188:191], v[42:45]
	v_mfma_f32_16x16x32_bf16 v[30:33], v[134:137], v[196:199], v[30:33]
	v_mfma_f32_16x16x32_bf16 v[26:29], v[142:145], v[196:199], v[26:29]
	v_mfma_f32_16x16x32_bf16 v[14:17], v[134:137], v[204:207], v[14:17]
	v_mfma_f32_16x16x32_bf16 v[10:13], v[142:145], v[204:207], v[10:13]
	v_mfma_f32_16x16x32_bf16 v[54:57], v[150:153], v[170:173], v[54:57]
	v_mfma_f32_16x16x32_bf16 v[50:53], v[158:161], v[170:173], v[50:53]
	v_mfma_f32_16x16x32_bf16 v[38:41], v[150:153], v[188:191], v[38:41]
	v_mfma_f32_16x16x32_bf16 v[34:37], v[158:161], v[188:191], v[34:37]
	v_mfma_f32_16x16x32_bf16 v[22:25], v[150:153], v[196:199], v[22:25]
	v_mfma_f32_16x16x32_bf16 v[18:21], v[158:161], v[196:199], v[18:21]
	v_mfma_f32_16x16x32_bf16 v[6:9], v[150:153], v[204:207], v[6:9]
	v_mfma_f32_16x16x32_bf16 v[2:5], v[158:161], v[204:207], v[2:5]
	s_setprio 0
	s_barrier
; #define PG8_STAGE(bufoff, gbase, voff) do { const char* _gb = (const char*)(gbase); asm volatile("" : "+s"(_gb)); _Pragma("unroll") for (int _i = 0; _i < 2; ++_i) { asm volatile("" : "+v"((voff)[_i])); \
;         __builtin_amdgcn_global_load_lds((const unsigned*)(_gb + (voff)[_i]), (PG8_LAS unsigned*)(lds + (bufoff) + ldsw + _i * 8192), 16, 0, 0); } } while (0)
; #define PG8_LDA(dst, b, h) do { _Pragma("unroll") for (int m = 0; m < 4; ++m) _Pragma("unroll") for (int k = 0; k < 2; ++k) dst[m][k] = *(const PG8_LAS bf16x8*)(lds + PG8_SA(b, h) + aoff + m * 2048 + k * 1024); } while (0)
; #define PG8_LDB(dst, b, h) do { _Pragma("unroll") for (int n = 0; n < 2; ++n) _Pragma("unroll") for (int k = 0; k < 2; ++k) dst[n][k] = *(const PG8_LAS bf16x8*)(lds + PG8_SB(b, h) + boff + n * 2048 + k * 1024); } while (0)
; #define PG8_WAIT_V(n) asm volatile("s_waitcnt vmcnt(" #n ")" ::: "memory")
; #define PG8_WAIT_L(n) asm volatile("s_waitcnt lgkmcnt(" #n ")" ::: "memory")
; #define PG8_BAR __builtin_amdgcn_s_barrier()
; #define PG8_SCHED __builtin_amdgcn_sched_barrier(0)
; #define PG8_STAGE(bufoff, gbase, voff) do { const char* _gb = (const char*)(gbase); asm volatile("" : "+s"(_gb)); _Pragma("unroll") for (int _i = 0; _i < 2; ++_i) { asm volatile("" : "+v"((voff)[_i])); \
;         __builtin_amdgcn_global_load_lds((const unsigned*)(_gb + (voff)[_i]), (PG8_LAS unsigned*)(lds + (bufoff) + ldsw + _i * 8192), 16, 0, 0); } } while (0)
; #define PG8_LDA(dst, b, h) do { _Pragma("unroll") for (int m = 0; m < 4; ++m) _Pragma("unroll") for (int k = 0; k < 2; ++k) dst[m][k] = *(const PG8_LAS bf16x8*)(lds + PG8_SA(b, h) + aoff + m * 2048 + k * 1024); } while (0)
; #define PG8_WAIT_V(n) asm volatile("s_waitcnt vmcnt(" #n ")" ::: "memory")
; template <class Epi, class Sched, bool ALIGN_EPI = false, bool SP2 = false>
; __device__ __forceinline__ void gemm_phase(PG8_LAS unsigned char* lds, const Gemm g, const Sched& S, const Epi& E) {
;     ...
;             PG8_LDB(B0, 1, 0); PG8_LDB(B1, 1, 1); PG8_SCHED; PG8_LDA(At, 1, 0); PG8_STAGE(PG8_SA(0, 1), a2 + hstep, voffA);
;             PG8_WAIT_V(8); PG8_WAIT_L(0); PG8_BAR; PG8_MMA2(0); PG8_BAR; PG8_SCHED;
;             PG8_LDA(At, 1, 1); PG8_STAGE(PG8_SB(1, 0), b3, voffB); PG8_STAGE(PG8_SB(1, 1), b3 + hstep, voffB); PG8_STAGE(PG8_SA(1, 0), a3, voffA);
;             PG8_WAIT_V(8); PG8_WAIT_L(0); PG8_BAR; PG8_MMA2(1); PG8_BAR; PG8_SCHED;
	s_add_i32 s88, 0, 0x18000
	s_add_i32 s89, 0, 0x1c000
	s_add_u32 s16, s28, 0x100000
	s_addc_u32 s17, s29, 0
	s_mov_b32 m0, s74
	ds_read_b128 v[200:203], v182 offset:38912
	global_load_lds_dwordx4 v1, s[16:17]
	s_mov_b32 m0, s75
	ds_read_b128 v[204:207], v182 offset:39936
	global_load_lds_dwordx4 v175, s[16:17]
	v_add_u32_e32 v142, s88, v178
	v_add_u32_e32 v158, s89, v178
	ds_read_b128 v[130:133], v142
	ds_read_b128 v[134:137], v142 offset:1024
	ds_read_b128 v[138:141], v142 offset:2048
	ds_read_b128 v[142:145], v142 offset:3072
	ds_read_b128 v[146:149], v158
	ds_read_b128 v[150:153], v158 offset:1024
	ds_read_b128 v[154:157], v158 offset:2048
	ds_read_b128 v[158:161], v158 offset:3072
	ds_read_b128 v[166:169], v182 offset:32768
	ds_read_b128 v[170:173], v182 offset:33792
	ds_read_b128 v[184:187], v182 offset:34816
	ds_read_b128 v[188:191], v182 offset:35840
	ds_read_b128 v[192:195], v182 offset:36864
	ds_read_b128 v[196:199], v182 offset:37888
	s_waitcnt vmcnt(8)
	s_waitcnt lgkmcnt(0)
	s_setprio 1
	s_waitcnt lgkmcnt(0)
	s_barrier
	v_mfma_f32_16x16x32_bf16 v[126:129], v[130:133], v[166:169], v[126:129]
	v_mfma_f32_16x16x32_bf16 v[122:125], v[138:141], v[166:169], v[122:125]
	v_mfma_f32_16x16x32_bf16 v[110:113], v[130:133], v[184:187], v[110:113]
	v_mfma_f32_16x16x32_bf16 v[106:109], v[138:141], v[184:187], v[106:109]
	v_mfma_f32_16x16x32_bf16 v[94:97], v[130:133], v[192:195], v[94:97]
	v_mfma_f32_16x16x32_bf16 v[90:93], v[138:141], v[192:195], v[90:93]
	v_mfma_f32_16x16x32_bf16 v[78:81], v[130:133], v[200:203], v[78:81]
	v_mfma_f32_16x16x32_bf16 v[74:77], v[138:141], v[200:203], v[74:77]
	v_mfma_f32_16x16x32_bf16 v[118:121], v[146:149], v[166:169], v[118:121]
	v_mfma_f32_16x16x32_bf16 v[114:117], v[154:157], v[166:169], v[114:117]
	v_mfma_f32_16x16x32_bf16 v[102:105], v[146:149], v[184:187], v[102:105]
	v_mfma_f32_16x16x32_bf16 v[98:101], v[154:157], v[184:187], v[98:101]
	v_mfma_f32_16x16x32_bf16 v[86:89], v[146:149], v[192:195], v[86:89]
	v_mfma_f32_16x16x32_bf16 v[82:85], v[154:157], v[192:195], v[82:85]
	v_mfma_f32_16x16x32_bf16 v[70:73], v[146:149], v[200:203], v[70:73]
	v_mfma_f32_16x16x32_bf16 v[66:69], v[154:157], v[200:203], v[66:69]
	v_mfma_f32_16x16x32_bf16 v[126:129], v[134:137], v[170:173], v[126:129]
	v_mfma_f32_16x16x32_bf16 v[122:125], v[142:145], v[170:173], v[122:125]
	v_mfma_f32_16x16x32_bf16 v[110:113], v[134:137], v[188:191], v[110:113]
	v_mfma_f32_16x16x32_bf16 v[106:109], v[142:145], v[188:191], v[106:109]
	v_mfma_f32_16x16x32_bf16 v[94:97], v[134:137], v[196:199], v[94:97]
	v_mfma_f32_16x16x32_bf16 v[90:93], v[142:145], v[196:199], v[90:93]
	v_mfma_f32_16x16x32_bf16 v[78:81], v[134:137], v[204:207], v[78:81]
	v_mfma_f32_16x16x32_bf16 v[74:77], v[142:145], v[204:207], v[74:77]
	v_mfma_f32_16x16x32_bf16 v[118:121], v[150:153], v[170:173], v[118:121]
	v_mfma_f32_16x16x32_bf16 v[114:117], v[158:161], v[170:173], v[114:117]
	v_mfma_f32_16x16x32_bf16 v[102:105], v[150:153], v[188:191], v[102:105]
	v_mfma_f32_16x16x32_bf16 v[98:101], v[158:161], v[188:191], v[98:101]
	v_mfma_f32_16x16x32_bf16 v[86:89], v[150:153], v[196:199], v[86:89]
	v_mfma_f32_16x16x32_bf16 v[82:85], v[158:161], v[196:199], v[82:85]
	v_mfma_f32_16x16x32_bf16 v[70:73], v[150:153], v[204:207], v[70:73]
	v_mfma_f32_16x16x32_bf16 v[66:69], v[158:161], v[204:207], v[66:69]
	s_setprio 0
	s_barrier
	s_add_u32 s16, s26, 0x80
	s_addc_u32 s17, s27, 0
	s_add_i32 s28, s88, s73
	s_mov_b32 m0, s28
	ds_read_b128 v[184:187], v182 offset:51200
	global_load_lds_dwordx4 v174, s[16:17]
	s_add_i32 m0, s28, 0x2000
	ds_read_b128 v[188:191], v182 offset:52224
	global_load_lds_dwordx4 v176, s[16:17]
	s_add_u32 s16, s26, 0x100080
	s_addc_u32 s17, s27, 0
	s_add_i32 s26, s89, s73
	s_mov_b32 m0, s26
	ds_read_b128 v[192:195], v182 offset:53248
	global_load_lds_dwordx4 v174, s[16:17]
	s_add_i32 m0, s26, 0x2000
	ds_read_b128 v[196:199], v182 offset:54272
	global_load_lds_dwordx4 v176, s[16:17]
	s_mov_b32 m0, s77
	ds_read_b128 v[200:203], v182 offset:55296
	global_load_lds_dwordx4 v1, s[2:3]
	s_mov_b32 m0, s78
	ds_read_b128 v[204:207], v182 offset:56320
	global_load_lds_dwordx4 v175, s[2:3]
	ds_read_b128 v[166:169], v182 offset:49152
	ds_read_b128 v[170:173], v182 offset:50176
	s_waitcnt vmcnt(8)
	s_waitcnt lgkmcnt(0)
	s_setprio 1
	s_waitcnt lgkmcnt(0)
	s_barrier
	v_mfma_f32_16x16x32_bf16 v[62:65], v[130:133], v[166:169], v[62:65]
	v_mfma_f32_16x16x32_bf16 v[58:61], v[138:141], v[166:169], v[58:61]
	v_mfma_f32_16x16x32_bf16 v[46:49], v[130:133], v[184:187], v[46:49]
	v_mfma_f32_16x16x32_bf16 v[42:45], v[138:141], v[184:187], v[42:45]
	v_mfma_f32_16x16x32_bf16 v[30:33], v[130:133], v[192:195], v[30:33]
	v_mfma_f32_16x16x32_bf16 v[26:29], v[138:141], v[192:195], v[26:29]
	v_mfma_f32_16x16x32_bf16 v[14:17], v[130:133], v[200:203], v[14:17]
	v_mfma_f32_16x16x32_bf16 v[10:13], v[138:141], v[200:203], v[10:13]
	v_mfma_f32_16x16x32_bf16 v[54:57], v[146:149], v[166:169], v[54:57]
	v_mfma_f32_16x16x32_bf16 v[50:53], v[154:157], v[166:169], v[50:53]
	v_mfma_f32_16x16x32_bf16 v[38:41], v[146:149], v[184:187], v[38:41]
	v_mfma_f32_16x16x32_bf16 v[34:37], v[154:157], v[184:187], v[34:37]
	v_mfma_f32_16x16x32_bf16 v[22:25], v[146:149], v[192:195], v[22:25]
	v_mfma_f32_16x16x32_bf16 v[18:21], v[154:157], v[192:195], v[18:21]
	v_mfma_f32_16x16x32_bf16 v[6:9], v[146:149], v[200:203], v[6:9]
	v_mfma_f32_16x16x32_bf16 v[2:5], v[154:157], v[200:203], v[2:5]
	v_mfma_f32_16x16x32_bf16 v[62:65], v[134:137], v[170:173], v[62:65]
	v_mfma_f32_16x16x32_bf16 v[58:61], v[142:145], v[170:173], v[58:61]
	v_mfma_f32_16x16x32_bf16 v[46:49], v[134:137], v[188:191], v[46:49]
	v_mfma_f32_16x16x32_bf16 v[42:45], v[142:145], v[188:191], v[42:45]
	v_mfma_f32_16x16x32_bf16 v[30:33], v[134:137], v[196:199], v[30:33]
	v_mfma_f32_16x16x32_bf16 v[26:29], v[142:145], v[196:199], v[26:29]
	v_mfma_f32_16x16x32_bf16 v[14:17], v[134:137], v[204:207], v[14:17]
	v_mfma_f32_16x16x32_bf16 v[10:13], v[142:145], v[204:207], v[10:13]
	v_mfma_f32_16x16x32_bf16 v[54:57], v[150:153], v[170:173], v[54:57]
	v_mfma_f32_16x16x32_bf16 v[50:53], v[158:161], v[170:173], v[50:53]
	v_mfma_f32_16x16x32_bf16 v[38:41], v[150:153], v[188:191], v[38:41]
	v_mfma_f32_16x16x32_bf16 v[34:37], v[158:161], v[188:191], v[34:37]
	v_mfma_f32_16x16x32_bf16 v[22:25], v[150:153], v[196:199], v[22:25]
	v_mfma_f32_16x16x32_bf16 v[18:21], v[158:161], v[196:199], v[18:21]
	v_mfma_f32_16x16x32_bf16 v[6:9], v[150:153], v[204:207], v[6:9]
	v_mfma_f32_16x16x32_bf16 v[2:5], v[158:161], v[204:207], v[2:5]
	s_setprio 0
	s_barrier
	s_add_i32 s87, s87, 2
	s_add_u32 s85, s85, 0x100
	s_addc_u32 s86, s86, 0
	s_cmp_gt_u32 s87, 61
	s_mov_b64 s[16:17], s[24:25]
	s_cbranch_scc0 .LBB0_833
	s_and_b64 vcc, exec, s[12:13]
	s_cbranch_vccz .LBB0_836
	s_barrier

; #define PG8_STAGE(bufoff, gbase, voff) do { const char* _gb = (const char*)(gbase); asm volatile("" : "+s"(_gb)); _Pragma("unroll") for (int _i = 0; _i < 2; ++_i) { asm volatile("" : "+v"((voff)[_i])); \
;         __builtin_amdgcn_global_load_lds((const unsigned*)(_gb + (voff)[_i]), (PG8_LAS unsigned*)(lds + (bufoff) + ldsw + _i * 8192), 16, 0, 0); } } while (0)
; #define PG8_LDA(dst, b, h) do { _Pragma("unroll") for (int m = 0; m < 4; ++m) _Pragma("unroll") for (int k = 0; k < 2; ++k) dst[m][k] = *(const PG8_LAS bf16x8*)(lds + PG8_SA(b, h) + aoff + m * 2048 + k * 1024); } while (0)
; #define PG8_LDB(dst, b, h) do { _Pragma("unroll") for (int n = 0; n < 2; ++n) _Pragma("unroll") for (int k = 0; k < 2; ++k) dst[n][k] = *(const PG8_LAS bf16x8*)(lds + PG8_SB(b, h) + boff + n * 2048 + k * 1024); } while (0)
; #define PG8_WAIT_V(n) asm volatile("s_waitcnt vmcnt(" #n ")" ::: "memory")
; #define PG8_WAIT_L(n) asm volatile("s_waitcnt lgkmcnt(" #n ")" ::: "memory")
; #define PG8_BAR __builtin_amdgcn_s_barrier()
; #define PG8_SCHED __builtin_amdgcn_sched_barrier(0)
; #define PG8_LDA(dst, b, h) do { _Pragma("unroll") for (int m = 0; m < 4; ++m) _Pragma("unroll") for (int k = 0; k < 2; ++k) dst[m][k] = *(const PG8_LAS bf16x8*)(lds + PG8_SA(b, h) + aoff + m * 2048 + k * 1024); } while (0)
; #define PG8_BAR __builtin_amdgcn_s_barrier()
; template <class Epi, class Sched, bool ALIGN_EPI = false, bool SP2 = false>
; __device__ __forceinline__ void gemm_phase(PG8_LAS unsigned char* lds, const Gemm g, const Sched& S, const Epi& E) {
;     ...
;             const bool last = (t == nt - 2);
;             const char* a1 = cA + (size_t)(t + 1) * kstep;
;             const char* a2 = last ? nA : cA + (size_t)(t + 2) * kstep; const char* b2 = last ? nB : cB + (size_t)(t + 2) * kstep;
;             const char* a3 = a2 + kstep; const char* b3 = b2 + kstep;
;             if (last && has_next) S.a_ready(nxt);
;             if constexpr (SP2) {
;             PG8_LDB(B0, 0, 0); PG8_LDB(B1, 0, 1); PG8_SCHED; PG8_LDA(At, 0, 0); PG8_STAGE(PG8_SA(1, 1), a1 + hstep, voffA);
;             PG8_WAIT_V(8); PG8_WAIT_L(0); PG8_BAR; PG8_MMA2(0); PG8_BAR; PG8_SCHED;
;             PG8_LDA(At, 0, 1); PG8_STAGE(PG8_SB(0, 0), b2, voffB); PG8_STAGE(PG8_SB(0, 1), b2 + hstep, voffB); PG8_STAGE(PG8_SA(0, 0), a2, voffA);
;             PG8_WAIT_V(8); PG8_WAIT_L(0); PG8_BAR; PG8_MMA2(1); PG8_BAR; PG8_SCHED;
.LBB0_933:
	s_add_u32 s14, s12, 0x100
	s_addc_u32 s15, s13, 0
	s_cmp_eq_u32 s83, 60
	s_cselect_b32 s18, s21, s14
	s_cselect_b32 s19, s20, s15
	s_cselect_b32 s16, s51, s62
	s_cselect_b32 s17, s49, s63
	s_add_u32 s2, s18, 0x80
	s_addc_u32 s3, s19, 0
	s_add_u32 s12, s12, 0x100080
	s_addc_u32 s13, s13, 0
	s_add_i32 m0, s33, 0xc000
	ds_read_b128 v[230:233], v219 offset:6144
	global_load_lds_dwordx4 v1, s[12:13]
	s_add_i32 m0, s33, 0xe000
	ds_read_b128 v[234:237], v219 offset:7168
	global_load_lds_dwordx4 v199, s[12:13]
	v_add_u32_e32 v142, s78, v201
	v_add_u32_e32 v147, s79, v201
	ds_read_b128 v[6:9], v142
	ds_read_b128 v[62:65], v142 offset:1024
	ds_read_b128 v[138:141], v142 offset:2048
	ds_read_b128 v[142:145], v142 offset:3072
	ds_read_b128 v[164:167], v147
	ds_read_b128 v[168:171], v147 offset:1024
	ds_read_b128 v[172:175], v147 offset:2048
	ds_read_b128 v[176:179], v147 offset:3072
	ds_read_b128 v[180:183], v219
	ds_read_b128 v[184:187], v219 offset:1024
	ds_read_b128 v[188:191], v219 offset:2048
	ds_read_b128 v[192:195], v219 offset:3072
	ds_read_b128 v[222:225], v219 offset:4096
	ds_read_b128 v[226:229], v219 offset:5120
	s_waitcnt vmcnt(8)
	s_waitcnt lgkmcnt(0)
	s_setprio 1
	s_waitcnt lgkmcnt(0)
	s_barrier
	v_mfma_f32_16x16x32_bf16 v[118:121], v[6:9], v[180:183], v[118:121]
	v_mfma_f32_16x16x32_bf16 v[114:117], v[138:141], v[180:183], v[114:117]
	v_mfma_f32_16x16x32_bf16 v[106:109], v[6:9], v[188:191], v[106:109]
	v_mfma_f32_16x16x32_bf16 v[86:89], v[138:141], v[188:191], v[86:89]
	v_mfma_f32_16x16x32_bf16 v[134:137], v[6:9], v[222:225], v[134:137]
	v_mfma_f32_16x16x32_bf16 v[90:93], v[138:141], v[222:225], v[90:93]
	v_mfma_f32_16x16x32_bf16 v[130:133], v[6:9], v[230:233], v[130:133]
	v_mfma_f32_16x16x32_bf16 v[110:113], v[138:141], v[230:233], v[110:113]
	v_mfma_f32_16x16x32_bf16 v[94:97], v[164:167], v[180:183], v[94:97]
	v_mfma_f32_16x16x32_bf16 v[82:85], v[172:175], v[180:183], v[82:85]
	v_mfma_f32_16x16x32_bf16 v[78:81], v[164:167], v[188:191], v[78:81]
	v_mfma_f32_16x16x32_bf16 v[74:77], v[172:175], v[188:191], v[74:77]
	v_mfma_f32_16x16x32_bf16 v[126:129], v[164:167], v[222:225], v[126:129]
	v_mfma_f32_16x16x32_bf16 v[98:101], v[172:175], v[222:225], v[98:101]
	v_mfma_f32_16x16x32_bf16 v[122:125], v[164:167], v[230:233], v[122:125]
	v_mfma_f32_16x16x32_bf16 v[102:105], v[172:175], v[230:233], v[102:105]
	v_mfma_f32_16x16x32_bf16 v[118:121], v[62:65], v[184:187], v[118:121]
	v_mfma_f32_16x16x32_bf16 v[114:117], v[142:145], v[184:187], v[114:117]
	v_mfma_f32_16x16x32_bf16 v[106:109], v[62:65], v[192:195], v[106:109]
	v_mfma_f32_16x16x32_bf16 v[86:89], v[142:145], v[192:195], v[86:89]
	v_mfma_f32_16x16x32_bf16 v[134:137], v[62:65], v[226:229], v[134:137]
	v_mfma_f32_16x16x32_bf16 v[90:93], v[142:145], v[226:229], v[90:93]
	v_mfma_f32_16x16x32_bf16 v[130:133], v[62:65], v[234:237], v[130:133]
	v_mfma_f32_16x16x32_bf16 v[110:113], v[142:145], v[234:237], v[110:113]
	v_mfma_f32_16x16x32_bf16 v[94:97], v[168:171], v[184:187], v[94:97]
	v_mfma_f32_16x16x32_bf16 v[82:85], v[176:179], v[184:187], v[82:85]
	v_mfma_f32_16x16x32_bf16 v[78:81], v[168:171], v[192:195], v[78:81]
	v_mfma_f32_16x16x32_bf16 v[74:77], v[176:179], v[192:195], v[74:77]
	v_mfma_f32_16x16x32_bf16 v[126:129], v[168:171], v[226:229], v[126:129]
	v_mfma_f32_16x16x32_bf16 v[98:101], v[176:179], v[226:229], v[98:101]
	v_mfma_f32_16x16x32_bf16 v[122:125], v[168:171], v[234:237], v[122:125]
	v_mfma_f32_16x16x32_bf16 v[102:105], v[176:179], v[234:237], v[102:105]
	s_setprio 0
	s_barrier
	s_add_i32 s84, s78, s25
	s_mov_b64 s[12:13], s[16:17]
	s_mov_b32 m0, s84
	ds_read_b128 v[188:191], v219 offset:18432
	global_load_lds_dwordx4 v198, s[12:13]
	s_add_i32 m0, s84, 0x2000
	ds_read_b128 v[192:195], v219 offset:19456
	global_load_lds_dwordx4 v200, s[12:13]
	s_add_u32 s12, s16, 0x100000
	s_addc_u32 s13, s17, 0
	s_add_i32 s84, s79, s25
	s_mov_b32 m0, s84
	ds_read_b128 v[222:225], v219 offset:20480
	global_load_lds_dwordx4 v198, s[12:13]
	s_add_i32 m0, s84, 0x2000
	ds_read_b128 v[226:229], v219 offset:21504
	global_load_lds_dwordx4 v200, s[12:13]
	s_mov_b64 s[12:13], s[18:19]
	s_mov_b32 m0, s33
	ds_read_b128 v[230:233], v219 offset:22528
	global_load_lds_dwordx4 v1, s[12:13]
	s_mov_b32 m0, s45
	ds_read_b128 v[234:237], v219 offset:23552
	global_load_lds_dwordx4 v199, s[12:13]
	ds_read_b128 v[180:183], v219 offset:16384
	ds_read_b128 v[184:187], v219 offset:17408
	s_waitcnt vmcnt(8)
	s_waitcnt lgkmcnt(0)
	s_setprio 1
	s_waitcnt lgkmcnt(0)
	s_barrier
	v_mfma_f32_16x16x32_bf16 v[34:37], v[6:9], v[180:183], v[34:37]
	v_mfma_f32_16x16x32_bf16 v[30:33], v[138:141], v[180:183], v[30:33]
	v_mfma_f32_16x16x32_bf16 v[26:29], v[6:9], v[188:191], v[26:29]
	v_mfma_f32_16x16x32_bf16 v[22:25], v[138:141], v[188:191], v[22:25]
	v_mfma_f32_16x16x32_bf16 v[70:73], v[6:9], v[222:225], v[70:73]
	v_mfma_f32_16x16x32_bf16 v[66:69], v[138:141], v[222:225], v[66:69]
	v_mfma_f32_16x16x32_bf16 v[50:53], v[138:141], v[230:233], v[50:53]
	v_mfma_f32_16x16x32_bf16 v[18:21], v[164:167], v[180:183], v[18:21]
	v_mfma_f32_16x16x32_bf16 v[14:17], v[172:175], v[180:183], v[14:17]
	v_mfma_f32_16x16x32_bf16 v[10:13], v[164:167], v[188:191], v[10:13]
	v_mfma_f32_16x16x32_bf16 v[2:5], v[172:175], v[188:191], v[2:5]
	v_mfma_f32_16x16x32_bf16 v[54:57], v[164:167], v[222:225], v[54:57]
	v_mfma_f32_16x16x32_bf16 v[46:49], v[172:175], v[222:225], v[46:49]
	v_mfma_f32_16x16x32_bf16 v[42:45], v[164:167], v[230:233], v[42:45]
	v_mfma_f32_16x16x32_bf16 v[38:41], v[172:175], v[230:233], v[38:41]
	v_mfma_f32_16x16x32_bf16 v[34:37], v[62:65], v[184:187], v[34:37]
	v_mfma_f32_16x16x32_bf16 v[30:33], v[142:145], v[184:187], v[30:33]
	v_mfma_f32_16x16x32_bf16 v[26:29], v[62:65], v[192:195], v[26:29]
	v_mfma_f32_16x16x32_bf16 v[22:25], v[142:145], v[192:195], v[22:25]
	v_mfma_f32_16x16x32_bf16 v[70:73], v[62:65], v[226:229], v[70:73]
	v_mfma_f32_16x16x32_bf16 v[66:69], v[142:145], v[226:229], v[66:69]
	v_mfma_f32_16x16x32_bf16 v[6:9], v[6:9], v[230:233], v[58:61]
	v_mfma_f32_16x16x32_bf16 v[50:53], v[142:145], v[234:237], v[50:53]
	v_mfma_f32_16x16x32_bf16 v[18:21], v[168:171], v[184:187], v[18:21]
	v_mfma_f32_16x16x32_bf16 v[14:17], v[176:179], v[184:187], v[14:17]
	v_mfma_f32_16x16x32_bf16 v[10:13], v[168:171], v[192:195], v[10:13]
	v_mfma_f32_16x16x32_bf16 v[2:5], v[176:179], v[192:195], v[2:5]
	v_mfma_f32_16x16x32_bf16 v[54:57], v[168:171], v[226:229], v[54:57]
	v_mfma_f32_16x16x32_bf16 v[46:49], v[176:179], v[226:229], v[46:49]
	v_mfma_f32_16x16x32_bf16 v[42:45], v[168:171], v[234:237], v[42:45]
	v_mfma_f32_16x16x32_bf16 v[38:41], v[176:179], v[234:237], v[38:41]
	v_mfma_f32_16x16x32_bf16 v[6:9], v[62:65], v[234:237], v[6:9]
	s_setprio 0
	s_barrier
; #define PG8_STAGE(bufoff, gbase, voff) do { const char* _gb = (const char*)(gbase); asm volatile("" : "+s"(_gb)); _Pragma("unroll") for (int _i = 0; _i < 2; ++_i) { asm volatile("" : "+v"((voff)[_i])); \
;         __builtin_amdgcn_global_load_lds((const unsigned*)(_gb + (voff)[_i]), (PG8_LAS unsigned*)(lds + (bufoff) + ldsw + _i * 8192), 16, 0, 0); } } while (0)
; #define PG8_LDA(dst, b, h) do { _Pragma("unroll") for (int m = 0; m < 4; ++m) _Pragma("unroll") for (int k = 0; k < 2; ++k) dst[m][k] = *(const PG8_LAS bf16x8*)(lds + PG8_SA(b, h) + aoff + m * 2048 + k * 1024); } while (0)
; #define PG8_LDB(dst, b, h) do { _Pragma("unroll") for (int n = 0; n < 2; ++n) _Pragma("unroll") for (int k = 0; k < 2; ++k) dst[n][k] = *(const PG8_LAS bf16x8*)(lds + PG8_SB(b, h) + boff + n * 2048 + k * 1024); } while (0)
; #define PG8_WAIT_V(n) asm volatile("s_waitcnt vmcnt(" #n ")" ::: "memory")
; #define PG8_WAIT_L(n) asm volatile("s_waitcnt lgkmcnt(" #n ")" ::: "memory")
; #define PG8_BAR __builtin_amdgcn_s_barrier()
; #define PG8_SCHED __builtin_amdgcn_sched_barrier(0)
; #define PG8_STAGE(bufoff, gbase, voff) do { const char* _gb = (const char*)(gbase); asm volatile("" : "+s"(_gb)); _Pragma("unroll") for (int _i = 0; _i < 2; ++_i) { asm volatile("" : "+v"((voff)[_i])); \
;         __builtin_amdgcn_global_load_lds((const unsigned*)(_gb + (voff)[_i]), (PG8_LAS unsigned*)(lds + (bufoff) + ldsw + _i * 8192), 16, 0, 0); } } while (0)
; #define PG8_LDA(dst, b, h) do { _Pragma("unroll") for (int m = 0; m < 4; ++m) _Pragma("unroll") for (int k = 0; k < 2; ++k) dst[m][k] = *(const PG8_LAS bf16x8*)(lds + PG8_SA(b, h) + aoff + m * 2048 + k * 1024); } while (0)
; #define PG8_WAIT_V(n) asm volatile("s_waitcnt vmcnt(" #n ")" ::: "memory")
; template <class Epi, class Sched, bool ALIGN_EPI = false, bool SP2 = false>
; __device__ __forceinline__ void gemm_phase(PG8_LAS unsigned char* lds, const Gemm g, const Sched& S, const Epi& E) {
;     ...
;             PG8_LDB(B0, 1, 0); PG8_LDB(B1, 1, 1); PG8_SCHED; PG8_LDA(At, 1, 0); PG8_STAGE(PG8_SA(0, 1), a2 + hstep, voffA);
;             PG8_WAIT_V(8); PG8_WAIT_L(0); PG8_BAR; PG8_MMA2(0); PG8_BAR; PG8_SCHED;
;             PG8_LDA(At, 1, 1); PG8_STAGE(PG8_SB(1, 0), b3, voffB); PG8_STAGE(PG8_SB(1, 1), b3 + hstep, voffB); PG8_STAGE(PG8_SA(1, 0), a3, voffA);
;             PG8_WAIT_V(8); PG8_WAIT_L(0); PG8_BAR; PG8_MMA2(1); PG8_BAR; PG8_SCHED;
	s_add_i32 s84, 0, 0x18000
	s_add_i32 s85, 0, 0x1c000
	s_add_u32 s12, s18, 0x100000
	s_addc_u32 s13, s19, 0
	s_mov_b32 m0, s47
	ds_read_b128 v[230:233], v219 offset:38912
	global_load_lds_dwordx4 v1, s[12:13]
	s_mov_b32 m0, s87
	ds_read_b128 v[234:237], v219 offset:39936
	global_load_lds_dwordx4 v199, s[12:13]
	v_add_u32_e32 v142, s84, v201
	v_add_u32_e32 v147, s85, v201
	ds_read_b128 v[58:61], v142
	ds_read_b128 v[62:65], v142 offset:1024
	ds_read_b128 v[138:141], v142 offset:2048
	ds_read_b128 v[142:145], v142 offset:3072
	ds_read_b128 v[164:167], v147
	ds_read_b128 v[168:171], v147 offset:1024
	ds_read_b128 v[172:175], v147 offset:2048
	ds_read_b128 v[176:179], v147 offset:3072
	ds_read_b128 v[180:183], v219 offset:32768
	ds_read_b128 v[184:187], v219 offset:33792
	ds_read_b128 v[188:191], v219 offset:34816
	ds_read_b128 v[192:195], v219 offset:35840
	ds_read_b128 v[222:225], v219 offset:36864
	ds_read_b128 v[226:229], v219 offset:37888
	s_waitcnt vmcnt(8)
	s_waitcnt lgkmcnt(0)
	s_setprio 1
	s_waitcnt lgkmcnt(0)
	s_barrier
	v_mfma_f32_16x16x32_bf16 v[118:121], v[58:61], v[180:183], v[118:121]
	v_mfma_f32_16x16x32_bf16 v[114:117], v[138:141], v[180:183], v[114:117]
	v_mfma_f32_16x16x32_bf16 v[106:109], v[58:61], v[188:191], v[106:109]
	v_mfma_f32_16x16x32_bf16 v[86:89], v[138:141], v[188:191], v[86:89]
	v_mfma_f32_16x16x32_bf16 v[134:137], v[58:61], v[222:225], v[134:137]
	v_mfma_f32_16x16x32_bf16 v[90:93], v[138:141], v[222:225], v[90:93]
	v_mfma_f32_16x16x32_bf16 v[130:133], v[58:61], v[230:233], v[130:133]
	v_mfma_f32_16x16x32_bf16 v[110:113], v[138:141], v[230:233], v[110:113]
	v_mfma_f32_16x16x32_bf16 v[94:97], v[164:167], v[180:183], v[94:97]
	v_mfma_f32_16x16x32_bf16 v[82:85], v[172:175], v[180:183], v[82:85]
	v_mfma_f32_16x16x32_bf16 v[78:81], v[164:167], v[188:191], v[78:81]
	v_mfma_f32_16x16x32_bf16 v[74:77], v[172:175], v[188:191], v[74:77]
	v_mfma_f32_16x16x32_bf16 v[126:129], v[164:167], v[222:225], v[126:129]
	v_mfma_f32_16x16x32_bf16 v[98:101], v[172:175], v[222:225], v[98:101]
	v_mfma_f32_16x16x32_bf16 v[122:125], v[164:167], v[230:233], v[122:125]
	v_mfma_f32_16x16x32_bf16 v[102:105], v[172:175], v[230:233], v[102:105]
	v_mfma_f32_16x16x32_bf16 v[118:121], v[62:65], v[184:187], v[118:121]
	v_mfma_f32_16x16x32_bf16 v[114:117], v[142:145], v[184:187], v[114:117]
	v_mfma_f32_16x16x32_bf16 v[106:109], v[62:65], v[192:195], v[106:109]
	v_mfma_f32_16x16x32_bf16 v[86:89], v[142:145], v[192:195], v[86:89]
	v_mfma_f32_16x16x32_bf16 v[134:137], v[62:65], v[226:229], v[134:137]
	v_mfma_f32_16x16x32_bf16 v[90:93], v[142:145], v[226:229], v[90:93]
	v_mfma_f32_16x16x32_bf16 v[130:133], v[62:65], v[234:237], v[130:133]
	v_mfma_f32_16x16x32_bf16 v[110:113], v[142:145], v[234:237], v[110:113]
	v_mfma_f32_16x16x32_bf16 v[94:97], v[168:171], v[184:187], v[94:97]
	v_mfma_f32_16x16x32_bf16 v[82:85], v[176:179], v[184:187], v[82:85]
	v_mfma_f32_16x16x32_bf16 v[78:81], v[168:171], v[192:195], v[78:81]
	v_mfma_f32_16x16x32_bf16 v[74:77], v[176:179], v[192:195], v[74:77]
	v_mfma_f32_16x16x32_bf16 v[126:129], v[168:171], v[226:229], v[126:129]
	v_mfma_f32_16x16x32_bf16 v[98:101], v[176:179], v[226:229], v[98:101]
	v_mfma_f32_16x16x32_bf16 v[122:125], v[168:171], v[234:237], v[122:125]
	v_mfma_f32_16x16x32_bf16 v[102:105], v[176:179], v[234:237], v[102:105]
	s_setprio 0
	s_barrier
	s_add_u32 s12, s16, 0x80
	s_addc_u32 s13, s17, 0
	s_add_i32 s18, s84, s25
	s_mov_b32 m0, s18
	ds_read_b128 v[188:191], v219 offset:51200
	global_load_lds_dwordx4 v198, s[12:13]
	s_add_i32 m0, s18, 0x2000
	ds_read_b128 v[192:195], v219 offset:52224
	global_load_lds_dwordx4 v200, s[12:13]
	s_add_u32 s12, s16, 0x100080
	s_addc_u32 s13, s17, 0
	s_add_i32 s16, s85, s25
	s_mov_b32 m0, s16
	ds_read_b128 v[222:225], v219 offset:53248
	global_load_lds_dwordx4 v198, s[12:13]
	s_add_i32 m0, s16, 0x2000
	ds_read_b128 v[226:229], v219 offset:54272
	global_load_lds_dwordx4 v200, s[12:13]
	s_mov_b32 m0, s71
	ds_read_b128 v[230:233], v219 offset:55296
	global_load_lds_dwordx4 v1, s[2:3]
	s_mov_b32 m0, s72
	ds_read_b128 v[234:237], v219 offset:56320
	global_load_lds_dwordx4 v199, s[2:3]
	ds_read_b128 v[180:183], v219 offset:49152
	ds_read_b128 v[184:187], v219 offset:50176
	s_waitcnt vmcnt(8)
	s_waitcnt lgkmcnt(0)
	s_setprio 1
	s_waitcnt lgkmcnt(0)
	s_barrier
	v_mfma_f32_16x16x32_bf16 v[6:9], v[58:61], v[230:233], v[6:9]
	v_mfma_f32_16x16x32_bf16 v[34:37], v[58:61], v[180:183], v[34:37]
	v_mfma_f32_16x16x32_bf16 v[26:29], v[58:61], v[188:191], v[26:29]
	v_mfma_f32_16x16x32_bf16 v[70:73], v[58:61], v[222:225], v[70:73]
	v_mfma_f32_16x16x32_bf16 v[58:61], v[62:65], v[234:237], v[6:9]
	v_mfma_f32_16x16x32_bf16 v[6:9], v[138:141], v[230:233], v[50:53]
	v_mfma_f32_16x16x32_bf16 v[50:53], v[142:145], v[234:237], v[6:9]
	v_mfma_f32_16x16x32_bf16 v[6:9], v[164:167], v[180:183], v[18:21]
	v_mfma_f32_16x16x32_bf16 v[18:21], v[168:171], v[184:187], v[6:9]
	v_mfma_f32_16x16x32_bf16 v[6:9], v[172:175], v[180:183], v[14:17]
	v_mfma_f32_16x16x32_bf16 v[14:17], v[176:179], v[184:187], v[6:9]
	v_mfma_f32_16x16x32_bf16 v[6:9], v[164:167], v[188:191], v[10:13]
	v_mfma_f32_16x16x32_bf16 v[10:13], v[168:171], v[192:195], v[6:9]
	v_mfma_f32_16x16x32_bf16 v[6:9], v[164:167], v[222:225], v[54:57]
	v_mfma_f32_16x16x32_bf16 v[54:57], v[168:171], v[226:229], v[6:9]
	v_mfma_f32_16x16x32_bf16 v[6:9], v[172:175], v[222:225], v[46:49]
	v_mfma_f32_16x16x32_bf16 v[46:49], v[176:179], v[226:229], v[6:9]
	v_mfma_f32_16x16x32_bf16 v[6:9], v[164:167], v[230:233], v[42:45]
	v_mfma_f32_16x16x32_bf16 v[30:33], v[138:141], v[180:183], v[30:33]
	v_mfma_f32_16x16x32_bf16 v[22:25], v[138:141], v[188:191], v[22:25]
	v_mfma_f32_16x16x32_bf16 v[66:69], v[138:141], v[222:225], v[66:69]
	v_mfma_f32_16x16x32_bf16 v[2:5], v[172:175], v[188:191], v[2:5]
	v_mfma_f32_16x16x32_bf16 v[42:45], v[168:171], v[234:237], v[6:9]
	v_mfma_f32_16x16x32_bf16 v[6:9], v[172:175], v[230:233], v[38:41]
	v_mfma_f32_16x16x32_bf16 v[34:37], v[62:65], v[184:187], v[34:37]
	v_mfma_f32_16x16x32_bf16 v[30:33], v[142:145], v[184:187], v[30:33]
	v_mfma_f32_16x16x32_bf16 v[26:29], v[62:65], v[192:195], v[26:29]
	v_mfma_f32_16x16x32_bf16 v[22:25], v[142:145], v[192:195], v[22:25]
	v_mfma_f32_16x16x32_bf16 v[70:73], v[62:65], v[226:229], v[70:73]
	v_mfma_f32_16x16x32_bf16 v[66:69], v[142:145], v[226:229], v[66:69]
	v_mfma_f32_16x16x32_bf16 v[2:5], v[176:179], v[192:195], v[2:5]
	v_mfma_f32_16x16x32_bf16 v[38:41], v[176:179], v[234:237], v[6:9]
	s_setprio 0
	s_barrier
	s_add_i32 s83, s83, 2
	s_add_u32 s62, s62, 0x100
	s_addc_u32 s63, s63, 0
	s_cmp_gt_u32 s83, 61
	s_mov_b64 s[12:13], s[14:15]
	s_cbranch_scc0 .LBB0_933
	s_nop 0
	s_and_b64 vcc, exec, s[38:39]
	s_cbranch_vccz .LBB0_936
	s_barrier

; #define PG8_STAGE(bufoff, gbase, voff) do { const char* _gb = (const char*)(gbase); asm volatile("" : "+s"(_gb)); _Pragma("unroll") for (int _i = 0; _i < 2; ++_i) { asm volatile("" : "+v"((voff)[_i])); \
;         __builtin_amdgcn_global_load_lds((const unsigned*)(_gb + (voff)[_i]), (PG8_LAS unsigned*)(lds + (bufoff) + ldsw + _i * 8192), 16, 0, 0); } } while (0)
; #define PG8_LDA(dst, b, h) do { _Pragma("unroll") for (int m = 0; m < 4; ++m) _Pragma("unroll") for (int k = 0; k < 2; ++k) dst[m][k] = *(const PG8_LAS bf16x8*)(lds + PG8_SA(b, h) + aoff + m * 2048 + k * 1024); } while (0)
; #define PG8_LDB(dst, b, h) do { _Pragma("unroll") for (int n = 0; n < 2; ++n) _Pragma("unroll") for (int k = 0; k < 2; ++k) dst[n][k] = *(const PG8_LAS bf16x8*)(lds + PG8_SB(b, h) + boff + n * 2048 + k * 1024); } while (0)
; #define PG8_WAIT_V(n) asm volatile("s_waitcnt vmcnt(" #n ")" ::: "memory")
; #define PG8_WAIT_L(n) asm volatile("s_waitcnt lgkmcnt(" #n ")" ::: "memory")
; #define PG8_BAR __builtin_amdgcn_s_barrier()
; #define PG8_SCHED __builtin_amdgcn_sched_barrier(0)
; #define PG8_STAGE(bufoff, gbase, voff) do { const char* _gb = (const char*)(gbase); asm volatile("" : "+s"(_gb)); _Pragma("unroll") for (int _i = 0; _i < 2; ++_i) { asm volatile("" : "+v"((voff)[_i])); \
;         __builtin_amdgcn_global_load_lds((const unsigned*)(_gb + (voff)[_i]), (PG8_LAS unsigned*)(lds + (bufoff) + ldsw + _i * 8192), 16, 0, 0); } } while (0)
; #define PG8_LDA(dst, b, h) do { _Pragma("unroll") for (int m = 0; m < 4; ++m) _Pragma("unroll") for (int k = 0; k < 2; ++k) dst[m][k] = *(const PG8_LAS bf16x8*)(lds + PG8_SA(b, h) + aoff + m * 2048 + k * 1024); } while (0)
; #define PG8_WAIT_V(n) asm volatile("s_waitcnt vmcnt(" #n ")" ::: "memory")
; template <class Epi, class Sched, bool ALIGN_EPI = false, bool SP2 = false>
; __device__ __forceinline__ void gemm_phase(PG8_LAS unsigned char* lds, const Gemm g, const Sched& S, const Epi& E) {
;     ...
;             PG8_LDB(B0, 0, 0); PG8_LDB(B1, 0, 1); PG8_SCHED; PG8_LDA(At, 0, 0); PG8_STAGE(PG8_SA(1, 1), a1 + hstep, voffA);
;             PG8_WAIT_V(8); PG8_WAIT_L(0); PG8_BAR; PG8_MMA2(0); PG8_BAR; PG8_SCHED;
;             PG8_LDA(At, 0, 1); PG8_STAGE(PG8_SB(0, 0), b2, voffB); PG8_STAGE(PG8_SB(0, 1), b2 + hstep, voffB); PG8_STAGE(PG8_SA(0, 0), a2, voffA);
;             PG8_WAIT_V(8); PG8_WAIT_L(0); PG8_BAR; PG8_MMA2(1); PG8_BAR; PG8_SCHED;
.LBB0_1125:
	s_add_u32 s20, s16, 0x100
	s_addc_u32 s21, s17, 0
	s_cmpk_eq_i32 s53, 0xbc
	s_cselect_b32 s26, s6, s20
	s_cselect_b32 s27, s7, s21
	s_cselect_b32 s24, s18, s51
	s_cselect_b32 s25, s19, s52
	s_add_u32 s2, s26, 0x80
	s_addc_u32 s3, s27, 0
	s_add_u32 s16, s16, 0x300080
	s_addc_u32 s17, s17, 0
	s_add_i32 m0, s34, 0xc000
	ds_read_b128 v[202:205], v164 offset:6144
	global_load_lds_dwordx4 v1, s[16:17]
	s_add_i32 m0, s34, 0xe000
	ds_read_b128 v[206:209], v164 offset:7168
	global_load_lds_dwordx4 v157, s[16:17]
	ds_read_b128 v[130:133], v162
	ds_read_b128 v[134:137], v162 offset:1024
	ds_read_b128 v[138:141], v162 offset:2048
	ds_read_b128 v[142:145], v162 offset:3072
	ds_read_b128 v[150:153], v163
	ds_read_b128 v[166:169], v163 offset:1024
	ds_read_b128 v[170:173], v163 offset:2048
	ds_read_b128 v[174:177], v163 offset:3072
	ds_read_b128 v[178:181], v164
	ds_read_b128 v[182:185], v164 offset:1024
	ds_read_b128 v[186:189], v164 offset:2048
	ds_read_b128 v[190:193], v164 offset:3072
	ds_read_b128 v[194:197], v164 offset:4096
	ds_read_b128 v[198:201], v164 offset:5120
	s_waitcnt vmcnt(8)
	s_waitcnt lgkmcnt(0)
	s_setprio 1
	s_waitcnt lgkmcnt(0)
	s_barrier
	v_mfma_f32_16x16x32_bf16 v[126:129], v[130:133], v[178:181], v[126:129]
	v_mfma_f32_16x16x32_bf16 v[122:125], v[138:141], v[178:181], v[122:125]
	v_mfma_f32_16x16x32_bf16 v[110:113], v[130:133], v[186:189], v[110:113]
	v_mfma_f32_16x16x32_bf16 v[106:109], v[138:141], v[186:189], v[106:109]
	v_mfma_f32_16x16x32_bf16 v[94:97], v[130:133], v[194:197], v[94:97]
	v_mfma_f32_16x16x32_bf16 v[90:93], v[138:141], v[194:197], v[90:93]
	v_mfma_f32_16x16x32_bf16 v[78:81], v[130:133], v[202:205], v[78:81]
	v_mfma_f32_16x16x32_bf16 v[74:77], v[138:141], v[202:205], v[74:77]
	v_mfma_f32_16x16x32_bf16 v[118:121], v[150:153], v[178:181], v[118:121]
	v_mfma_f32_16x16x32_bf16 v[114:117], v[170:173], v[178:181], v[114:117]
	v_mfma_f32_16x16x32_bf16 v[102:105], v[150:153], v[186:189], v[102:105]
	v_mfma_f32_16x16x32_bf16 v[98:101], v[170:173], v[186:189], v[98:101]
	v_mfma_f32_16x16x32_bf16 v[86:89], v[150:153], v[194:197], v[86:89]
	v_mfma_f32_16x16x32_bf16 v[82:85], v[170:173], v[194:197], v[82:85]
	v_mfma_f32_16x16x32_bf16 v[70:73], v[150:153], v[202:205], v[70:73]
	v_mfma_f32_16x16x32_bf16 v[66:69], v[170:173], v[202:205], v[66:69]
	v_mfma_f32_16x16x32_bf16 v[126:129], v[134:137], v[182:185], v[126:129]
	v_mfma_f32_16x16x32_bf16 v[122:125], v[142:145], v[182:185], v[122:125]
	v_mfma_f32_16x16x32_bf16 v[110:113], v[134:137], v[190:193], v[110:113]
	v_mfma_f32_16x16x32_bf16 v[106:109], v[142:145], v[190:193], v[106:109]
	v_mfma_f32_16x16x32_bf16 v[94:97], v[134:137], v[198:201], v[94:97]
	v_mfma_f32_16x16x32_bf16 v[90:93], v[142:145], v[198:201], v[90:93]
	v_mfma_f32_16x16x32_bf16 v[78:81], v[134:137], v[206:209], v[78:81]
	v_mfma_f32_16x16x32_bf16 v[74:77], v[142:145], v[206:209], v[74:77]
	v_mfma_f32_16x16x32_bf16 v[118:121], v[166:169], v[182:185], v[118:121]
	v_mfma_f32_16x16x32_bf16 v[114:117], v[174:177], v[182:185], v[114:117]
	v_mfma_f32_16x16x32_bf16 v[102:105], v[166:169], v[190:193], v[102:105]
	v_mfma_f32_16x16x32_bf16 v[98:101], v[174:177], v[190:193], v[98:101]
	v_mfma_f32_16x16x32_bf16 v[86:89], v[166:169], v[198:201], v[86:89]
	v_mfma_f32_16x16x32_bf16 v[82:85], v[174:177], v[198:201], v[82:85]
	v_mfma_f32_16x16x32_bf16 v[70:73], v[166:169], v[206:209], v[70:73]
	v_mfma_f32_16x16x32_bf16 v[66:69], v[174:177], v[206:209], v[66:69]
	s_setprio 0
	s_barrier
	s_add_i32 s54, s43, s33
	s_mov_b64 s[16:17], s[24:25]
	s_mov_b32 m0, s54
	ds_read_b128 v[186:189], v164 offset:18432
	global_load_lds_dwordx4 v156, s[16:17]
	s_add_i32 m0, s54, 0x2000
	ds_read_b128 v[190:193], v164 offset:19456
	global_load_lds_dwordx4 v158, s[16:17]
	s_add_u32 s16, s24, 0x300000
	s_addc_u32 s17, s25, 0
	s_add_i32 s54, s44, s33
	s_mov_b32 m0, s54
	ds_read_b128 v[194:197], v164 offset:20480
	global_load_lds_dwordx4 v156, s[16:17]
	s_add_i32 m0, s54, 0x2000
	ds_read_b128 v[198:201], v164 offset:21504
	global_load_lds_dwordx4 v158, s[16:17]
	s_mov_b64 s[16:17], s[26:27]
	s_mov_b32 m0, s34
	ds_read_b128 v[202:205], v164 offset:22528
	global_load_lds_dwordx4 v1, s[16:17]
	s_mov_b32 m0, s35
	ds_read_b128 v[206:209], v164 offset:23552
	global_load_lds_dwordx4 v157, s[16:17]
	ds_read_b128 v[178:181], v164 offset:16384
	ds_read_b128 v[182:185], v164 offset:17408
	s_waitcnt vmcnt(8)
	s_waitcnt lgkmcnt(0)
	s_setprio 1
	s_waitcnt lgkmcnt(0)
	s_barrier
	v_mfma_f32_16x16x32_bf16 v[62:65], v[130:133], v[178:181], v[62:65]
	v_mfma_f32_16x16x32_bf16 v[58:61], v[138:141], v[178:181], v[58:61]
	v_mfma_f32_16x16x32_bf16 v[46:49], v[130:133], v[186:189], v[46:49]
	v_mfma_f32_16x16x32_bf16 v[42:45], v[138:141], v[186:189], v[42:45]
	v_mfma_f32_16x16x32_bf16 v[30:33], v[130:133], v[194:197], v[30:33]
	v_mfma_f32_16x16x32_bf16 v[26:29], v[138:141], v[194:197], v[26:29]
	v_mfma_f32_16x16x32_bf16 v[14:17], v[130:133], v[202:205], v[14:17]
	v_mfma_f32_16x16x32_bf16 v[10:13], v[138:141], v[202:205], v[10:13]
	v_mfma_f32_16x16x32_bf16 v[54:57], v[150:153], v[178:181], v[54:57]
	v_mfma_f32_16x16x32_bf16 v[50:53], v[170:173], v[178:181], v[50:53]
	v_mfma_f32_16x16x32_bf16 v[38:41], v[150:153], v[186:189], v[38:41]
	v_mfma_f32_16x16x32_bf16 v[34:37], v[170:173], v[186:189], v[34:37]
	v_mfma_f32_16x16x32_bf16 v[22:25], v[150:153], v[194:197], v[22:25]
	v_mfma_f32_16x16x32_bf16 v[18:21], v[170:173], v[194:197], v[18:21]
	v_mfma_f32_16x16x32_bf16 v[6:9], v[150:153], v[202:205], v[6:9]
	v_mfma_f32_16x16x32_bf16 v[2:5], v[170:173], v[202:205], v[2:5]
	v_mfma_f32_16x16x32_bf16 v[62:65], v[134:137], v[182:185], v[62:65]
	v_mfma_f32_16x16x32_bf16 v[58:61], v[142:145], v[182:185], v[58:61]
	v_mfma_f32_16x16x32_bf16 v[46:49], v[134:137], v[190:193], v[46:49]
	v_mfma_f32_16x16x32_bf16 v[42:45], v[142:145], v[190:193], v[42:45]
	v_mfma_f32_16x16x32_bf16 v[30:33], v[134:137], v[198:201], v[30:33]
	v_mfma_f32_16x16x32_bf16 v[26:29], v[142:145], v[198:201], v[26:29]
	v_mfma_f32_16x16x32_bf16 v[14:17], v[134:137], v[206:209], v[14:17]
	v_mfma_f32_16x16x32_bf16 v[10:13], v[142:145], v[206:209], v[10:13]
	v_mfma_f32_16x16x32_bf16 v[54:57], v[166:169], v[182:185], v[54:57]
	v_mfma_f32_16x16x32_bf16 v[50:53], v[174:177], v[182:185], v[50:53]
	v_mfma_f32_16x16x32_bf16 v[38:41], v[166:169], v[190:193], v[38:41]
	v_mfma_f32_16x16x32_bf16 v[34:37], v[174:177], v[190:193], v[34:37]
	v_mfma_f32_16x16x32_bf16 v[22:25], v[166:169], v[198:201], v[22:25]
	v_mfma_f32_16x16x32_bf16 v[18:21], v[174:177], v[198:201], v[18:21]
	v_mfma_f32_16x16x32_bf16 v[6:9], v[166:169], v[206:209], v[6:9]
	v_mfma_f32_16x16x32_bf16 v[2:5], v[174:177], v[206:209], v[2:5]
	s_setprio 0
	s_barrier
; #define PG8_STAGE(bufoff, gbase, voff) do { const char* _gb = (const char*)(gbase); asm volatile("" : "+s"(_gb)); _Pragma("unroll") for (int _i = 0; _i < 2; ++_i) { asm volatile("" : "+v"((voff)[_i])); \
;         __builtin_amdgcn_global_load_lds((const unsigned*)(_gb + (voff)[_i]), (PG8_LAS unsigned*)(lds + (bufoff) + ldsw + _i * 8192), 16, 0, 0); } } while (0)
; #define PG8_LDA(dst, b, h) do { _Pragma("unroll") for (int m = 0; m < 4; ++m) _Pragma("unroll") for (int k = 0; k < 2; ++k) dst[m][k] = *(const PG8_LAS bf16x8*)(lds + PG8_SA(b, h) + aoff + m * 2048 + k * 1024); } while (0)
; #define PG8_LDB(dst, b, h) do { _Pragma("unroll") for (int n = 0; n < 2; ++n) _Pragma("unroll") for (int k = 0; k < 2; ++k) dst[n][k] = *(const PG8_LAS bf16x8*)(lds + PG8_SB(b, h) + boff + n * 2048 + k * 1024); } while (0)
; #define PG8_WAIT_V(n) asm volatile("s_waitcnt vmcnt(" #n ")" ::: "memory")
; #define PG8_WAIT_L(n) asm volatile("s_waitcnt lgkmcnt(" #n ")" ::: "memory")
; #define PG8_BAR __builtin_amdgcn_s_barrier()
; #define PG8_SCHED __builtin_amdgcn_sched_barrier(0)
; #define PG8_LDA(dst, b, h) do { _Pragma("unroll") for (int m = 0; m < 4; ++m) _Pragma("unroll") for (int k = 0; k < 2; ++k) dst[m][k] = *(const PG8_LAS bf16x8*)(lds + PG8_SA(b, h) + aoff + m * 2048 + k * 1024); } while (0)
; #define PG8_BAR __builtin_amdgcn_s_barrier()
; template <class Epi, class Sched, bool ALIGN_EPI = false, bool SP2 = false>
; __device__ __forceinline__ void gemm_phase(PG8_LAS unsigned char* lds, const Gemm g, const Sched& S, const Epi& E) {
;     ...
;         for (int t = 0; t < nt; t += 2) {
;             const bool last = (t == nt - 2);
;             const char* a1 = cA + (size_t)(t + 1) * kstep;
;             const char* a2 = last ? nA : cA + (size_t)(t + 2) * kstep; const char* b2 = last ? nB : cB + (size_t)(t + 2) * kstep;
;             const char* a3 = a2 + kstep; const char* b3 = b2 + kstep;
;             if (last && has_next) S.a_ready(nxt);
;     ...
;             PG8_LDB(B0, 1, 0); PG8_LDB(B1, 1, 1); PG8_SCHED; PG8_LDA(At, 1, 0); PG8_STAGE(PG8_SA(0, 1), a2 + hstep, voffA);
;             PG8_WAIT_V(8); PG8_WAIT_L(0); PG8_BAR; PG8_MMA2(0); PG8_BAR; PG8_SCHED;
;             PG8_LDA(At, 1, 1); PG8_STAGE(PG8_SB(1, 0), b3, voffB); PG8_STAGE(PG8_SB(1, 1), b3 + hstep, voffB); PG8_STAGE(PG8_SA(1, 0), a3, voffA);
;             PG8_WAIT_V(8); PG8_WAIT_L(0); PG8_BAR; PG8_MMA2(1); PG8_BAR; PG8_SCHED;
	s_add_i32 s54, 0, 0x18000
	s_add_i32 s55, 0, 0x1c000
	s_add_u32 s16, s26, 0x300000
	s_addc_u32 s17, s27, 0
	s_mov_b32 m0, s36
	ds_read_b128 v[202:205], v164 offset:38912
	global_load_lds_dwordx4 v1, s[16:17]
	s_mov_b32 m0, s37
	ds_read_b128 v[206:209], v164 offset:39936
	global_load_lds_dwordx4 v157, s[16:17]
	v_add_u32_e32 v142, s54, v160
	v_add_u32_e32 v154, s55, v160
	ds_read_b128 v[130:133], v142
	ds_read_b128 v[134:137], v142 offset:1024
	ds_read_b128 v[138:141], v142 offset:2048
	ds_read_b128 v[142:145], v142 offset:3072
	ds_read_b128 v[150:153], v154
	ds_read_b128 v[166:169], v154 offset:1024
	ds_read_b128 v[170:173], v154 offset:2048
	ds_read_b128 v[174:177], v154 offset:3072
	ds_read_b128 v[178:181], v164 offset:32768
	ds_read_b128 v[182:185], v164 offset:33792
	ds_read_b128 v[186:189], v164 offset:34816
	ds_read_b128 v[190:193], v164 offset:35840
	ds_read_b128 v[194:197], v164 offset:36864
	ds_read_b128 v[198:201], v164 offset:37888
	s_waitcnt vmcnt(8)
	s_waitcnt lgkmcnt(0)
	s_setprio 1
	s_waitcnt lgkmcnt(0)
	s_barrier
	v_mfma_f32_16x16x32_bf16 v[126:129], v[130:133], v[178:181], v[126:129]
	v_mfma_f32_16x16x32_bf16 v[122:125], v[138:141], v[178:181], v[122:125]
	v_mfma_f32_16x16x32_bf16 v[110:113], v[130:133], v[186:189], v[110:113]
	v_mfma_f32_16x16x32_bf16 v[106:109], v[138:141], v[186:189], v[106:109]
	v_mfma_f32_16x16x32_bf16 v[94:97], v[130:133], v[194:197], v[94:97]
	v_mfma_f32_16x16x32_bf16 v[90:93], v[138:141], v[194:197], v[90:93]
	v_mfma_f32_16x16x32_bf16 v[78:81], v[130:133], v[202:205], v[78:81]
	v_mfma_f32_16x16x32_bf16 v[74:77], v[138:141], v[202:205], v[74:77]
	v_mfma_f32_16x16x32_bf16 v[118:121], v[150:153], v[178:181], v[118:121]
	v_mfma_f32_16x16x32_bf16 v[114:117], v[170:173], v[178:181], v[114:117]
	v_mfma_f32_16x16x32_bf16 v[102:105], v[150:153], v[186:189], v[102:105]
	v_mfma_f32_16x16x32_bf16 v[98:101], v[170:173], v[186:189], v[98:101]
	v_mfma_f32_16x16x32_bf16 v[86:89], v[150:153], v[194:197], v[86:89]
	v_mfma_f32_16x16x32_bf16 v[82:85], v[170:173], v[194:197], v[82:85]
	v_mfma_f32_16x16x32_bf16 v[70:73], v[150:153], v[202:205], v[70:73]
	v_mfma_f32_16x16x32_bf16 v[66:69], v[170:173], v[202:205], v[66:69]
	v_mfma_f32_16x16x32_bf16 v[126:129], v[134:137], v[182:185], v[126:129]
	v_mfma_f32_16x16x32_bf16 v[122:125], v[142:145], v[182:185], v[122:125]
	v_mfma_f32_16x16x32_bf16 v[110:113], v[134:137], v[190:193], v[110:113]
	v_mfma_f32_16x16x32_bf16 v[106:109], v[142:145], v[190:193], v[106:109]
	v_mfma_f32_16x16x32_bf16 v[94:97], v[134:137], v[198:201], v[94:97]
	v_mfma_f32_16x16x32_bf16 v[90:93], v[142:145], v[198:201], v[90:93]
	v_mfma_f32_16x16x32_bf16 v[78:81], v[134:137], v[206:209], v[78:81]
	v_mfma_f32_16x16x32_bf16 v[74:77], v[142:145], v[206:209], v[74:77]
	v_mfma_f32_16x16x32_bf16 v[118:121], v[166:169], v[182:185], v[118:121]
	v_mfma_f32_16x16x32_bf16 v[114:117], v[174:177], v[182:185], v[114:117]
	v_mfma_f32_16x16x32_bf16 v[102:105], v[166:169], v[190:193], v[102:105]
	v_mfma_f32_16x16x32_bf16 v[98:101], v[174:177], v[190:193], v[98:101]
	v_mfma_f32_16x16x32_bf16 v[86:89], v[166:169], v[198:201], v[86:89]
	v_mfma_f32_16x16x32_bf16 v[82:85], v[174:177], v[198:201], v[82:85]
	v_mfma_f32_16x16x32_bf16 v[70:73], v[166:169], v[206:209], v[70:73]
	v_mfma_f32_16x16x32_bf16 v[66:69], v[174:177], v[206:209], v[66:69]
	s_setprio 0
	s_barrier
	s_add_u32 s16, s24, 0x80
	s_addc_u32 s17, s25, 0
	s_add_i32 s26, s54, s33
	s_mov_b32 m0, s26
	ds_read_b128 v[186:189], v164 offset:51200
	global_load_lds_dwordx4 v156, s[16:17]
	s_add_i32 m0, s26, 0x2000
	ds_read_b128 v[190:193], v164 offset:52224
	global_load_lds_dwordx4 v158, s[16:17]
	s_add_u32 s16, s24, 0x300080
	s_addc_u32 s17, s25, 0
	s_add_i32 s24, s55, s33
	s_mov_b32 m0, s24
	ds_read_b128 v[194:197], v164 offset:53248
	global_load_lds_dwordx4 v156, s[16:17]
	s_add_i32 m0, s24, 0x2000
	ds_read_b128 v[198:201], v164 offset:54272
	global_load_lds_dwordx4 v158, s[16:17]
	s_mov_b32 m0, s39
	ds_read_b128 v[202:205], v164 offset:55296
	global_load_lds_dwordx4 v1, s[2:3]
	s_mov_b32 m0, s40
	ds_read_b128 v[206:209], v164 offset:56320
	global_load_lds_dwordx4 v157, s[2:3]
	ds_read_b128 v[178:181], v164 offset:49152
	ds_read_b128 v[182:185], v164 offset:50176
	s_waitcnt vmcnt(8)
	s_waitcnt lgkmcnt(0)
	s_setprio 1
	s_waitcnt lgkmcnt(0)
	s_barrier
	v_mfma_f32_16x16x32_bf16 v[62:65], v[130:133], v[178:181], v[62:65]
	v_mfma_f32_16x16x32_bf16 v[58:61], v[138:141], v[178:181], v[58:61]
	v_mfma_f32_16x16x32_bf16 v[46:49], v[130:133], v[186:189], v[46:49]
	v_mfma_f32_16x16x32_bf16 v[42:45], v[138:141], v[186:189], v[42:45]
	v_mfma_f32_16x16x32_bf16 v[30:33], v[130:133], v[194:197], v[30:33]
	v_mfma_f32_16x16x32_bf16 v[26:29], v[138:141], v[194:197], v[26:29]
	v_mfma_f32_16x16x32_bf16 v[14:17], v[130:133], v[202:205], v[14:17]
	v_mfma_f32_16x16x32_bf16 v[10:13], v[138:141], v[202:205], v[10:13]
	v_mfma_f32_16x16x32_bf16 v[54:57], v[150:153], v[178:181], v[54:57]
	v_mfma_f32_16x16x32_bf16 v[50:53], v[170:173], v[178:181], v[50:53]
	v_mfma_f32_16x16x32_bf16 v[38:41], v[150:153], v[186:189], v[38:41]
	v_mfma_f32_16x16x32_bf16 v[34:37], v[170:173], v[186:189], v[34:37]
	v_mfma_f32_16x16x32_bf16 v[22:25], v[150:153], v[194:197], v[22:25]
	v_mfma_f32_16x16x32_bf16 v[18:21], v[170:173], v[194:197], v[18:21]
	v_mfma_f32_16x16x32_bf16 v[6:9], v[150:153], v[202:205], v[6:9]
	v_mfma_f32_16x16x32_bf16 v[2:5], v[170:173], v[202:205], v[2:5]
	v_mfma_f32_16x16x32_bf16 v[62:65], v[134:137], v[182:185], v[62:65]
	v_mfma_f32_16x16x32_bf16 v[58:61], v[142:145], v[182:185], v[58:61]
	v_mfma_f32_16x16x32_bf16 v[46:49], v[134:137], v[190:193], v[46:49]
	v_mfma_f32_16x16x32_bf16 v[42:45], v[142:145], v[190:193], v[42:45]
	v_mfma_f32_16x16x32_bf16 v[30:33], v[134:137], v[198:201], v[30:33]
	v_mfma_f32_16x16x32_bf16 v[26:29], v[142:145], v[198:201], v[26:29]
	v_mfma_f32_16x16x32_bf16 v[14:17], v[134:137], v[206:209], v[14:17]
	v_mfma_f32_16x16x32_bf16 v[10:13], v[142:145], v[206:209], v[10:13]
	v_mfma_f32_16x16x32_bf16 v[54:57], v[166:169], v[182:185], v[54:57]
	v_mfma_f32_16x16x32_bf16 v[50:53], v[174:177], v[182:185], v[50:53]
	v_mfma_f32_16x16x32_bf16 v[38:41], v[166:169], v[190:193], v[38:41]
	v_mfma_f32_16x16x32_bf16 v[34:37], v[174:177], v[190:193], v[34:37]
	v_mfma_f32_16x16x32_bf16 v[22:25], v[166:169], v[198:201], v[22:25]
	v_mfma_f32_16x16x32_bf16 v[18:21], v[174:177], v[198:201], v[18:21]
	v_mfma_f32_16x16x32_bf16 v[6:9], v[166:169], v[206:209], v[6:9]
	v_mfma_f32_16x16x32_bf16 v[2:5], v[174:177], v[206:209], v[2:5]
	s_setprio 0
	s_barrier
	s_add_i32 s53, s53, 2
	s_add_u32 s51, s51, 0x100
	s_addc_u32 s52, s52, 0
	s_cmpk_gt_u32 s53, 0xbd
	s_mov_b64 s[16:17], s[20:21]
	s_cbranch_scc0 .LBB0_1125
	s_and_b64 vcc, exec, s[14:15]
	s_cbranch_vccz .LBB0_1128
	s_barrier

; #define PG8_STAGE(bufoff, gbase, voff) do { const char* _gb = (const char*)(gbase); asm volatile("" : "+s"(_gb)); _Pragma("unroll") for (int _i = 0; _i < 2; ++_i) { asm volatile("" : "+v"((voff)[_i])); \
;         __builtin_amdgcn_global_load_lds((const unsigned*)(_gb + (voff)[_i]), (PG8_LAS unsigned*)(lds + (bufoff) + ldsw + _i * 8192), 16, 0, 0); } } while (0)
; #define PG8_LDA(dst, b, h) do { _Pragma("unroll") for (int m = 0; m < 4; ++m) _Pragma("unroll") for (int k = 0; k < 2; ++k) dst[m][k] = *(const PG8_LAS bf16x8*)(lds + PG8_SA(b, h) + aoff + m * 2048 + k * 1024); } while (0)
; #define PG8_LDB(dst, b, h) do { _Pragma("unroll") for (int n = 0; n < 2; ++n) _Pragma("unroll") for (int k = 0; k < 2; ++k) dst[n][k] = *(const PG8_LAS bf16x8*)(lds + PG8_SB(b, h) + boff + n * 2048 + k * 1024); } while (0)
; #define PG8_WAIT_V(n) asm volatile("s_waitcnt vmcnt(" #n ")" ::: "memory")
; #define PG8_WAIT_L(n) asm volatile("s_waitcnt lgkmcnt(" #n ")" ::: "memory")
; #define PG8_BAR __builtin_amdgcn_s_barrier()
; #define PG8_SCHED __builtin_amdgcn_sched_barrier(0)
; #define PG8_STAGE(bufoff, gbase, voff) do { const char* _gb = (const char*)(gbase); asm volatile("" : "+s"(_gb)); _Pragma("unroll") for (int _i = 0; _i < 2; ++_i) { asm volatile("" : "+v"((voff)[_i])); \
;         __builtin_amdgcn_global_load_lds((const unsigned*)(_gb + (voff)[_i]), (PG8_LAS unsigned*)(lds + (bufoff) + ldsw + _i * 8192), 16, 0, 0); } } while (0)
; #define PG8_LDA(dst, b, h) do { _Pragma("unroll") for (int m = 0; m < 4; ++m) _Pragma("unroll") for (int k = 0; k < 2; ++k) dst[m][k] = *(const PG8_LAS bf16x8*)(lds + PG8_SA(b, h) + aoff + m * 2048 + k * 1024); } while (0)
; #define PG8_WAIT_V(n) asm volatile("s_waitcnt vmcnt(" #n ")" ::: "memory")
; template <class Epi, class Sched, bool ALIGN_EPI = false, bool SP2 = false>
; __device__ __forceinline__ void gemm_phase(PG8_LAS unsigned char* lds, const Gemm g, const Sched& S, const Epi& E) {
;     ...
;             PG8_LDB(B0, 0, 0); PG8_LDB(B1, 0, 1); PG8_SCHED; PG8_LDA(At, 0, 0); PG8_STAGE(PG8_SA(1, 1), a1 + hstep, voffA);
;             PG8_WAIT_V(8); PG8_WAIT_L(0); PG8_BAR; PG8_MMA2(0); PG8_BAR; PG8_SCHED;
;             PG8_LDA(At, 0, 1); PG8_STAGE(PG8_SB(0, 0), b2, voffB); PG8_STAGE(PG8_SB(0, 1), b2 + hstep, voffB); PG8_STAGE(PG8_SA(0, 0), a2, voffA);
;             PG8_WAIT_V(8); PG8_WAIT_L(0); PG8_BAR; PG8_MMA2(1); PG8_BAR; PG8_SCHED;
.LBB0_1217:
	s_add_u32 s28, s6, 0x100
	s_addc_u32 s29, s7, 0
	s_cmpk_eq_i32 s58, 0xbc
	s_cselect_b32 s36, s57, s28
	s_cselect_b32 s37, s56, s29
	s_cselect_b32 s34, s8, s4
	s_cselect_b32 s35, s9, s5
	s_add_u32 s30, s36, 0x80
	s_addc_u32 s31, s37, 0
	s_add_u32 s6, s6, 0x300080
	s_addc_u32 s7, s7, 0
	s_add_i32 m0, s41, 0xc000
	ds_read_b128 v[212:215], v177 offset:6144
	global_load_lds_dwordx4 v167, s[6:7]
	s_add_i32 m0, s41, 0xe000
	ds_read_b128 v[216:219], v177 offset:7168
	global_load_lds_dwordx4 v171, s[6:7]
	ds_read_b128 v[128:131], v175
	ds_read_b128 v[132:135], v175 offset:1024
	ds_read_b128 v[136:139], v175 offset:2048
	ds_read_b128 v[140:143], v175 offset:3072
	ds_read_b128 v[152:155], v176
	ds_read_b128 v[156:159], v176 offset:1024
	ds_read_b128 v[160:163], v176 offset:2048
	ds_read_b128 v[184:187], v176 offset:3072
	ds_read_b128 v[188:191], v177
	ds_read_b128 v[192:195], v177 offset:1024
	ds_read_b128 v[196:199], v177 offset:2048
	ds_read_b128 v[200:203], v177 offset:3072
	ds_read_b128 v[204:207], v177 offset:4096
	ds_read_b128 v[208:211], v177 offset:5120
	s_waitcnt vmcnt(8)
	s_waitcnt lgkmcnt(0)
	s_setprio 1
	s_waitcnt lgkmcnt(0)
	s_barrier
	v_mfma_f32_16x16x32_bf16 v[124:127], v[128:131], v[188:191], v[124:127]
	v_mfma_f32_16x16x32_bf16 v[120:123], v[136:139], v[188:191], v[120:123]
	v_mfma_f32_16x16x32_bf16 v[108:111], v[128:131], v[196:199], v[108:111]
	v_mfma_f32_16x16x32_bf16 v[104:107], v[136:139], v[196:199], v[104:107]
	v_mfma_f32_16x16x32_bf16 v[92:95], v[128:131], v[204:207], v[92:95]
	v_mfma_f32_16x16x32_bf16 v[88:91], v[136:139], v[204:207], v[88:91]
	v_mfma_f32_16x16x32_bf16 v[76:79], v[128:131], v[212:215], v[76:79]
	v_mfma_f32_16x16x32_bf16 v[72:75], v[136:139], v[212:215], v[72:75]
	v_mfma_f32_16x16x32_bf16 v[116:119], v[152:155], v[188:191], v[116:119]
	v_mfma_f32_16x16x32_bf16 v[112:115], v[160:163], v[188:191], v[112:115]
	v_mfma_f32_16x16x32_bf16 v[100:103], v[152:155], v[196:199], v[100:103]
	v_mfma_f32_16x16x32_bf16 v[96:99], v[160:163], v[196:199], v[96:99]
	v_mfma_f32_16x16x32_bf16 v[84:87], v[152:155], v[204:207], v[84:87]
	v_mfma_f32_16x16x32_bf16 v[80:83], v[160:163], v[204:207], v[80:83]
	v_mfma_f32_16x16x32_bf16 v[68:71], v[152:155], v[212:215], v[68:71]
	v_mfma_f32_16x16x32_bf16 v[64:67], v[160:163], v[212:215], v[64:67]
	v_mfma_f32_16x16x32_bf16 v[124:127], v[132:135], v[192:195], v[124:127]
	v_mfma_f32_16x16x32_bf16 v[120:123], v[140:143], v[192:195], v[120:123]
	v_mfma_f32_16x16x32_bf16 v[108:111], v[132:135], v[200:203], v[108:111]
	v_mfma_f32_16x16x32_bf16 v[104:107], v[140:143], v[200:203], v[104:107]
	v_mfma_f32_16x16x32_bf16 v[92:95], v[132:135], v[208:211], v[92:95]
	v_mfma_f32_16x16x32_bf16 v[88:91], v[140:143], v[208:211], v[88:91]
	v_mfma_f32_16x16x32_bf16 v[76:79], v[132:135], v[216:219], v[76:79]
	v_mfma_f32_16x16x32_bf16 v[72:75], v[140:143], v[216:219], v[72:75]
	v_mfma_f32_16x16x32_bf16 v[116:119], v[156:159], v[192:195], v[116:119]
	v_mfma_f32_16x16x32_bf16 v[112:115], v[184:187], v[192:195], v[112:115]
	v_mfma_f32_16x16x32_bf16 v[100:103], v[156:159], v[200:203], v[100:103]
	v_mfma_f32_16x16x32_bf16 v[96:99], v[184:187], v[200:203], v[96:99]
	v_mfma_f32_16x16x32_bf16 v[84:87], v[156:159], v[208:211], v[84:87]
	v_mfma_f32_16x16x32_bf16 v[80:83], v[184:187], v[208:211], v[80:83]
	v_mfma_f32_16x16x32_bf16 v[68:71], v[156:159], v[216:219], v[68:71]
	v_mfma_f32_16x16x32_bf16 v[64:67], v[184:187], v[216:219], v[64:67]
	s_setprio 0
	s_barrier
	s_add_i32 s59, s49, s39
	s_mov_b64 s[6:7], s[34:35]
	s_mov_b32 m0, s59
	ds_read_b128 v[196:199], v177 offset:18432
	global_load_lds_dwordx4 v169, s[6:7]
	s_add_i32 m0, s59, 0x2000
	ds_read_b128 v[200:203], v177 offset:19456
	global_load_lds_dwordx4 v172, s[6:7]
	s_add_u32 s6, s34, 0x300000
	s_addc_u32 s7, s35, 0
	s_add_i32 s59, s50, s39
	s_mov_b32 m0, s59
	ds_read_b128 v[204:207], v177 offset:20480
	global_load_lds_dwordx4 v169, s[6:7]
	s_add_i32 m0, s59, 0x2000
	ds_read_b128 v[208:211], v177 offset:21504
	global_load_lds_dwordx4 v172, s[6:7]
	s_mov_b64 s[6:7], s[36:37]
	s_mov_b32 m0, s41
	ds_read_b128 v[212:215], v177 offset:22528
	global_load_lds_dwordx4 v167, s[6:7]
	s_mov_b32 m0, s42
	ds_read_b128 v[216:219], v177 offset:23552
	global_load_lds_dwordx4 v171, s[6:7]
	ds_read_b128 v[188:191], v177 offset:16384
	ds_read_b128 v[192:195], v177 offset:17408
	s_waitcnt vmcnt(8)
	s_waitcnt lgkmcnt(0)
	s_setprio 1
	s_waitcnt lgkmcnt(0)
	s_barrier
	v_mfma_f32_16x16x32_bf16 v[60:63], v[128:131], v[188:191], v[60:63]
	v_mfma_f32_16x16x32_bf16 v[56:59], v[136:139], v[188:191], v[56:59]
	v_mfma_f32_16x16x32_bf16 v[44:47], v[128:131], v[196:199], v[44:47]
	v_mfma_f32_16x16x32_bf16 v[40:43], v[136:139], v[196:199], v[40:43]
	v_mfma_f32_16x16x32_bf16 v[28:31], v[128:131], v[204:207], v[28:31]
	v_mfma_f32_16x16x32_bf16 v[24:27], v[136:139], v[204:207], v[24:27]
	v_mfma_f32_16x16x32_bf16 v[12:15], v[128:131], v[212:215], v[12:15]
	v_mfma_f32_16x16x32_bf16 v[8:11], v[136:139], v[212:215], v[8:11]
	v_mfma_f32_16x16x32_bf16 v[52:55], v[152:155], v[188:191], v[52:55]
	v_mfma_f32_16x16x32_bf16 v[48:51], v[160:163], v[188:191], v[48:51]
	v_mfma_f32_16x16x32_bf16 v[36:39], v[152:155], v[196:199], v[36:39]
	v_mfma_f32_16x16x32_bf16 v[32:35], v[160:163], v[196:199], v[32:35]
	v_mfma_f32_16x16x32_bf16 v[20:23], v[152:155], v[204:207], v[20:23]
	v_mfma_f32_16x16x32_bf16 v[16:19], v[160:163], v[204:207], v[16:19]
	v_mfma_f32_16x16x32_bf16 v[4:7], v[152:155], v[212:215], v[4:7]
	v_mfma_f32_16x16x32_bf16 v[0:3], v[160:163], v[212:215], v[0:3]
	v_mfma_f32_16x16x32_bf16 v[60:63], v[132:135], v[192:195], v[60:63]
	v_mfma_f32_16x16x32_bf16 v[56:59], v[140:143], v[192:195], v[56:59]
	v_mfma_f32_16x16x32_bf16 v[44:47], v[132:135], v[200:203], v[44:47]
	v_mfma_f32_16x16x32_bf16 v[40:43], v[140:143], v[200:203], v[40:43]
	v_mfma_f32_16x16x32_bf16 v[28:31], v[132:135], v[208:211], v[28:31]
	v_mfma_f32_16x16x32_bf16 v[24:27], v[140:143], v[208:211], v[24:27]
	v_mfma_f32_16x16x32_bf16 v[12:15], v[132:135], v[216:219], v[12:15]
	v_mfma_f32_16x16x32_bf16 v[8:11], v[140:143], v[216:219], v[8:11]
	v_mfma_f32_16x16x32_bf16 v[52:55], v[156:159], v[192:195], v[52:55]
	v_mfma_f32_16x16x32_bf16 v[48:51], v[184:187], v[192:195], v[48:51]
	v_mfma_f32_16x16x32_bf16 v[36:39], v[156:159], v[200:203], v[36:39]
	v_mfma_f32_16x16x32_bf16 v[32:35], v[184:187], v[200:203], v[32:35]
	v_mfma_f32_16x16x32_bf16 v[20:23], v[156:159], v[208:211], v[20:23]
	v_mfma_f32_16x16x32_bf16 v[16:19], v[184:187], v[208:211], v[16:19]
	v_mfma_f32_16x16x32_bf16 v[4:7], v[156:159], v[216:219], v[4:7]
	v_mfma_f32_16x16x32_bf16 v[0:3], v[184:187], v[216:219], v[0:3]
	s_setprio 0
	s_barrier
; #define PG8_STAGE(bufoff, gbase, voff) do { const char* _gb = (const char*)(gbase); asm volatile("" : "+s"(_gb)); _Pragma("unroll") for (int _i = 0; _i < 2; ++_i) { asm volatile("" : "+v"((voff)[_i])); \
;         __builtin_amdgcn_global_load_lds((const unsigned*)(_gb + (voff)[_i]), (PG8_LAS unsigned*)(lds + (bufoff) + ldsw + _i * 8192), 16, 0, 0); } } while (0)
; #define PG8_LDA(dst, b, h) do { _Pragma("unroll") for (int m = 0; m < 4; ++m) _Pragma("unroll") for (int k = 0; k < 2; ++k) dst[m][k] = *(const PG8_LAS bf16x8*)(lds + PG8_SA(b, h) + aoff + m * 2048 + k * 1024); } while (0)
; #define PG8_LDB(dst, b, h) do { _Pragma("unroll") for (int n = 0; n < 2; ++n) _Pragma("unroll") for (int k = 0; k < 2; ++k) dst[n][k] = *(const PG8_LAS bf16x8*)(lds + PG8_SB(b, h) + boff + n * 2048 + k * 1024); } while (0)
; #define PG8_WAIT_V(n) asm volatile("s_waitcnt vmcnt(" #n ")" ::: "memory")
; #define PG8_WAIT_L(n) asm volatile("s_waitcnt lgkmcnt(" #n ")" ::: "memory")
; #define PG8_BAR __builtin_amdgcn_s_barrier()
; #define PG8_SCHED __builtin_amdgcn_sched_barrier(0)
; #define PG8_STAGE(bufoff, gbase, voff) do { const char* _gb = (const char*)(gbase); asm volatile("" : "+s"(_gb)); _Pragma("unroll") for (int _i = 0; _i < 2; ++_i) { asm volatile("" : "+v"((voff)[_i])); \
;         __builtin_amdgcn_global_load_lds((const unsigned*)(_gb + (voff)[_i]), (PG8_LAS unsigned*)(lds + (bufoff) + ldsw + _i * 8192), 16, 0, 0); } } while (0)
; #define PG8_LDA(dst, b, h) do { _Pragma("unroll") for (int m = 0; m < 4; ++m) _Pragma("unroll") for (int k = 0; k < 2; ++k) dst[m][k] = *(const PG8_LAS bf16x8*)(lds + PG8_SA(b, h) + aoff + m * 2048 + k * 1024); } while (0)
; #define PG8_WAIT_V(n) asm volatile("s_waitcnt vmcnt(" #n ")" ::: "memory")
; template <class Epi, class Sched, bool ALIGN_EPI = false, bool SP2 = false>
; __device__ __forceinline__ void gemm_phase(PG8_LAS unsigned char* lds, const Gemm g, const Sched& S, const Epi& E) {
;     ...
;             PG8_LDB(B0, 1, 0); PG8_LDB(B1, 1, 1); PG8_SCHED; PG8_LDA(At, 1, 0); PG8_STAGE(PG8_SA(0, 1), a2 + hstep, voffA);
;             PG8_WAIT_V(8); PG8_WAIT_L(0); PG8_BAR; PG8_MMA2(0); PG8_BAR; PG8_SCHED;
;             PG8_LDA(At, 1, 1); PG8_STAGE(PG8_SB(1, 0), b3, voffB); PG8_STAGE(PG8_SB(1, 1), b3 + hstep, voffB); PG8_STAGE(PG8_SA(1, 0), a3, voffA);
;             PG8_WAIT_V(8); PG8_WAIT_L(0); PG8_BAR; PG8_MMA2(1); PG8_BAR; PG8_SCHED;
	s_add_i32 s59, 0, 0x18000
	s_add_i32 s60, 0, 0x1c000
	s_add_u32 s6, s36, 0x300000
	s_addc_u32 s7, s37, 0
	s_mov_b32 m0, s43
	ds_read_b128 v[212:215], v177 offset:38912
	global_load_lds_dwordx4 v167, s[6:7]
	s_mov_b32 m0, s44
	ds_read_b128 v[216:219], v177 offset:39936
	global_load_lds_dwordx4 v171, s[6:7]
	v_add_u32_e32 v140, s59, v174
	v_add_u32_e32 v164, s60, v174
	ds_read_b128 v[128:131], v140
	ds_read_b128 v[132:135], v140 offset:1024
	ds_read_b128 v[136:139], v140 offset:2048
	ds_read_b128 v[140:143], v140 offset:3072
	ds_read_b128 v[152:155], v164
	ds_read_b128 v[156:159], v164 offset:1024
	ds_read_b128 v[160:163], v164 offset:2048
	ds_read_b128 v[184:187], v164 offset:3072
	ds_read_b128 v[188:191], v177 offset:32768
	ds_read_b128 v[192:195], v177 offset:33792
	ds_read_b128 v[196:199], v177 offset:34816
	ds_read_b128 v[200:203], v177 offset:35840
	ds_read_b128 v[204:207], v177 offset:36864
	ds_read_b128 v[208:211], v177 offset:37888
	s_waitcnt vmcnt(8)
	s_waitcnt lgkmcnt(0)
	s_setprio 1
	s_waitcnt lgkmcnt(0)
	s_barrier
	v_mfma_f32_16x16x32_bf16 v[124:127], v[128:131], v[188:191], v[124:127]
	v_mfma_f32_16x16x32_bf16 v[120:123], v[136:139], v[188:191], v[120:123]
	v_mfma_f32_16x16x32_bf16 v[108:111], v[128:131], v[196:199], v[108:111]
	v_mfma_f32_16x16x32_bf16 v[104:107], v[136:139], v[196:199], v[104:107]
	v_mfma_f32_16x16x32_bf16 v[92:95], v[128:131], v[204:207], v[92:95]
	v_mfma_f32_16x16x32_bf16 v[88:91], v[136:139], v[204:207], v[88:91]
	v_mfma_f32_16x16x32_bf16 v[76:79], v[128:131], v[212:215], v[76:79]
	v_mfma_f32_16x16x32_bf16 v[72:75], v[136:139], v[212:215], v[72:75]
	v_mfma_f32_16x16x32_bf16 v[116:119], v[152:155], v[188:191], v[116:119]
	v_mfma_f32_16x16x32_bf16 v[112:115], v[160:163], v[188:191], v[112:115]
	v_mfma_f32_16x16x32_bf16 v[100:103], v[152:155], v[196:199], v[100:103]
	v_mfma_f32_16x16x32_bf16 v[96:99], v[160:163], v[196:199], v[96:99]
	v_mfma_f32_16x16x32_bf16 v[84:87], v[152:155], v[204:207], v[84:87]
	v_mfma_f32_16x16x32_bf16 v[80:83], v[160:163], v[204:207], v[80:83]
	v_mfma_f32_16x16x32_bf16 v[68:71], v[152:155], v[212:215], v[68:71]
	v_mfma_f32_16x16x32_bf16 v[64:67], v[160:163], v[212:215], v[64:67]
	v_mfma_f32_16x16x32_bf16 v[124:127], v[132:135], v[192:195], v[124:127]
	v_mfma_f32_16x16x32_bf16 v[120:123], v[140:143], v[192:195], v[120:123]
	v_mfma_f32_16x16x32_bf16 v[108:111], v[132:135], v[200:203], v[108:111]
	v_mfma_f32_16x16x32_bf16 v[104:107], v[140:143], v[200:203], v[104:107]
	v_mfma_f32_16x16x32_bf16 v[92:95], v[132:135], v[208:211], v[92:95]
	v_mfma_f32_16x16x32_bf16 v[88:91], v[140:143], v[208:211], v[88:91]
	v_mfma_f32_16x16x32_bf16 v[76:79], v[132:135], v[216:219], v[76:79]
	v_mfma_f32_16x16x32_bf16 v[72:75], v[140:143], v[216:219], v[72:75]
	v_mfma_f32_16x16x32_bf16 v[116:119], v[156:159], v[192:195], v[116:119]
	v_mfma_f32_16x16x32_bf16 v[112:115], v[184:187], v[192:195], v[112:115]
	v_mfma_f32_16x16x32_bf16 v[100:103], v[156:159], v[200:203], v[100:103]
	v_mfma_f32_16x16x32_bf16 v[96:99], v[184:187], v[200:203], v[96:99]
	v_mfma_f32_16x16x32_bf16 v[84:87], v[156:159], v[208:211], v[84:87]
	v_mfma_f32_16x16x32_bf16 v[80:83], v[184:187], v[208:211], v[80:83]
	v_mfma_f32_16x16x32_bf16 v[68:71], v[156:159], v[216:219], v[68:71]
	v_mfma_f32_16x16x32_bf16 v[64:67], v[184:187], v[216:219], v[64:67]
	s_setprio 0
	s_barrier
	s_add_u32 s6, s34, 0x80
	s_addc_u32 s7, s35, 0
	s_add_i32 s36, s59, s39
	s_mov_b32 m0, s36
	ds_read_b128 v[196:199], v177 offset:51200
	global_load_lds_dwordx4 v169, s[6:7]
	s_add_i32 m0, s36, 0x2000
	ds_read_b128 v[200:203], v177 offset:52224
	global_load_lds_dwordx4 v172, s[6:7]
	s_add_u32 s6, s34, 0x300080
	s_addc_u32 s7, s35, 0
	s_add_i32 s34, s60, s39
	s_mov_b32 m0, s34
	ds_read_b128 v[204:207], v177 offset:53248
	global_load_lds_dwordx4 v169, s[6:7]
	s_add_i32 m0, s34, 0x2000
	ds_read_b128 v[208:211], v177 offset:54272
	global_load_lds_dwordx4 v172, s[6:7]
	s_mov_b32 m0, s47
	ds_read_b128 v[212:215], v177 offset:55296
	global_load_lds_dwordx4 v167, s[30:31]
	s_mov_b32 m0, s48
	ds_read_b128 v[216:219], v177 offset:56320
	global_load_lds_dwordx4 v171, s[30:31]
	ds_read_b128 v[188:191], v177 offset:49152
	ds_read_b128 v[192:195], v177 offset:50176
	s_waitcnt vmcnt(8)
	s_waitcnt lgkmcnt(0)
	s_setprio 1
	s_waitcnt lgkmcnt(0)
	s_barrier
	v_mfma_f32_16x16x32_bf16 v[60:63], v[128:131], v[188:191], v[60:63]
	v_mfma_f32_16x16x32_bf16 v[56:59], v[136:139], v[188:191], v[56:59]
	v_mfma_f32_16x16x32_bf16 v[44:47], v[128:131], v[196:199], v[44:47]
	v_mfma_f32_16x16x32_bf16 v[40:43], v[136:139], v[196:199], v[40:43]
	v_mfma_f32_16x16x32_bf16 v[28:31], v[128:131], v[204:207], v[28:31]
	v_mfma_f32_16x16x32_bf16 v[24:27], v[136:139], v[204:207], v[24:27]
	v_mfma_f32_16x16x32_bf16 v[12:15], v[128:131], v[212:215], v[12:15]
	v_mfma_f32_16x16x32_bf16 v[8:11], v[136:139], v[212:215], v[8:11]
	v_mfma_f32_16x16x32_bf16 v[52:55], v[152:155], v[188:191], v[52:55]
	v_mfma_f32_16x16x32_bf16 v[48:51], v[160:163], v[188:191], v[48:51]
	v_mfma_f32_16x16x32_bf16 v[36:39], v[152:155], v[196:199], v[36:39]
	v_mfma_f32_16x16x32_bf16 v[32:35], v[160:163], v[196:199], v[32:35]
	v_mfma_f32_16x16x32_bf16 v[20:23], v[152:155], v[204:207], v[20:23]
	v_mfma_f32_16x16x32_bf16 v[16:19], v[160:163], v[204:207], v[16:19]
	v_mfma_f32_16x16x32_bf16 v[4:7], v[152:155], v[212:215], v[4:7]
	v_mfma_f32_16x16x32_bf16 v[0:3], v[160:163], v[212:215], v[0:3]
	v_mfma_f32_16x16x32_bf16 v[60:63], v[132:135], v[192:195], v[60:63]
	v_mfma_f32_16x16x32_bf16 v[56:59], v[140:143], v[192:195], v[56:59]
	v_mfma_f32_16x16x32_bf16 v[44:47], v[132:135], v[200:203], v[44:47]
	v_mfma_f32_16x16x32_bf16 v[40:43], v[140:143], v[200:203], v[40:43]
	v_mfma_f32_16x16x32_bf16 v[28:31], v[132:135], v[208:211], v[28:31]
	v_mfma_f32_16x16x32_bf16 v[24:27], v[140:143], v[208:211], v[24:27]
	v_mfma_f32_16x16x32_bf16 v[12:15], v[132:135], v[216:219], v[12:15]
	v_mfma_f32_16x16x32_bf16 v[8:11], v[140:143], v[216:219], v[8:11]
	v_mfma_f32_16x16x32_bf16 v[52:55], v[156:159], v[192:195], v[52:55]
	v_mfma_f32_16x16x32_bf16 v[48:51], v[184:187], v[192:195], v[48:51]
	v_mfma_f32_16x16x32_bf16 v[36:39], v[156:159], v[200:203], v[36:39]
	v_mfma_f32_16x16x32_bf16 v[32:35], v[184:187], v[200:203], v[32:35]
	v_mfma_f32_16x16x32_bf16 v[20:23], v[156:159], v[208:211], v[20:23]
	v_mfma_f32_16x16x32_bf16 v[16:19], v[184:187], v[208:211], v[16:19]
	v_mfma_f32_16x16x32_bf16 v[4:7], v[156:159], v[216:219], v[4:7]
	v_mfma_f32_16x16x32_bf16 v[0:3], v[184:187], v[216:219], v[0:3]
	s_setprio 0
	s_barrier
	s_add_i32 s58, s58, 2
	s_add_u32 s4, s4, 0x100
	s_addc_u32 s5, s5, 0
	s_cmpk_gt_u32 s58, 0xbd
	s_mov_b64 s[6:7], s[28:29]
	s_cbranch_scc0 .LBB0_1217
	s_and_b64 vcc, exec, s[18:19]
	s_cbranch_vccz .LBB0_1220
	s_barrier
